# weight/cache conversion stores without the nt hint (on v038)
# baseline (speedup 1.0000x reference)
.LBB0_536:
	s_or_b64 exec, exec, s[10:11]
	v_ashrrev_i32_e32 v34, 17, v39
	s_waitcnt vmcnt(0)
	v_cvt_pk_bf16_f32 v30, v30, v31
	v_cvt_pk_bf16_f32 v31, v32, v33
	v_cvt_pk_bf16_f32 v32, v26, v27
	v_mul_i32_i24_e32 v26, 0x220, v34
	v_bfe_u32 v0, v39, 8, 9
	v_ashrrev_i32_e32 v27, 31, v26
	v_lshl_add_u64 v[26:27], v[26:27], 0, v[0:1]
	v_lshlrev_b64 v[26:27], 12, v[26:27]
	v_lshl_add_u64 v[26:27], s[28:29], 0, v[26:27]
	v_lshlrev_b32_e32 v0, 1, v38
	v_cvt_pk_bf16_f32 v33, v28, v29
	v_lshl_add_u64 v[26:27], v[26:27], 0, v[0:1]
	global_store_dwordx4 v[26:27], v[30:33], off
	s_and_saveexec_b64 s[10:11], vcc
	s_cbranch_execz .LBB0_539
	v_ashrrev_i32_e32 v31, 17, v40
	v_mul_i32_i24_e32 v32, 0x220, v31
	v_bfe_u32 v30, v40, 8, 9
	v_ashrrev_i32_e32 v33, 31, v32
	v_mov_b32_e32 v31, v1
	v_lshl_add_u64 v[30:31], v[32:33], 0, v[30:31]
	v_lshlrev_b64 v[30:31], 12, v[30:31]
	v_lshl_add_u64 v[30:31], s[28:29], 0, v[30:31]
	v_cvt_pk_bf16_f32 v26, v2, v3
	v_cvt_pk_bf16_f32 v27, v4, v5
	v_cvt_pk_bf16_f32 v28, v10, v11
	v_cvt_pk_bf16_f32 v29, v12, v13
	v_lshl_add_u64 v[30:31], v[30:31], 0, v[0:1]
	global_store_dwordx4 v[30:31], v[26:29], off
	s_or_b64 exec, exec, s[10:11]
	s_and_saveexec_b64 s[10:11], s[0:1]
	s_cbranch_execnz .LBB0_540

.LBB0_540:
	v_ashrrev_i32_e32 v31, 17, v41
	v_mul_i32_i24_e32 v32, 0x220, v31
	v_bfe_u32 v30, v41, 8, 9
	v_ashrrev_i32_e32 v33, 31, v32
	v_mov_b32_e32 v31, v1
	v_lshl_add_u64 v[30:31], v[32:33], 0, v[30:31]
	v_lshlrev_b64 v[30:31], 12, v[30:31]
	v_lshl_add_u64 v[30:31], s[28:29], 0, v[30:31]
	v_cvt_pk_bf16_f32 v26, v6, v7
	v_cvt_pk_bf16_f32 v27, v8, v9
	v_cvt_pk_bf16_f32 v28, v18, v19
	v_cvt_pk_bf16_f32 v29, v20, v21
	v_lshl_add_u64 v[30:31], v[30:31], 0, v[0:1]
	global_store_dwordx4 v[30:31], v[26:29], off
	s_or_b64 exec, exec, s[10:11]
	s_and_saveexec_b64 s[0:1], s[4:5]
	s_cbranch_execz .LBB0_529
.LBB0_541:
	v_ashrrev_i32_e32 v31, 17, v42
	v_mul_i32_i24_e32 v32, 0x220, v31
	v_bfe_u32 v30, v42, 8, 9
	v_ashrrev_i32_e32 v33, 31, v32
	v_mov_b32_e32 v31, v1
	v_lshl_add_u64 v[30:31], v[32:33], 0, v[30:31]
	v_lshlrev_b64 v[30:31], 12, v[30:31]
	v_lshl_add_u64 v[30:31], s[28:29], 0, v[30:31]
	v_cvt_pk_bf16_f32 v26, v14, v15
	v_cvt_pk_bf16_f32 v27, v16, v17
	v_cvt_pk_bf16_f32 v28, v22, v23
	v_cvt_pk_bf16_f32 v29, v24, v25
	v_lshl_add_u64 v[30:31], v[30:31], 0, v[0:1]
	global_store_dwordx4 v[30:31], v[26:29], off
	s_branch .LBB0_529

.LBB0_548:
	s_cmpk_gt_i32 s3, 0xfff
	s_mov_b64 s[0:1], -1
	s_cbranch_scc0 .LBB0_574
	s_cmpk_gt_u32 s3, 0x13ff
	s_cbranch_scc0 .LBB0_571
	s_cmpk_gt_u32 s3, 0x1fff
	s_cbranch_scc0 .LBB0_568
	s_cmpk_gt_u32 s3, 0x23ff
	s_cbranch_scc0 .LBB0_565
	s_cmpk_gt_u32 s3, 0x39ff
	s_cbranch_scc0 .LBB0_562
	s_cmpk_gt_u32 s3, 0x44ff
	s_cbranch_scc0 .LBB0_559
	s_cmpk_gt_u32 s3, 0x5aff
	s_cbranch_scc0 .LBB0_556
	s_and_b32 s0, s9, 0x7fffffc0
	s_add_i32 s0, s0, 0xffff4a00
	v_or_b32_e32 v0, s0, v3
	v_readlane_b32 s10, v248, 39
	s_and_b32 s4, s7, 0x7c0
	v_lshlrev_b64 v[30:31], 13, v[0:1]
	v_readlane_b32 s11, v248, 40
	s_lshl_b32 s88, s4, 2
	v_lshlrev_b32_e32 v0, 2, v2
	v_lshl_add_u64 v[30:31], s[10:11], 0, v[30:31]
	v_lshl_add_u64 v[30:31], v[30:31], 0, s[88:89]
	v_lshl_add_u64 v[90:91], v[30:31], 0, v[0:1]
	v_add_co_u32_e32 v34, vcc, 0x8000, v90
	s_mov_b32 s1, 0x18000
	s_nop 0
	v_addc_co_u32_e32 v35, vcc, 0, v91, vcc
	v_add_co_u32_e32 v38, vcc, s56, v90
	global_load_dwordx4 v[30:33], v[90:91], off nt
	s_nop 0
	global_load_dwordx4 v[34:37], v[34:35], off nt
	v_addc_co_u32_e32 v39, vcc, 0, v91, vcc
	v_add_co_u32_e32 v42, vcc, s1, v90
	s_mov_b32 s1, 0x28000
	s_nop 0
	v_addc_co_u32_e32 v43, vcc, 0, v91, vcc
	global_load_dwordx4 v[38:41], v[38:39], off nt
	s_nop 0
	global_load_dwordx4 v[42:45], v[42:43], off nt
	v_add_co_u32_e32 v46, vcc, s65, v90
	v_add_u32_e32 v0, 0x410, v20
	s_nop 0
	v_addc_co_u32_e32 v47, vcc, 0, v91, vcc
	v_add_co_u32_e32 v50, vcc, s1, v90
	s_mov_b32 s1, 0x30000
	s_nop 0
	v_addc_co_u32_e32 v51, vcc, 0, v91, vcc
	global_load_dwordx4 v[46:49], v[46:47], off nt
	s_nop 0
	global_load_dwordx4 v[50:53], v[50:51], off nt
	v_add_co_u32_e32 v54, vcc, s1, v90
	s_mov_b32 s1, 0x38000
	s_nop 0
	v_addc_co_u32_e32 v55, vcc, 0, v91, vcc
	v_add_co_u32_e32 v58, vcc, s1, v90
	s_mov_b32 s1, 0x48000
	s_nop 0
	v_addc_co_u32_e32 v59, vcc, 0, v91, vcc
	global_load_dwordx4 v[54:57], v[54:55], off nt
	s_nop 0
	global_load_dwordx4 v[58:61], v[58:59], off nt
	v_add_co_u32_e32 v62, vcc, s57, v90
	s_nop 1
	v_addc_co_u32_e32 v63, vcc, 0, v91, vcc
	v_add_co_u32_e32 v66, vcc, s1, v90
	s_mov_b32 s1, 0x58000
	s_nop 0
	v_addc_co_u32_e32 v67, vcc, 0, v91, vcc
	global_load_dwordx4 v[62:65], v[62:63], off nt
	s_nop 0
	global_load_dwordx4 v[66:69], v[66:67], off nt
	v_add_co_u32_e32 v70, vcc, s63, v90
	s_nop 1
	v_addc_co_u32_e32 v71, vcc, 0, v91, vcc
	v_add_co_u32_e32 v74, vcc, s1, v90
	s_mov_b32 s1, 0x68000
	s_nop 0
	v_addc_co_u32_e32 v75, vcc, 0, v91, vcc
	global_load_dwordx4 v[70:73], v[70:71], off nt
	s_nop 0
	global_load_dwordx4 v[74:77], v[74:75], off nt
	v_add_co_u32_e32 v78, vcc, s23, v90
	s_nop 1
	v_addc_co_u32_e32 v79, vcc, 0, v91, vcc
	v_add_co_u32_e32 v82, vcc, s1, v90
	s_mov_b32 s1, 0x78000
	s_nop 0
	v_addc_co_u32_e32 v83, vcc, 0, v91, vcc
	global_load_dwordx4 v[78:81], v[78:79], off nt
	s_nop 0
	global_load_dwordx4 v[82:85], v[82:83], off nt
	v_add_co_u32_e32 v86, vcc, s44, v90
	s_nop 1
	v_addc_co_u32_e32 v87, vcc, 0, v91, vcc
	global_load_dwordx4 v[86:89], v[86:87], off nt
	v_add_co_u32_e32 v90, vcc, s1, v90
	s_mov_b32 s1, s89
	s_nop 0
	v_addc_co_u32_e32 v91, vcc, 0, v91, vcc
	global_load_dwordx4 v[90:93], v[90:91], off nt
	s_waitcnt vmcnt(0)
	ds_write2_b32 v20, v30, v31 offset1:1
	ds_write2_b32 v20, v32, v33 offset0:2 offset1:3
	ds_write2_b32 v0, v34, v35 offset1:1
	v_add_u32_e32 v0, 0x418, v20
	ds_write2_b32 v0, v36, v37 offset1:1
	v_add_u32_e32 v0, 0x820, v20
	ds_write2_b32 v0, v38, v39 offset1:1
	v_add_u32_e32 v0, 0x828, v20
	ds_write2_b32 v0, v40, v41 offset1:1
	v_add_u32_e32 v0, 0xc30, v20
	ds_write2_b32 v0, v42, v43 offset1:1
	v_add_u32_e32 v0, 0xc38, v20
	ds_write2_b32 v0, v44, v45 offset1:1
	v_add_u32_e32 v0, 0x1040, v20
	ds_write2_b32 v0, v46, v47 offset1:1
	v_add_u32_e32 v0, 0x1048, v20
	ds_write2_b32 v0, v48, v49 offset1:1
	v_add_u32_e32 v0, 0x1450, v20
	ds_write2_b32 v0, v50, v51 offset1:1
	v_add_u32_e32 v0, 0x1458, v20
	ds_write2_b32 v0, v52, v53 offset1:1
	v_add_u32_e32 v0, 0x1860, v20
	v_lshl_add_u64 v[50:51], s[0:1], 1, v[4:5]
	s_mov_b64 s[0:1], 0
	ds_write2_b32 v0, v54, v55 offset1:1
	v_add_u32_e32 v0, 0x1868, v20
	ds_write2_b32 v0, v56, v57 offset1:1
	v_add_u32_e32 v0, 0x1c70, v20
	ds_write2_b32 v0, v58, v59 offset1:1
	v_add_u32_e32 v0, 0x1c78, v20
	ds_write2_b32 v0, v60, v61 offset1:1
	v_add_u32_e32 v0, 0x2080, v20
	v_add_u32_e32 v54, 0x400, v22
	ds_write2_b32 v0, v62, v63 offset1:1
	v_add_u32_e32 v0, 0x2088, v20
	ds_write2_b32 v0, v64, v65 offset1:1
	v_add_u32_e32 v0, 0x2490, v20
	ds_write2_b32 v0, v66, v67 offset1:1
	v_add_u32_e32 v0, 0x2498, v20
	ds_write2_b32 v0, v68, v69 offset1:1
	v_add_u32_e32 v0, 0x28a0, v20
	ds_write2_b32 v0, v70, v71 offset1:1
	v_add_u32_e32 v0, 0x28a8, v20
	ds_write2_b32 v0, v72, v73 offset1:1
	v_add_u32_e32 v0, 0x2cb0, v20
	ds_write2_b32 v0, v74, v75 offset1:1
	v_add_u32_e32 v0, 0x2cb8, v20
	ds_write2_b32 v0, v76, v77 offset1:1
	v_add_u32_e32 v0, 0x30c0, v20
	ds_write2_b32 v0, v78, v79 offset1:1
	v_add_u32_e32 v0, 0x30c8, v20
	ds_write2_b32 v0, v80, v81 offset1:1
	v_add_u32_e32 v0, 0x34d0, v20
	ds_write2_b32 v0, v82, v83 offset1:1
	v_add_u32_e32 v0, 0x34d8, v20
	ds_write2_b32 v0, v84, v85 offset1:1
	v_add_u32_e32 v0, 0x38e0, v20
	ds_write2_b32 v0, v86, v87 offset1:1
	v_add_u32_e32 v0, 0x38e8, v20
	ds_write2_b32 v0, v88, v89 offset1:1
	v_add_u32_e32 v0, 0x3cf0, v20
	ds_write2_b32 v0, v90, v91 offset1:1
	v_add_u32_e32 v0, 0x3cf8, v20
	ds_write2_b32 v0, v92, v93 offset1:1
	s_waitcnt lgkmcnt(0)
	ds_read2_b32 v[34:35], v22 offset0:65 offset1:73
	ds_read2_b32 v[36:37], v22 offset1:8
	ds_read2_b32 v[38:39], v22 offset0:130 offset1:138
	ds_read2_b32 v[40:41], v22 offset0:195 offset1:203
	ds_read2_b32 v[42:43], v54 offset0:4 offset1:12
	ds_read2_b32 v[44:45], v54 offset0:69 offset1:77
	ds_read2_b32 v[46:47], v54 offset0:134 offset1:142
	ds_read2_b32 v[48:49], v54 offset0:199 offset1:207
	v_or_b32_e32 v0, s4, v21
	v_mul_u32_u24_e32 v0, 0x2c00, v0
	s_waitcnt lgkmcnt(6)
	v_cvt_pk_bf16_f32 v30, v36, v34
	s_waitcnt lgkmcnt(4)
	v_cvt_pk_bf16_f32 v31, v38, v40
	s_waitcnt lgkmcnt(2)
	v_cvt_pk_bf16_f32 v32, v42, v44
	s_waitcnt lgkmcnt(0)
	v_cvt_pk_bf16_f32 v33, v46, v48
	v_lshl_add_u64 v[52:53], v[50:51], 0, v[0:1]
	global_store_dwordx4 v[52:53], v[30:33], off
	v_or_b32_e32 v0, s4, v23
	v_mul_u32_u24_e32 v0, 0x2c00, v0
	v_cvt_pk_bf16_f32 v30, v37, v35
	v_cvt_pk_bf16_f32 v31, v39, v41
	v_cvt_pk_bf16_f32 v32, v43, v45
	v_cvt_pk_bf16_f32 v33, v47, v49
	ds_read2_b32 v[36:37], v22 offset0:16 offset1:24
	ds_read2_b32 v[38:39], v22 offset0:81 offset1:89
	ds_read2_b32 v[40:41], v22 offset0:146 offset1:154
	ds_read2_b32 v[42:43], v22 offset0:211 offset1:219
	ds_read2_b32 v[44:45], v54 offset0:20 offset1:28
	ds_read2_b32 v[46:47], v54 offset0:85 offset1:93
	ds_read2_b32 v[48:49], v54 offset0:150 offset1:158
	ds_read2_b32 v[52:53], v54 offset0:215 offset1:223
	v_lshl_add_u64 v[34:35], v[50:51], 0, v[0:1]
	v_or_b32_e32 v0, s4, v24
	v_mul_u32_u24_e32 v0, 0x2c00, v0
	global_store_dwordx4 v[34:35], v[30:33], off
	v_lshl_add_u64 v[34:35], v[50:51], 0, v[0:1]
	v_or_b32_e32 v0, s4, v25
	s_waitcnt lgkmcnt(6)
	v_cvt_pk_bf16_f32 v30, v36, v38
	s_waitcnt lgkmcnt(4)
	v_cvt_pk_bf16_f32 v31, v40, v42
	s_waitcnt lgkmcnt(2)
	v_cvt_pk_bf16_f32 v32, v44, v46
	s_waitcnt lgkmcnt(0)
	v_cvt_pk_bf16_f32 v33, v48, v52
	global_store_dwordx4 v[34:35], v[30:33], off
	v_mul_u32_u24_e32 v0, 0x2c00, v0
	v_lshl_add_u64 v[34:35], v[50:51], 0, v[0:1]
	v_cvt_pk_bf16_f32 v30, v37, v39
	v_cvt_pk_bf16_f32 v31, v41, v43
	v_cvt_pk_bf16_f32 v32, v45, v47
	v_cvt_pk_bf16_f32 v33, v49, v53
	ds_read2_b32 v[36:37], v22 offset0:32 offset1:40
	ds_read2_b32 v[38:39], v22 offset0:97 offset1:105
	ds_read2_b32 v[40:41], v22 offset0:162 offset1:170
	ds_read2_b32 v[42:43], v22 offset0:227 offset1:235
	ds_read2_b32 v[44:45], v54 offset0:36 offset1:44
	ds_read2_b32 v[46:47], v54 offset0:101 offset1:109
	ds_read2_b32 v[48:49], v54 offset0:166 offset1:174
	ds_read2_b32 v[52:53], v54 offset0:231 offset1:239
	v_or_b32_e32 v0, s4, v26
	v_mul_u32_u24_e32 v0, 0x2c00, v0
	global_store_dwordx4 v[34:35], v[30:33], off
	v_lshl_add_u64 v[34:35], v[50:51], 0, v[0:1]
	v_or_b32_e32 v0, s4, v27
	s_waitcnt lgkmcnt(6)
	v_cvt_pk_bf16_f32 v30, v36, v38
	s_waitcnt lgkmcnt(4)
	v_cvt_pk_bf16_f32 v31, v40, v42
	s_waitcnt lgkmcnt(2)
	v_cvt_pk_bf16_f32 v32, v44, v46
	s_waitcnt lgkmcnt(0)
	v_cvt_pk_bf16_f32 v33, v48, v52
	global_store_dwordx4 v[34:35], v[30:33], off
	v_mul_u32_u24_e32 v0, 0x2c00, v0
	v_lshl_add_u64 v[34:35], v[50:51], 0, v[0:1]
	v_cvt_pk_bf16_f32 v30, v37, v39
	v_cvt_pk_bf16_f32 v31, v41, v43
	v_cvt_pk_bf16_f32 v32, v45, v47
	v_cvt_pk_bf16_f32 v33, v49, v53
	ds_read2_b32 v[36:37], v22 offset0:48 offset1:56
	ds_read2_b32 v[38:39], v22 offset0:113 offset1:121
	ds_read2_b32 v[40:41], v22 offset0:178 offset1:186
	ds_read2_b32 v[42:43], v22 offset0:243 offset1:251
	ds_read2_b32 v[44:45], v54 offset0:52 offset1:60
	ds_read2_b32 v[46:47], v54 offset0:117 offset1:125
	ds_read2_b32 v[48:49], v54 offset0:182 offset1:190
	ds_read2_b32 v[52:53], v54 offset0:247 offset1:255
	v_or_b32_e32 v0, s4, v28
	v_mul_u32_u24_e32 v0, 0x2c00, v0
	global_store_dwordx4 v[34:35], v[30:33], off
	v_lshl_add_u64 v[34:35], v[50:51], 0, v[0:1]
	v_or_b32_e32 v0, s4, v29
	s_waitcnt lgkmcnt(6)
	v_cvt_pk_bf16_f32 v30, v36, v38
	s_waitcnt lgkmcnt(4)
	v_cvt_pk_bf16_f32 v31, v40, v42
	s_waitcnt lgkmcnt(2)
	v_cvt_pk_bf16_f32 v32, v44, v46
	s_waitcnt lgkmcnt(0)
	v_cvt_pk_bf16_f32 v33, v48, v52
	v_mul_u32_u24_e32 v0, 0x2c00, v0
	global_store_dwordx4 v[34:35], v[30:33], off
	v_lshl_add_u64 v[34:35], v[50:51], 0, v[0:1]
	s_nop 0
	v_cvt_pk_bf16_f32 v30, v37, v39
	v_cvt_pk_bf16_f32 v31, v41, v43
	v_cvt_pk_bf16_f32 v32, v45, v47
	v_cvt_pk_bf16_f32 v33, v49, v53
	global_store_dwordx4 v[34:35], v[30:33], off
	s_waitcnt lgkmcnt(0)
.LBB0_556:
	s_andn2_b64 vcc, exec, s[0:1]
	s_cbranch_vccnz .LBB0_558
	s_add_i32 s0, s3, 0xbb00
	s_and_b32 s1, s0, 0xffff
	s_mul_i32 s1, s1, 0xba2f
	s_lshr_b32 s1, s1, 23
	s_mul_i32 s4, s1, 0xb0
	s_sub_i32 s0, s0, s4
	s_lshl_b32 s4, s0, 6
	v_lshl_or_b32 v0, s1, 6, v3
	v_readlane_b32 s10, v248, 41
	s_and_b32 s5, s4, 0xffc0
	v_mul_u32_u24_e32 v0, 0xb000, v0
	v_readlane_b32 s11, v248, 42
	s_lshl_b32 s88, s5, 2
	s_mov_b32 s5, 0x2c000
	v_lshl_add_u64 v[30:31], s[10:11], 0, v[0:1]
	v_lshl_add_u64 v[30:31], v[30:31], 0, s[88:89]
	v_lshlrev_b32_e32 v0, 2, v2
	v_lshl_add_u64 v[90:91], v[30:31], 0, v[0:1]
	v_add_co_u32_e32 v34, vcc, s5, v90
	s_mov_b32 s5, 0x58000
	s_nop 0
	v_addc_co_u32_e32 v35, vcc, 0, v91, vcc
	v_add_co_u32_e32 v38, vcc, s5, v90
	global_load_dwordx4 v[30:33], v[90:91], off nt
	s_nop 0
	global_load_dwordx4 v[34:37], v[34:35], off nt
	v_addc_co_u32_e32 v39, vcc, 0, v91, vcc
	s_mov_b32 s5, 0x84000
	v_add_co_u32_e32 v42, vcc, s5, v90
	s_mov_b32 s5, 0xb0000
	s_nop 0
	v_addc_co_u32_e32 v43, vcc, 0, v91, vcc
	global_load_dwordx4 v[38:41], v[38:39], off nt
	s_nop 0
	global_load_dwordx4 v[42:45], v[42:43], off nt
	v_add_co_u32_e32 v46, vcc, s5, v90
	s_mov_b32 s5, 0xdc000
	s_nop 0
	v_addc_co_u32_e32 v47, vcc, 0, v91, vcc
	v_add_co_u32_e32 v50, vcc, s5, v90
	s_mov_b32 s5, 0x108000
	s_nop 0
	v_addc_co_u32_e32 v51, vcc, 0, v91, vcc
	global_load_dwordx4 v[46:49], v[46:47], off nt
	s_nop 0
	global_load_dwordx4 v[50:53], v[50:51], off nt
	v_add_co_u32_e32 v54, vcc, s5, v90
	s_mov_b32 s5, 0x134000
	s_nop 0
	v_addc_co_u32_e32 v55, vcc, 0, v91, vcc
	v_add_co_u32_e32 v58, vcc, s5, v90
	s_mov_b32 s5, 0x18c000
	s_nop 0
	v_addc_co_u32_e32 v59, vcc, 0, v91, vcc
	global_load_dwordx4 v[54:57], v[54:55], off nt
	s_nop 0
	global_load_dwordx4 v[58:61], v[58:59], off nt
	v_add_co_u32_e32 v62, vcc, s30, v90
	v_add_u32_e32 v0, 0x410, v20
	s_nop 0
	v_addc_co_u32_e32 v63, vcc, 0, v91, vcc
	v_add_co_u32_e32 v66, vcc, s5, v90
	s_mov_b32 s5, 0x1b8000
	s_nop 0
	v_addc_co_u32_e32 v67, vcc, 0, v91, vcc
	global_load_dwordx4 v[62:65], v[62:63], off nt
	s_nop 0
	global_load_dwordx4 v[66:69], v[66:67], off nt
	v_add_co_u32_e32 v70, vcc, s5, v90
	s_mov_b32 s5, 0x1e4000
	s_nop 0
	v_addc_co_u32_e32 v71, vcc, 0, v91, vcc
	v_add_co_u32_e32 v74, vcc, s5, v90
	s_mov_b32 s5, 0x23c000
	s_nop 0
	v_addc_co_u32_e32 v75, vcc, 0, v91, vcc
	global_load_dwordx4 v[70:73], v[70:71], off nt
	s_nop 0
	global_load_dwordx4 v[74:77], v[74:75], off nt
	v_add_co_u32_e32 v78, vcc, s26, v90
	s_lshl_b32 s88, s1, 7
	s_nop 0
	v_addc_co_u32_e32 v79, vcc, 0, v91, vcc
	global_load_dwordx4 v[78:81], v[78:79], off nt
	v_add_co_u32_e32 v82, vcc, s5, v90
	s_mov_b32 s5, 0x268000
	s_nop 0
	v_addc_co_u32_e32 v83, vcc, 0, v91, vcc
	global_load_dwordx4 v[82:85], v[82:83], off nt
	v_add_co_u32_e32 v86, vcc, s5, v90
	s_mov_b32 s5, 0x294000
	s_nop 0
	v_addc_co_u32_e32 v87, vcc, 0, v91, vcc
	global_load_dwordx4 v[86:89], v[86:87], off nt
	v_add_co_u32_e32 v90, vcc, s5, v90
	s_and_b32 s1, s0, 0xffff
	s_nop 0
	v_addc_co_u32_e32 v91, vcc, 0, v91, vcc
	global_load_dwordx4 v[90:93], v[90:91], off nt
	s_waitcnt vmcnt(0)
	ds_write2_b32 v20, v30, v31 offset1:1
	ds_write2_b32 v20, v32, v33 offset0:2 offset1:3
	ds_write2_b32 v0, v34, v35 offset1:1
	v_add_u32_e32 v0, 0x418, v20
	ds_write2_b32 v0, v36, v37 offset1:1
	v_add_u32_e32 v0, 0x820, v20
	s_lshl_b32 s0, s0, 7
	s_and_b32 s0, s0, 0x7f00
	s_add_i32 s5, s0, 0xffffd480
	s_cmpk_lt_u32 s1, 0x58
	ds_write2_b32 v0, v38, v39 offset1:1
	v_add_u32_e32 v0, 0x828, v20
	ds_write2_b32 v0, v40, v41 offset1:1
	v_add_u32_e32 v0, 0xc30, v20
	ds_write2_b32 v0, v42, v43 offset1:1
	v_add_u32_e32 v0, 0xc38, v20
	ds_write2_b32 v0, v44, v45 offset1:1
	v_add_u32_e32 v0, 0x1040, v20
	s_cselect_b32 s0, s0, s5
	s_and_b32 s1, s4, 64
	s_or_b32 s0, s1, s0
	ds_write2_b32 v0, v46, v47 offset1:1
	v_add_u32_e32 v0, 0x1048, v20
	ds_write2_b32 v0, v48, v49 offset1:1
	v_add_u32_e32 v0, 0x1450, v20
	ds_write2_b32 v0, v50, v51 offset1:1
	v_add_u32_e32 v0, 0x1458, v20
	ds_write2_b32 v0, v52, v53 offset1:1
	v_add_u32_e32 v0, 0x1860, v20
	v_or_b32_e32 v52, s0, v21
	v_ashrrev_i32_e32 v53, 31, v52
	v_lshl_add_u64 v[50:51], v[6:7], 0, s[88:89]
	ds_write2_b32 v0, v54, v55 offset1:1
	v_add_u32_e32 v0, 0x1868, v20
	ds_write2_b32 v0, v56, v57 offset1:1
	v_add_u32_e32 v0, 0x1c70, v20
	ds_write2_b32 v0, v58, v59 offset1:1
	v_add_u32_e32 v0, 0x1c78, v20
	ds_write2_b32 v0, v60, v61 offset1:1
	v_add_u32_e32 v0, 0x2080, v20
	v_lshlrev_b64 v[52:53], 12, v[52:53]
	v_lshl_add_u64 v[52:53], v[50:51], 0, v[52:53]
	ds_write2_b32 v0, v62, v63 offset1:1
	v_add_u32_e32 v0, 0x2088, v20
	ds_write2_b32 v0, v64, v65 offset1:1
	v_add_u32_e32 v0, 0x2490, v20
	ds_write2_b32 v0, v66, v67 offset1:1
	v_add_u32_e32 v0, 0x2498, v20
	ds_write2_b32 v0, v68, v69 offset1:1
	v_add_u32_e32 v0, 0x28a0, v20
	ds_write2_b32 v0, v70, v71 offset1:1
	v_add_u32_e32 v0, 0x28a8, v20
	ds_write2_b32 v0, v72, v73 offset1:1
	v_add_u32_e32 v0, 0x2cb0, v20
	ds_write2_b32 v0, v74, v75 offset1:1
	v_add_u32_e32 v0, 0x2cb8, v20
	ds_write2_b32 v0, v76, v77 offset1:1
	v_add_u32_e32 v0, 0x30c0, v20
	ds_write2_b32 v0, v78, v79 offset1:1
	v_add_u32_e32 v0, 0x30c8, v20
	ds_write2_b32 v0, v80, v81 offset1:1
	v_add_u32_e32 v0, 0x34d0, v20
	ds_write2_b32 v0, v82, v83 offset1:1
	v_add_u32_e32 v0, 0x34d8, v20
	ds_write2_b32 v0, v84, v85 offset1:1
	v_add_u32_e32 v0, 0x38e0, v20
	ds_write2_b32 v0, v86, v87 offset1:1
	v_add_u32_e32 v0, 0x38e8, v20
	ds_write2_b32 v0, v88, v89 offset1:1
	v_add_u32_e32 v0, 0x3cf0, v20
	ds_write2_b32 v0, v90, v91 offset1:1
	v_add_u32_e32 v0, 0x3cf8, v20
	ds_write2_b32 v0, v92, v93 offset1:1
	s_waitcnt lgkmcnt(0)
	v_add_u32_e32 v0, 0x400, v22
	ds_read2_b32 v[34:35], v22 offset0:65 offset1:73
	ds_read2_b32 v[36:37], v22 offset1:8
	ds_read2_b32 v[38:39], v22 offset0:130 offset1:138
	ds_read2_b32 v[40:41], v22 offset0:195 offset1:203
	ds_read2_b32 v[42:43], v0 offset0:4 offset1:12
	ds_read2_b32 v[44:45], v0 offset0:69 offset1:77
	ds_read2_b32 v[46:47], v0 offset0:134 offset1:142
	ds_read2_b32 v[48:49], v0 offset0:199 offset1:207
	s_waitcnt lgkmcnt(6)
	v_cvt_pk_bf16_f32 v30, v36, v34
	s_waitcnt lgkmcnt(2)
	v_cvt_pk_bf16_f32 v32, v42, v44
	v_cvt_pk_bf16_f32 v31, v38, v40
	s_waitcnt lgkmcnt(0)
	v_cvt_pk_bf16_f32 v33, v46, v48
	v_or_b32_e32 v34, s0, v23
	global_store_dwordx4 v[52:53], v[30:33], off
	s_nop 1
	v_cvt_pk_bf16_f32 v30, v37, v35
	v_ashrrev_i32_e32 v35, 31, v34
	v_cvt_pk_bf16_f32 v31, v39, v41
	v_cvt_pk_bf16_f32 v32, v43, v45
	v_cvt_pk_bf16_f32 v33, v47, v49
	v_lshlrev_b64 v[34:35], 12, v[34:35]
	ds_read2_b32 v[36:37], v22 offset0:81 offset1:89
	ds_read2_b32 v[38:39], v22 offset0:16 offset1:24
	ds_read2_b32 v[40:41], v22 offset0:146 offset1:154
	ds_read2_b32 v[42:43], v22 offset0:211 offset1:219
	ds_read2_b32 v[44:45], v0 offset0:20 offset1:28
	ds_read2_b32 v[46:47], v0 offset0:85 offset1:93
	ds_read2_b32 v[48:49], v0 offset0:150 offset1:158
	ds_read2_b32 v[52:53], v0 offset0:215 offset1:223
	v_lshl_add_u64 v[34:35], v[50:51], 0, v[34:35]
	global_store_dwordx4 v[34:35], v[30:33], off
	v_or_b32_e32 v34, s0, v24
	v_ashrrev_i32_e32 v35, 31, v34
	v_lshlrev_b64 v[34:35], 12, v[34:35]
	s_waitcnt lgkmcnt(6)
	v_cvt_pk_bf16_f32 v30, v38, v36
	s_waitcnt lgkmcnt(4)
	v_cvt_pk_bf16_f32 v31, v40, v42
	s_waitcnt lgkmcnt(2)
	v_cvt_pk_bf16_f32 v32, v44, v46
	s_waitcnt lgkmcnt(0)
	v_cvt_pk_bf16_f32 v33, v48, v52
	v_lshl_add_u64 v[34:35], v[50:51], 0, v[34:35]
	global_store_dwordx4 v[34:35], v[30:33], off
	v_or_b32_e32 v34, s0, v25
	v_ashrrev_i32_e32 v35, 31, v34
	v_cvt_pk_bf16_f32 v30, v39, v37
	v_cvt_pk_bf16_f32 v31, v41, v43
	v_cvt_pk_bf16_f32 v32, v45, v47
	v_cvt_pk_bf16_f32 v33, v49, v53
	v_lshlrev_b64 v[34:35], 12, v[34:35]
	ds_read2_b32 v[36:37], v22 offset0:32 offset1:40
	ds_read2_b32 v[38:39], v22 offset0:97 offset1:105
	ds_read2_b32 v[40:41], v22 offset0:162 offset1:170
	ds_read2_b32 v[42:43], v22 offset0:227 offset1:235
	ds_read2_b32 v[44:45], v0 offset0:36 offset1:44
	ds_read2_b32 v[46:47], v0 offset0:101 offset1:109
	ds_read2_b32 v[48:49], v0 offset0:166 offset1:174
	ds_read2_b32 v[52:53], v0 offset0:231 offset1:239
	v_lshl_add_u64 v[34:35], v[50:51], 0, v[34:35]
	global_store_dwordx4 v[34:35], v[30:33], off
	v_or_b32_e32 v34, s0, v26
	v_ashrrev_i32_e32 v35, 31, v34
	v_lshlrev_b64 v[34:35], 12, v[34:35]
	s_waitcnt lgkmcnt(6)
	v_cvt_pk_bf16_f32 v30, v36, v38
	s_waitcnt lgkmcnt(4)
	v_cvt_pk_bf16_f32 v31, v40, v42
	s_waitcnt lgkmcnt(2)
	v_cvt_pk_bf16_f32 v32, v44, v46
	s_waitcnt lgkmcnt(0)
	v_cvt_pk_bf16_f32 v33, v48, v52
	v_lshl_add_u64 v[34:35], v[50:51], 0, v[34:35]
	global_store_dwordx4 v[34:35], v[30:33], off
	v_or_b32_e32 v34, s0, v27
	v_ashrrev_i32_e32 v35, 31, v34
	v_cvt_pk_bf16_f32 v30, v37, v39
	v_cvt_pk_bf16_f32 v31, v41, v43
	v_cvt_pk_bf16_f32 v32, v45, v47
	v_cvt_pk_bf16_f32 v33, v49, v53
	v_lshlrev_b64 v[34:35], 12, v[34:35]
	ds_read2_b32 v[36:37], v22 offset0:48 offset1:56
	ds_read2_b32 v[38:39], v22 offset0:113 offset1:121
	ds_read2_b32 v[40:41], v22 offset0:178 offset1:186
	ds_read2_b32 v[42:43], v22 offset0:243 offset1:251
	ds_read2_b32 v[44:45], v0 offset0:52 offset1:60
	ds_read2_b32 v[46:47], v0 offset0:117 offset1:125
	ds_read2_b32 v[48:49], v0 offset0:182 offset1:190
	ds_read2_b32 v[52:53], v0 offset0:247 offset1:255
	v_lshl_add_u64 v[34:35], v[50:51], 0, v[34:35]
	global_store_dwordx4 v[34:35], v[30:33], off
	v_or_b32_e32 v34, s0, v28
	v_ashrrev_i32_e32 v35, 31, v34
	v_lshlrev_b64 v[34:35], 12, v[34:35]
	s_waitcnt lgkmcnt(6)
	v_cvt_pk_bf16_f32 v30, v36, v38
	s_waitcnt lgkmcnt(4)
	v_cvt_pk_bf16_f32 v31, v40, v42
	s_waitcnt lgkmcnt(2)
	v_cvt_pk_bf16_f32 v32, v44, v46
	s_waitcnt lgkmcnt(0)
	v_cvt_pk_bf16_f32 v33, v48, v52
	v_lshl_add_u64 v[34:35], v[50:51], 0, v[34:35]
	global_store_dwordx4 v[34:35], v[30:33], off
	v_or_b32_e32 v34, s0, v29
	v_ashrrev_i32_e32 v35, 31, v34
	v_lshlrev_b64 v[34:35], 12, v[34:35]
	v_cvt_pk_bf16_f32 v30, v37, v39
	v_cvt_pk_bf16_f32 v31, v41, v43
	v_cvt_pk_bf16_f32 v32, v45, v47
	v_cvt_pk_bf16_f32 v33, v49, v53
	v_lshl_add_u64 v[34:35], v[50:51], 0, v[34:35]
	global_store_dwordx4 v[34:35], v[30:33], off
	s_waitcnt lgkmcnt(0)

.LBB0_559:
	s_andn2_b64 vcc, exec, s[0:1]
	s_cbranch_vccnz .LBB0_561
	s_add_i32 s0, s9, 0x18c00
	s_and_b32 s1, s0, 0x1ffc0
	v_or_b32_e32 v0, s1, v3
	v_readlane_b32 s76, v247, 59
	s_and_b32 s0, s7, 0x7c0
	v_lshlrev_b32_e32 v0, 13, v0
	v_readlane_b32 s77, v247, 60
	s_lshl_b32 s88, s0, 2
	s_mov_b32 s4, 0x18000
	v_lshl_add_u64 v[30:31], s[76:77], 0, v[0:1]
	v_lshl_add_u64 v[30:31], v[30:31], 0, s[88:89]
	v_lshlrev_b32_e32 v0, 2, v2
	v_lshl_add_u64 v[90:91], v[30:31], 0, v[0:1]
	v_add_co_u32_e32 v34, vcc, 0x8000, v90
	v_add_u32_e32 v0, 0x410, v20
	s_nop 0
	v_addc_co_u32_e32 v35, vcc, 0, v91, vcc
	v_add_co_u32_e32 v38, vcc, s56, v90
	global_load_dwordx4 v[30:33], v[90:91], off nt
	s_nop 0
	global_load_dwordx4 v[34:37], v[34:35], off nt
	v_addc_co_u32_e32 v39, vcc, 0, v91, vcc
	v_add_co_u32_e32 v42, vcc, s4, v90
	s_mov_b32 s4, 0x28000
	s_nop 0
	v_addc_co_u32_e32 v43, vcc, 0, v91, vcc
	global_load_dwordx4 v[38:41], v[38:39], off nt
	s_nop 0
	global_load_dwordx4 v[42:45], v[42:43], off nt
	v_add_co_u32_e32 v46, vcc, s65, v90
	s_lshl_b32 s88, s1, 1
	s_nop 0
	v_addc_co_u32_e32 v47, vcc, 0, v91, vcc
	v_add_co_u32_e32 v50, vcc, s4, v90
	s_mov_b32 s4, 0x30000
	s_nop 0
	v_addc_co_u32_e32 v51, vcc, 0, v91, vcc
	global_load_dwordx4 v[46:49], v[46:47], off nt
	s_nop 0
	global_load_dwordx4 v[50:53], v[50:51], off nt
	v_add_co_u32_e32 v54, vcc, s4, v90
	s_mov_b32 s4, 0x38000
	s_nop 0
	v_addc_co_u32_e32 v55, vcc, 0, v91, vcc
	v_add_co_u32_e32 v58, vcc, s4, v90
	s_mov_b32 s4, 0x48000
	s_nop 0
	v_addc_co_u32_e32 v59, vcc, 0, v91, vcc
	global_load_dwordx4 v[54:57], v[54:55], off nt
	s_nop 0
	global_load_dwordx4 v[58:61], v[58:59], off nt
	v_add_co_u32_e32 v62, vcc, s57, v90
	v_readlane_b32 s78, v247, 61
	s_nop 0
	v_addc_co_u32_e32 v63, vcc, 0, v91, vcc
	v_add_co_u32_e32 v66, vcc, s4, v90
	s_mov_b32 s4, 0x58000
	s_nop 0
	v_addc_co_u32_e32 v67, vcc, 0, v91, vcc
	global_load_dwordx4 v[62:65], v[62:63], off nt
	s_nop 0
	global_load_dwordx4 v[66:69], v[66:67], off nt
	v_add_co_u32_e32 v70, vcc, s63, v90
	v_readlane_b32 s79, v247, 62
	s_nop 0
	v_addc_co_u32_e32 v71, vcc, 0, v91, vcc
	v_add_co_u32_e32 v74, vcc, s4, v90
	s_mov_b32 s4, 0x68000
	s_nop 0
	v_addc_co_u32_e32 v75, vcc, 0, v91, vcc
	global_load_dwordx4 v[70:73], v[70:71], off nt
	s_nop 0
	global_load_dwordx4 v[74:77], v[74:75], off nt
	v_add_co_u32_e32 v78, vcc, s23, v90
	v_readlane_b32 s80, v247, 63
	s_nop 0
	v_addc_co_u32_e32 v79, vcc, 0, v91, vcc
	v_add_co_u32_e32 v82, vcc, s4, v90
	s_mov_b32 s4, 0x78000
	s_nop 0
	v_addc_co_u32_e32 v83, vcc, 0, v91, vcc
	global_load_dwordx4 v[78:81], v[78:79], off nt
	s_nop 0
	global_load_dwordx4 v[82:85], v[82:83], off nt
	v_add_co_u32_e32 v86, vcc, s44, v90
	v_readlane_b32 s81, v246, 0
	s_nop 0
	v_addc_co_u32_e32 v87, vcc, 0, v91, vcc
	global_load_dwordx4 v[86:89], v[86:87], off nt
	v_add_co_u32_e32 v90, vcc, s4, v90
	v_readlane_b32 s82, v246, 1
	s_nop 0
	v_addc_co_u32_e32 v91, vcc, 0, v91, vcc
	global_load_dwordx4 v[90:93], v[90:91], off nt
	s_waitcnt vmcnt(0)
	ds_write2_b32 v20, v30, v31 offset1:1
	ds_write2_b32 v20, v32, v33 offset0:2 offset1:3
	ds_write2_b32 v0, v34, v35 offset1:1
	v_add_u32_e32 v0, 0x418, v20
	ds_write2_b32 v0, v36, v37 offset1:1
	v_add_u32_e32 v0, 0x820, v20
	v_readlane_b32 s83, v246, 2
	ds_write2_b32 v0, v38, v39 offset1:1
	v_add_u32_e32 v0, 0x828, v20
	ds_write2_b32 v0, v40, v41 offset1:1
	v_add_u32_e32 v0, 0xc30, v20
	ds_write2_b32 v0, v42, v43 offset1:1
	v_add_u32_e32 v0, 0xc38, v20
	ds_write2_b32 v0, v44, v45 offset1:1
	v_add_u32_e32 v0, 0x1040, v20
	ds_write2_b32 v0, v46, v47 offset1:1
	v_add_u32_e32 v0, 0x1048, v20
	ds_write2_b32 v0, v48, v49 offset1:1
	v_add_u32_e32 v0, 0x1450, v20
	ds_write2_b32 v0, v50, v51 offset1:1
	v_add_u32_e32 v0, 0x1458, v20
	ds_write2_b32 v0, v52, v53 offset1:1
	v_add_u32_e32 v0, 0x1860, v20
	v_lshl_add_u64 v[50:51], v[8:9], 0, s[88:89]
	ds_write2_b32 v0, v54, v55 offset1:1
	v_add_u32_e32 v0, 0x1868, v20
	ds_write2_b32 v0, v56, v57 offset1:1
	v_add_u32_e32 v0, 0x1c70, v20
	ds_write2_b32 v0, v58, v59 offset1:1
	v_add_u32_e32 v0, 0x1c78, v20
	ds_write2_b32 v0, v60, v61 offset1:1
	v_add_u32_e32 v0, 0x2080, v20
	v_add_u32_e32 v54, 0x400, v22
	ds_write2_b32 v0, v62, v63 offset1:1
	v_add_u32_e32 v0, 0x2088, v20
	ds_write2_b32 v0, v64, v65 offset1:1
	v_add_u32_e32 v0, 0x2490, v20
	ds_write2_b32 v0, v66, v67 offset1:1
	v_add_u32_e32 v0, 0x2498, v20
	ds_write2_b32 v0, v68, v69 offset1:1
	v_add_u32_e32 v0, 0x28a0, v20
	ds_write2_b32 v0, v70, v71 offset1:1
	v_add_u32_e32 v0, 0x28a8, v20
	ds_write2_b32 v0, v72, v73 offset1:1
	v_add_u32_e32 v0, 0x2cb0, v20
	ds_write2_b32 v0, v74, v75 offset1:1
	v_add_u32_e32 v0, 0x2cb8, v20
	ds_write2_b32 v0, v76, v77 offset1:1
	v_add_u32_e32 v0, 0x30c0, v20
	ds_write2_b32 v0, v78, v79 offset1:1
	v_add_u32_e32 v0, 0x30c8, v20
	ds_write2_b32 v0, v80, v81 offset1:1
	v_add_u32_e32 v0, 0x34d0, v20
	ds_write2_b32 v0, v82, v83 offset1:1
	v_add_u32_e32 v0, 0x34d8, v20
	ds_write2_b32 v0, v84, v85 offset1:1
	v_add_u32_e32 v0, 0x38e0, v20
	ds_write2_b32 v0, v86, v87 offset1:1
	v_add_u32_e32 v0, 0x38e8, v20
	ds_write2_b32 v0, v88, v89 offset1:1
	v_add_u32_e32 v0, 0x3cf0, v20
	ds_write2_b32 v0, v90, v91 offset1:1
	v_add_u32_e32 v0, 0x3cf8, v20
	ds_write2_b32 v0, v92, v93 offset1:1
	s_waitcnt lgkmcnt(0)
	ds_read2_b32 v[34:35], v22 offset0:65 offset1:73
	ds_read2_b32 v[36:37], v22 offset1:8
	ds_read2_b32 v[38:39], v22 offset0:130 offset1:138
	ds_read2_b32 v[40:41], v22 offset0:195 offset1:203
	ds_read2_b32 v[42:43], v54 offset0:4 offset1:12
	ds_read2_b32 v[44:45], v54 offset0:69 offset1:77
	ds_read2_b32 v[46:47], v54 offset0:134 offset1:142
	ds_read2_b32 v[48:49], v54 offset0:199 offset1:207
	v_or_b32_e32 v0, s0, v21
	v_mul_u32_u24_e32 v0, 0x2c00, v0
	s_waitcnt lgkmcnt(6)
	v_cvt_pk_bf16_f32 v30, v36, v34
	s_waitcnt lgkmcnt(4)
	v_cvt_pk_bf16_f32 v31, v38, v40
	s_waitcnt lgkmcnt(2)
	v_cvt_pk_bf16_f32 v32, v42, v44
	s_waitcnt lgkmcnt(0)
	v_cvt_pk_bf16_f32 v33, v46, v48
	v_lshl_add_u64 v[52:53], v[50:51], 0, v[0:1]
	global_store_dwordx4 v[52:53], v[30:33], off
	v_or_b32_e32 v0, s0, v23
	v_mul_u32_u24_e32 v0, 0x2c00, v0
	v_cvt_pk_bf16_f32 v30, v37, v35
	v_cvt_pk_bf16_f32 v31, v39, v41
	v_cvt_pk_bf16_f32 v32, v43, v45
	v_cvt_pk_bf16_f32 v33, v47, v49
	ds_read2_b32 v[36:37], v22 offset0:16 offset1:24
	ds_read2_b32 v[38:39], v22 offset0:81 offset1:89
	ds_read2_b32 v[40:41], v22 offset0:146 offset1:154
	ds_read2_b32 v[42:43], v22 offset0:211 offset1:219
	ds_read2_b32 v[44:45], v54 offset0:20 offset1:28
	ds_read2_b32 v[46:47], v54 offset0:85 offset1:93
	ds_read2_b32 v[48:49], v54 offset0:150 offset1:158
	ds_read2_b32 v[52:53], v54 offset0:215 offset1:223
	v_lshl_add_u64 v[34:35], v[50:51], 0, v[0:1]
	v_or_b32_e32 v0, s0, v24
	v_mul_u32_u24_e32 v0, 0x2c00, v0
	global_store_dwordx4 v[34:35], v[30:33], off
	v_lshl_add_u64 v[34:35], v[50:51], 0, v[0:1]
	v_or_b32_e32 v0, s0, v25
	s_waitcnt lgkmcnt(6)
	v_cvt_pk_bf16_f32 v30, v36, v38
	s_waitcnt lgkmcnt(4)
	v_cvt_pk_bf16_f32 v31, v40, v42
	s_waitcnt lgkmcnt(2)
	v_cvt_pk_bf16_f32 v32, v44, v46
	s_waitcnt lgkmcnt(0)
	v_cvt_pk_bf16_f32 v33, v48, v52
	global_store_dwordx4 v[34:35], v[30:33], off
	v_mul_u32_u24_e32 v0, 0x2c00, v0
	v_lshl_add_u64 v[34:35], v[50:51], 0, v[0:1]
	v_cvt_pk_bf16_f32 v30, v37, v39
	v_cvt_pk_bf16_f32 v31, v41, v43
	v_cvt_pk_bf16_f32 v32, v45, v47
	v_cvt_pk_bf16_f32 v33, v49, v53
	ds_read2_b32 v[36:37], v22 offset0:32 offset1:40
	ds_read2_b32 v[38:39], v22 offset0:97 offset1:105
	ds_read2_b32 v[40:41], v22 offset0:162 offset1:170
	ds_read2_b32 v[42:43], v22 offset0:227 offset1:235
	ds_read2_b32 v[44:45], v54 offset0:36 offset1:44
	ds_read2_b32 v[46:47], v54 offset0:101 offset1:109
	ds_read2_b32 v[48:49], v54 offset0:166 offset1:174
	ds_read2_b32 v[52:53], v54 offset0:231 offset1:239
	v_or_b32_e32 v0, s0, v26
	v_mul_u32_u24_e32 v0, 0x2c00, v0
	global_store_dwordx4 v[34:35], v[30:33], off
	v_lshl_add_u64 v[34:35], v[50:51], 0, v[0:1]
	v_or_b32_e32 v0, s0, v27
	s_waitcnt lgkmcnt(6)
	v_cvt_pk_bf16_f32 v30, v36, v38
	s_waitcnt lgkmcnt(4)
	v_cvt_pk_bf16_f32 v31, v40, v42
	s_waitcnt lgkmcnt(2)
	v_cvt_pk_bf16_f32 v32, v44, v46
	s_waitcnt lgkmcnt(0)
	v_cvt_pk_bf16_f32 v33, v48, v52
	global_store_dwordx4 v[34:35], v[30:33], off
	v_mul_u32_u24_e32 v0, 0x2c00, v0
	v_lshl_add_u64 v[34:35], v[50:51], 0, v[0:1]
	v_cvt_pk_bf16_f32 v30, v37, v39
	v_cvt_pk_bf16_f32 v31, v41, v43
	v_cvt_pk_bf16_f32 v32, v45, v47
	v_cvt_pk_bf16_f32 v33, v49, v53
	ds_read2_b32 v[36:37], v22 offset0:48 offset1:56
	ds_read2_b32 v[38:39], v22 offset0:113 offset1:121
	ds_read2_b32 v[40:41], v22 offset0:178 offset1:186
	ds_read2_b32 v[42:43], v22 offset0:243 offset1:251
	ds_read2_b32 v[44:45], v54 offset0:52 offset1:60
	ds_read2_b32 v[46:47], v54 offset0:117 offset1:125
	ds_read2_b32 v[48:49], v54 offset0:182 offset1:190
	ds_read2_b32 v[52:53], v54 offset0:247 offset1:255
	v_or_b32_e32 v0, s0, v28
	v_mul_u32_u24_e32 v0, 0x2c00, v0
	global_store_dwordx4 v[34:35], v[30:33], off
	v_lshl_add_u64 v[34:35], v[50:51], 0, v[0:1]
	v_or_b32_e32 v0, s0, v29
	s_waitcnt lgkmcnt(6)
	v_cvt_pk_bf16_f32 v30, v36, v38
	s_waitcnt lgkmcnt(4)
	v_cvt_pk_bf16_f32 v31, v40, v42
	s_waitcnt lgkmcnt(2)
	v_cvt_pk_bf16_f32 v32, v44, v46
	s_waitcnt lgkmcnt(0)
	v_cvt_pk_bf16_f32 v33, v48, v52
	v_mul_u32_u24_e32 v0, 0x2c00, v0
	global_store_dwordx4 v[34:35], v[30:33], off
	v_lshl_add_u64 v[34:35], v[50:51], 0, v[0:1]
	s_nop 0
	v_cvt_pk_bf16_f32 v30, v37, v39
	v_cvt_pk_bf16_f32 v31, v41, v43
	v_cvt_pk_bf16_f32 v32, v45, v47
	v_cvt_pk_bf16_f32 v33, v49, v53
	global_store_dwordx4 v[34:35], v[30:33], off
	s_waitcnt lgkmcnt(0)

.LBB0_562:
	s_andn2_b64 vcc, exec, s[0:1]
	s_cbranch_vccnz .LBB0_564
	s_add_i32 s0, s3, 0xdc00
	s_and_b32 s1, s0, 0xffff
	s_mul_i32 s1, s1, 0xba2f
	s_lshr_b32 s1, s1, 23
	s_mul_i32 s4, s1, 0xb0
	s_sub_i32 s0, s0, s4
	s_lshl_b32 s4, s0, 6
	v_lshl_or_b32 v0, s1, 6, v3
	s_mov_b64 s[10:11], s[52:53]
	v_readlane_b32 s52, v248, 0
	s_and_b32 s5, s4, 0xffc0
	v_mul_u32_u24_e32 v0, 0xb000, v0
	v_readlane_b32 s54, v248, 2
	v_readlane_b32 s55, v248, 3
	s_lshl_b32 s88, s5, 2
	s_mov_b32 s5, 0x2c000
	v_lshl_add_u64 v[30:31], s[54:55], 0, v[0:1]
	v_lshl_add_u64 v[30:31], v[30:31], 0, s[88:89]
	v_lshlrev_b32_e32 v0, 2, v2
	v_lshl_add_u64 v[90:91], v[30:31], 0, v[0:1]
	v_add_co_u32_e32 v34, vcc, s5, v90
	s_mov_b32 s5, 0x58000
	s_nop 0
	v_addc_co_u32_e32 v35, vcc, 0, v91, vcc
	v_add_co_u32_e32 v38, vcc, s5, v90
	global_load_dwordx4 v[30:33], v[90:91], off nt
	s_nop 0
	global_load_dwordx4 v[34:37], v[34:35], off nt
	v_addc_co_u32_e32 v39, vcc, 0, v91, vcc
	s_mov_b32 s5, 0x84000
	v_add_co_u32_e32 v42, vcc, s5, v90
	s_mov_b32 s5, 0xb0000
	s_nop 0
	v_addc_co_u32_e32 v43, vcc, 0, v91, vcc
	global_load_dwordx4 v[38:41], v[38:39], off nt
	s_nop 0
	global_load_dwordx4 v[42:45], v[42:43], off nt
	v_add_co_u32_e32 v46, vcc, s5, v90
	s_mov_b32 s5, 0xdc000
	s_nop 0
	v_addc_co_u32_e32 v47, vcc, 0, v91, vcc
	v_add_co_u32_e32 v50, vcc, s5, v90
	s_mov_b32 s5, 0x108000
	s_nop 0
	v_addc_co_u32_e32 v51, vcc, 0, v91, vcc
	global_load_dwordx4 v[46:49], v[46:47], off nt
	s_nop 0
	global_load_dwordx4 v[50:53], v[50:51], off nt
	v_add_co_u32_e32 v54, vcc, s5, v90
	s_mov_b32 s5, 0x134000
	s_nop 0
	v_addc_co_u32_e32 v55, vcc, 0, v91, vcc
	v_add_co_u32_e32 v58, vcc, s5, v90
	s_mov_b32 s5, 0x18c000
	s_nop 0
	v_addc_co_u32_e32 v59, vcc, 0, v91, vcc
	global_load_dwordx4 v[54:57], v[54:55], off nt
	s_nop 0
	global_load_dwordx4 v[58:61], v[58:59], off nt
	v_add_co_u32_e32 v62, vcc, s30, v90
	v_add_u32_e32 v0, 0x410, v20
	s_nop 0
	v_addc_co_u32_e32 v63, vcc, 0, v91, vcc
	v_add_co_u32_e32 v66, vcc, s5, v90
	s_mov_b32 s5, 0x1b8000
	s_nop 0
	v_addc_co_u32_e32 v67, vcc, 0, v91, vcc
	global_load_dwordx4 v[62:65], v[62:63], off nt
	s_nop 0
	global_load_dwordx4 v[66:69], v[66:67], off nt
	v_add_co_u32_e32 v70, vcc, s5, v90
	s_mov_b32 s5, 0x1e4000
	s_nop 0
	v_addc_co_u32_e32 v71, vcc, 0, v91, vcc
	v_add_co_u32_e32 v74, vcc, s5, v90
	s_mov_b32 s5, 0x23c000
	s_nop 0
	v_addc_co_u32_e32 v75, vcc, 0, v91, vcc
	global_load_dwordx4 v[70:73], v[70:71], off nt
	s_nop 0
	global_load_dwordx4 v[74:77], v[74:75], off nt
	v_add_co_u32_e32 v78, vcc, s26, v90
	s_lshl_b32 s88, s1, 7
	s_nop 0
	v_addc_co_u32_e32 v79, vcc, 0, v91, vcc
	global_load_dwordx4 v[78:81], v[78:79], off nt
	v_add_co_u32_e32 v82, vcc, s5, v90
	s_mov_b32 s5, 0x268000
	s_nop 0
	v_addc_co_u32_e32 v83, vcc, 0, v91, vcc
	global_load_dwordx4 v[82:85], v[82:83], off nt
	v_add_co_u32_e32 v86, vcc, s5, v90
	s_mov_b32 s5, 0x294000
	s_nop 0
	v_addc_co_u32_e32 v87, vcc, 0, v91, vcc
	global_load_dwordx4 v[86:89], v[86:87], off nt
	v_add_co_u32_e32 v90, vcc, s5, v90
	s_and_b32 s1, s0, 0xffff
	s_nop 0
	v_addc_co_u32_e32 v91, vcc, 0, v91, vcc
	global_load_dwordx4 v[90:93], v[90:91], off nt
	s_waitcnt vmcnt(0)
	ds_write2_b32 v20, v30, v31 offset1:1
	ds_write2_b32 v20, v32, v33 offset0:2 offset1:3
	ds_write2_b32 v0, v34, v35 offset1:1
	v_add_u32_e32 v0, 0x418, v20
	ds_write2_b32 v0, v36, v37 offset1:1
	v_add_u32_e32 v0, 0x820, v20
	s_lshl_b32 s0, s0, 7
	s_and_b32 s0, s0, 0x7f00
	s_add_i32 s5, s0, 0xffffd480
	s_cmpk_lt_u32 s1, 0x58
	ds_write2_b32 v0, v38, v39 offset1:1
	v_add_u32_e32 v0, 0x828, v20
	ds_write2_b32 v0, v40, v41 offset1:1
	v_add_u32_e32 v0, 0xc30, v20
	ds_write2_b32 v0, v42, v43 offset1:1
	v_add_u32_e32 v0, 0xc38, v20
	ds_write2_b32 v0, v44, v45 offset1:1
	v_add_u32_e32 v0, 0x1040, v20
	s_cselect_b32 s0, s0, s5
	s_and_b32 s1, s4, 64
	s_or_b32 s0, s1, s0
	ds_write2_b32 v0, v46, v47 offset1:1
	v_add_u32_e32 v0, 0x1048, v20
	ds_write2_b32 v0, v48, v49 offset1:1
	v_add_u32_e32 v0, 0x1450, v20
	ds_write2_b32 v0, v50, v51 offset1:1
	v_add_u32_e32 v0, 0x1458, v20
	ds_write2_b32 v0, v52, v53 offset1:1
	v_add_u32_e32 v0, 0x1860, v20
	v_or_b32_e32 v52, s0, v21
	v_ashrrev_i32_e32 v53, 31, v52
	v_lshl_add_u64 v[50:51], v[10:11], 0, s[88:89]
	ds_write2_b32 v0, v54, v55 offset1:1
	v_add_u32_e32 v0, 0x1868, v20
	ds_write2_b32 v0, v56, v57 offset1:1
	v_add_u32_e32 v0, 0x1c70, v20
	ds_write2_b32 v0, v58, v59 offset1:1
	v_add_u32_e32 v0, 0x1c78, v20
	ds_write2_b32 v0, v60, v61 offset1:1
	v_add_u32_e32 v0, 0x2080, v20
	v_lshlrev_b64 v[52:53], 12, v[52:53]
	v_lshl_add_u64 v[52:53], v[50:51], 0, v[52:53]
	v_readlane_b32 s53, v248, 1
	ds_write2_b32 v0, v62, v63 offset1:1
	v_add_u32_e32 v0, 0x2088, v20
	ds_write2_b32 v0, v64, v65 offset1:1
	v_add_u32_e32 v0, 0x2490, v20
	ds_write2_b32 v0, v66, v67 offset1:1
	v_add_u32_e32 v0, 0x2498, v20
	ds_write2_b32 v0, v68, v69 offset1:1
	v_add_u32_e32 v0, 0x28a0, v20
	v_readlane_b32 s56, v248, 4
	v_readlane_b32 s57, v248, 5
	s_mov_b32 s57, 0x40000
	ds_write2_b32 v0, v70, v71 offset1:1
	v_add_u32_e32 v0, 0x28a8, v20
	ds_write2_b32 v0, v72, v73 offset1:1
	v_add_u32_e32 v0, 0x2cb0, v20
	ds_write2_b32 v0, v74, v75 offset1:1
	v_add_u32_e32 v0, 0x2cb8, v20
	ds_write2_b32 v0, v76, v77 offset1:1
	v_add_u32_e32 v0, 0x30c0, v20
	ds_write2_b32 v0, v78, v79 offset1:1
	v_add_u32_e32 v0, 0x30c8, v20
	ds_write2_b32 v0, v80, v81 offset1:1
	v_add_u32_e32 v0, 0x34d0, v20
	s_mov_b32 s56, 0x10000
	ds_write2_b32 v0, v82, v83 offset1:1
	v_add_u32_e32 v0, 0x34d8, v20
	ds_write2_b32 v0, v84, v85 offset1:1
	v_add_u32_e32 v0, 0x38e0, v20
	s_mov_b64 s[52:53], s[10:11]
	v_readlane_b32 s58, v248, 6
	ds_write2_b32 v0, v86, v87 offset1:1
	v_add_u32_e32 v0, 0x38e8, v20
	ds_write2_b32 v0, v88, v89 offset1:1
	v_add_u32_e32 v0, 0x3cf0, v20
	v_readlane_b32 s59, v248, 7
	ds_write2_b32 v0, v90, v91 offset1:1
	v_add_u32_e32 v0, 0x3cf8, v20
	ds_write2_b32 v0, v92, v93 offset1:1
	s_waitcnt lgkmcnt(0)
	v_add_u32_e32 v0, 0x400, v22
	ds_read2_b32 v[34:35], v22 offset0:65 offset1:73
	ds_read2_b32 v[36:37], v22 offset1:8
	ds_read2_b32 v[38:39], v22 offset0:130 offset1:138
	ds_read2_b32 v[40:41], v22 offset0:195 offset1:203
	ds_read2_b32 v[42:43], v0 offset0:4 offset1:12
	ds_read2_b32 v[44:45], v0 offset0:69 offset1:77
	ds_read2_b32 v[46:47], v0 offset0:134 offset1:142
	ds_read2_b32 v[48:49], v0 offset0:199 offset1:207
	s_waitcnt lgkmcnt(6)
	v_cvt_pk_bf16_f32 v30, v36, v34
	s_waitcnt lgkmcnt(2)
	v_cvt_pk_bf16_f32 v32, v42, v44
	v_cvt_pk_bf16_f32 v31, v38, v40
	s_waitcnt lgkmcnt(0)
	v_cvt_pk_bf16_f32 v33, v46, v48
	v_or_b32_e32 v34, s0, v23
	global_store_dwordx4 v[52:53], v[30:33], off
	s_nop 1
	v_cvt_pk_bf16_f32 v30, v37, v35
	v_ashrrev_i32_e32 v35, 31, v34
	v_cvt_pk_bf16_f32 v31, v39, v41
	v_cvt_pk_bf16_f32 v32, v43, v45
	v_cvt_pk_bf16_f32 v33, v47, v49
	v_lshlrev_b64 v[34:35], 12, v[34:35]
	ds_read2_b32 v[36:37], v22 offset0:81 offset1:89
	ds_read2_b32 v[38:39], v22 offset0:16 offset1:24
	ds_read2_b32 v[40:41], v22 offset0:146 offset1:154
	ds_read2_b32 v[42:43], v22 offset0:211 offset1:219
	ds_read2_b32 v[44:45], v0 offset0:20 offset1:28
	ds_read2_b32 v[46:47], v0 offset0:85 offset1:93
	ds_read2_b32 v[48:49], v0 offset0:150 offset1:158
	ds_read2_b32 v[52:53], v0 offset0:215 offset1:223
	v_lshl_add_u64 v[34:35], v[50:51], 0, v[34:35]
	global_store_dwordx4 v[34:35], v[30:33], off
	v_or_b32_e32 v34, s0, v24
	v_ashrrev_i32_e32 v35, 31, v34
	v_lshlrev_b64 v[34:35], 12, v[34:35]
	s_waitcnt lgkmcnt(6)
	v_cvt_pk_bf16_f32 v30, v38, v36
	s_waitcnt lgkmcnt(4)
	v_cvt_pk_bf16_f32 v31, v40, v42
	s_waitcnt lgkmcnt(2)
	v_cvt_pk_bf16_f32 v32, v44, v46
	s_waitcnt lgkmcnt(0)
	v_cvt_pk_bf16_f32 v33, v48, v52
	v_lshl_add_u64 v[34:35], v[50:51], 0, v[34:35]
	global_store_dwordx4 v[34:35], v[30:33], off
	v_or_b32_e32 v34, s0, v25
	v_ashrrev_i32_e32 v35, 31, v34
	v_cvt_pk_bf16_f32 v30, v39, v37
	v_cvt_pk_bf16_f32 v31, v41, v43
	v_cvt_pk_bf16_f32 v32, v45, v47
	v_cvt_pk_bf16_f32 v33, v49, v53
	v_lshlrev_b64 v[34:35], 12, v[34:35]
	ds_read2_b32 v[36:37], v22 offset0:32 offset1:40
	ds_read2_b32 v[38:39], v22 offset0:97 offset1:105
	ds_read2_b32 v[40:41], v22 offset0:162 offset1:170
	ds_read2_b32 v[42:43], v22 offset0:227 offset1:235
	ds_read2_b32 v[44:45], v0 offset0:36 offset1:44
	ds_read2_b32 v[46:47], v0 offset0:101 offset1:109
	ds_read2_b32 v[48:49], v0 offset0:166 offset1:174
	ds_read2_b32 v[52:53], v0 offset0:231 offset1:239
	v_lshl_add_u64 v[34:35], v[50:51], 0, v[34:35]
	global_store_dwordx4 v[34:35], v[30:33], off
	v_or_b32_e32 v34, s0, v26
	v_ashrrev_i32_e32 v35, 31, v34
	v_lshlrev_b64 v[34:35], 12, v[34:35]
	s_waitcnt lgkmcnt(6)
	v_cvt_pk_bf16_f32 v30, v36, v38
	s_waitcnt lgkmcnt(4)
	v_cvt_pk_bf16_f32 v31, v40, v42
	s_waitcnt lgkmcnt(2)
	v_cvt_pk_bf16_f32 v32, v44, v46
	s_waitcnt lgkmcnt(0)
	v_cvt_pk_bf16_f32 v33, v48, v52
	v_lshl_add_u64 v[34:35], v[50:51], 0, v[34:35]
	global_store_dwordx4 v[34:35], v[30:33], off
	v_or_b32_e32 v34, s0, v27
	v_ashrrev_i32_e32 v35, 31, v34
	v_cvt_pk_bf16_f32 v30, v37, v39
	v_cvt_pk_bf16_f32 v31, v41, v43
	v_cvt_pk_bf16_f32 v32, v45, v47
	v_cvt_pk_bf16_f32 v33, v49, v53
	v_lshlrev_b64 v[34:35], 12, v[34:35]
	ds_read2_b32 v[36:37], v22 offset0:48 offset1:56
	ds_read2_b32 v[38:39], v22 offset0:113 offset1:121
	ds_read2_b32 v[40:41], v22 offset0:178 offset1:186
	ds_read2_b32 v[42:43], v22 offset0:243 offset1:251
	ds_read2_b32 v[44:45], v0 offset0:52 offset1:60
	ds_read2_b32 v[46:47], v0 offset0:117 offset1:125
	ds_read2_b32 v[48:49], v0 offset0:182 offset1:190
	ds_read2_b32 v[52:53], v0 offset0:247 offset1:255
	v_lshl_add_u64 v[34:35], v[50:51], 0, v[34:35]
	global_store_dwordx4 v[34:35], v[30:33], off
	v_or_b32_e32 v34, s0, v28
	v_ashrrev_i32_e32 v35, 31, v34
	v_lshlrev_b64 v[34:35], 12, v[34:35]
	s_waitcnt lgkmcnt(6)
	v_cvt_pk_bf16_f32 v30, v36, v38
	s_waitcnt lgkmcnt(4)
	v_cvt_pk_bf16_f32 v31, v40, v42
	s_waitcnt lgkmcnt(2)
	v_cvt_pk_bf16_f32 v32, v44, v46
	s_waitcnt lgkmcnt(0)
	v_cvt_pk_bf16_f32 v33, v48, v52
	v_lshl_add_u64 v[34:35], v[50:51], 0, v[34:35]
	global_store_dwordx4 v[34:35], v[30:33], off
	v_or_b32_e32 v34, s0, v29
	v_ashrrev_i32_e32 v35, 31, v34
	v_lshlrev_b64 v[34:35], 12, v[34:35]
	v_cvt_pk_bf16_f32 v30, v37, v39
	v_cvt_pk_bf16_f32 v31, v41, v43
	v_cvt_pk_bf16_f32 v32, v45, v47
	v_cvt_pk_bf16_f32 v33, v49, v53
	v_lshl_add_u64 v[34:35], v[50:51], 0, v[34:35]
	global_store_dwordx4 v[34:35], v[30:33], off
	s_waitcnt lgkmcnt(0)

.LBB0_565:
	s_andn2_b64 vcc, exec, s[0:1]
	s_cbranch_vccnz .LBB0_567
	s_add_i32 s0, s9, 0x1c000
	s_and_b32 s1, s0, 0x1ffc0
	v_or_b32_e32 v0, s1, v3
	s_mov_b64 s[4:5], s[52:53]
	v_readlane_b32 s52, v248, 0
	s_and_b32 s0, s7, 0x7c0
	v_lshlrev_b32_e32 v0, 13, v0
	v_readlane_b32 s53, v248, 1
	s_lshl_b32 s88, s0, 2
	v_readlane_b32 s56, v248, 4
	v_lshl_add_u64 v[30:31], s[52:53], 0, v[0:1]
	v_lshl_add_u64 v[30:31], v[30:31], 0, s[88:89]
	v_lshlrev_b32_e32 v0, 2, v2
	v_lshl_add_u64 v[90:91], v[30:31], 0, v[0:1]
	v_add_co_u32_e32 v34, vcc, 0x8000, v90
	s_mov_b32 s56, 0x10000
	s_nop 0
	v_addc_co_u32_e32 v35, vcc, 0, v91, vcc
	v_add_co_u32_e32 v38, vcc, s56, v90
	s_mov_b64 s[52:53], s[4:5]
	global_load_dwordx4 v[30:33], v[90:91], off nt
	s_nop 0
	global_load_dwordx4 v[34:37], v[34:35], off nt
	v_addc_co_u32_e32 v39, vcc, 0, v91, vcc
	s_mov_b32 s4, 0x18000
	v_add_co_u32_e32 v42, vcc, s4, v90
	s_mov_b32 s4, 0x28000
	s_nop 0
	v_addc_co_u32_e32 v43, vcc, 0, v91, vcc
	global_load_dwordx4 v[38:41], v[38:39], off nt
	s_nop 0
	global_load_dwordx4 v[42:45], v[42:43], off nt
	v_add_co_u32_e32 v46, vcc, s65, v90
	v_readlane_b32 s57, v248, 5
	s_nop 0
	v_addc_co_u32_e32 v47, vcc, 0, v91, vcc
	v_add_co_u32_e32 v50, vcc, s4, v90
	s_mov_b32 s4, 0x30000
	s_nop 0
	v_addc_co_u32_e32 v51, vcc, 0, v91, vcc
	global_load_dwordx4 v[46:49], v[46:47], off nt
	s_nop 0
	global_load_dwordx4 v[50:53], v[50:51], off nt
	v_add_co_u32_e32 v54, vcc, s4, v90
	s_mov_b32 s4, 0x38000
	s_nop 0
	v_addc_co_u32_e32 v55, vcc, 0, v91, vcc
	v_add_co_u32_e32 v58, vcc, s4, v90
	s_mov_b32 s57, 0x40000
	s_nop 0
	v_addc_co_u32_e32 v59, vcc, 0, v91, vcc
	global_load_dwordx4 v[54:57], v[54:55], off nt
	s_nop 0
	global_load_dwordx4 v[58:61], v[58:59], off nt
	v_add_co_u32_e32 v62, vcc, s57, v90
	s_mov_b32 s4, 0x48000
	s_nop 0
	v_addc_co_u32_e32 v63, vcc, 0, v91, vcc
	v_add_co_u32_e32 v66, vcc, s4, v90
	s_mov_b32 s4, 0x58000
	s_nop 0
	v_addc_co_u32_e32 v67, vcc, 0, v91, vcc
	global_load_dwordx4 v[62:65], v[62:63], off nt
	s_nop 0
	global_load_dwordx4 v[66:69], v[66:67], off nt
	v_add_co_u32_e32 v70, vcc, s63, v90
	v_add_u32_e32 v0, 0x410, v20
	s_nop 0
	v_addc_co_u32_e32 v71, vcc, 0, v91, vcc
	v_add_co_u32_e32 v74, vcc, s4, v90
	s_mov_b32 s4, 0x68000
	s_nop 0
	v_addc_co_u32_e32 v75, vcc, 0, v91, vcc
	global_load_dwordx4 v[70:73], v[70:71], off nt
	s_nop 0
	global_load_dwordx4 v[74:77], v[74:75], off nt
	v_add_co_u32_e32 v78, vcc, s23, v90
	s_lshl_b32 s88, s1, 1
	s_nop 0
	v_addc_co_u32_e32 v79, vcc, 0, v91, vcc
	v_add_co_u32_e32 v82, vcc, s4, v90
	s_mov_b32 s4, 0x78000
	s_nop 0
	v_addc_co_u32_e32 v83, vcc, 0, v91, vcc
	global_load_dwordx4 v[78:81], v[78:79], off nt
	s_nop 0
	global_load_dwordx4 v[82:85], v[82:83], off nt
	v_add_co_u32_e32 v86, vcc, s44, v90
	v_readlane_b32 s54, v248, 2
	s_nop 0
	v_addc_co_u32_e32 v87, vcc, 0, v91, vcc
	global_load_dwordx4 v[86:89], v[86:87], off nt
	v_add_co_u32_e32 v90, vcc, s4, v90
	v_readlane_b32 s55, v248, 3
	s_nop 0
	v_addc_co_u32_e32 v91, vcc, 0, v91, vcc
	global_load_dwordx4 v[90:93], v[90:91], off nt
	s_waitcnt vmcnt(0)
	ds_write2_b32 v20, v30, v31 offset1:1
	ds_write2_b32 v20, v32, v33 offset0:2 offset1:3
	ds_write2_b32 v0, v34, v35 offset1:1
	v_add_u32_e32 v0, 0x418, v20
	ds_write2_b32 v0, v36, v37 offset1:1
	v_add_u32_e32 v0, 0x820, v20
	v_readlane_b32 s58, v248, 6
	v_readlane_b32 s59, v248, 7
	ds_write2_b32 v0, v38, v39 offset1:1
	v_add_u32_e32 v0, 0x828, v20
	ds_write2_b32 v0, v40, v41 offset1:1
	v_add_u32_e32 v0, 0xc30, v20
	ds_write2_b32 v0, v42, v43 offset1:1
	v_add_u32_e32 v0, 0xc38, v20
	ds_write2_b32 v0, v44, v45 offset1:1
	v_add_u32_e32 v0, 0x1040, v20
	ds_write2_b32 v0, v46, v47 offset1:1
	v_add_u32_e32 v0, 0x1048, v20
	ds_write2_b32 v0, v48, v49 offset1:1
	v_add_u32_e32 v0, 0x1450, v20
	ds_write2_b32 v0, v50, v51 offset1:1
	v_add_u32_e32 v0, 0x1458, v20
	ds_write2_b32 v0, v52, v53 offset1:1
	v_add_u32_e32 v0, 0x1860, v20
	v_lshl_add_u64 v[50:51], v[12:13], 0, s[88:89]
	ds_write2_b32 v0, v54, v55 offset1:1
	v_add_u32_e32 v0, 0x1868, v20
	ds_write2_b32 v0, v56, v57 offset1:1
	v_add_u32_e32 v0, 0x1c70, v20
	ds_write2_b32 v0, v58, v59 offset1:1
	v_add_u32_e32 v0, 0x1c78, v20
	ds_write2_b32 v0, v60, v61 offset1:1
	v_add_u32_e32 v0, 0x2080, v20
	v_add_u32_e32 v54, 0x400, v22
	ds_write2_b32 v0, v62, v63 offset1:1
	v_add_u32_e32 v0, 0x2088, v20
	ds_write2_b32 v0, v64, v65 offset1:1
	v_add_u32_e32 v0, 0x2490, v20
	ds_write2_b32 v0, v66, v67 offset1:1
	v_add_u32_e32 v0, 0x2498, v20
	ds_write2_b32 v0, v68, v69 offset1:1
	v_add_u32_e32 v0, 0x28a0, v20
	ds_write2_b32 v0, v70, v71 offset1:1
	v_add_u32_e32 v0, 0x28a8, v20
	ds_write2_b32 v0, v72, v73 offset1:1
	v_add_u32_e32 v0, 0x2cb0, v20
	ds_write2_b32 v0, v74, v75 offset1:1
	v_add_u32_e32 v0, 0x2cb8, v20
	ds_write2_b32 v0, v76, v77 offset1:1
	v_add_u32_e32 v0, 0x30c0, v20
	ds_write2_b32 v0, v78, v79 offset1:1
	v_add_u32_e32 v0, 0x30c8, v20
	ds_write2_b32 v0, v80, v81 offset1:1
	v_add_u32_e32 v0, 0x34d0, v20
	ds_write2_b32 v0, v82, v83 offset1:1
	v_add_u32_e32 v0, 0x34d8, v20
	ds_write2_b32 v0, v84, v85 offset1:1
	v_add_u32_e32 v0, 0x38e0, v20
	ds_write2_b32 v0, v86, v87 offset1:1
	v_add_u32_e32 v0, 0x38e8, v20
	ds_write2_b32 v0, v88, v89 offset1:1
	v_add_u32_e32 v0, 0x3cf0, v20
	ds_write2_b32 v0, v90, v91 offset1:1
	v_add_u32_e32 v0, 0x3cf8, v20
	ds_write2_b32 v0, v92, v93 offset1:1
	s_waitcnt lgkmcnt(0)
	ds_read2_b32 v[34:35], v22 offset0:65 offset1:73
	ds_read2_b32 v[36:37], v22 offset1:8
	ds_read2_b32 v[38:39], v22 offset0:130 offset1:138
	ds_read2_b32 v[40:41], v22 offset0:195 offset1:203
	ds_read2_b32 v[42:43], v54 offset0:4 offset1:12
	ds_read2_b32 v[44:45], v54 offset0:69 offset1:77
	ds_read2_b32 v[46:47], v54 offset0:134 offset1:142
	ds_read2_b32 v[48:49], v54 offset0:199 offset1:207
	v_or_b32_e32 v0, s0, v21
	v_lshlrev_b32_e32 v0, 12, v0
	s_waitcnt lgkmcnt(6)
	v_cvt_pk_bf16_f32 v30, v36, v34
	s_waitcnt lgkmcnt(4)
	v_cvt_pk_bf16_f32 v31, v38, v40
	s_waitcnt lgkmcnt(2)
	v_cvt_pk_bf16_f32 v32, v42, v44
	s_waitcnt lgkmcnt(0)
	v_cvt_pk_bf16_f32 v33, v46, v48
	v_lshl_add_u64 v[52:53], v[50:51], 0, v[0:1]
	global_store_dwordx4 v[52:53], v[30:33], off
	v_or_b32_e32 v0, s0, v23
	v_lshlrev_b32_e32 v0, 12, v0
	v_cvt_pk_bf16_f32 v30, v37, v35
	v_cvt_pk_bf16_f32 v31, v39, v41
	v_cvt_pk_bf16_f32 v32, v43, v45
	v_cvt_pk_bf16_f32 v33, v47, v49
	ds_read2_b32 v[36:37], v22 offset0:81 offset1:89
	ds_read2_b32 v[38:39], v22 offset0:16 offset1:24
	ds_read2_b32 v[40:41], v22 offset0:146 offset1:154
	ds_read2_b32 v[42:43], v22 offset0:211 offset1:219
	ds_read2_b32 v[44:45], v54 offset0:20 offset1:28
	ds_read2_b32 v[46:47], v54 offset0:85 offset1:93
	ds_read2_b32 v[48:49], v54 offset0:150 offset1:158
	ds_read2_b32 v[52:53], v54 offset0:215 offset1:223
	v_lshl_add_u64 v[34:35], v[50:51], 0, v[0:1]
	v_or_b32_e32 v0, s0, v24
	v_lshlrev_b32_e32 v0, 12, v0
	global_store_dwordx4 v[34:35], v[30:33], off
	v_lshl_add_u64 v[34:35], v[50:51], 0, v[0:1]
	v_or_b32_e32 v0, s0, v25
	s_waitcnt lgkmcnt(6)
	v_cvt_pk_bf16_f32 v30, v38, v36
	s_waitcnt lgkmcnt(4)
	v_cvt_pk_bf16_f32 v31, v40, v42
	s_waitcnt lgkmcnt(2)
	v_cvt_pk_bf16_f32 v32, v44, v46
	s_waitcnt lgkmcnt(0)
	v_cvt_pk_bf16_f32 v33, v48, v52
	global_store_dwordx4 v[34:35], v[30:33], off
	v_lshlrev_b32_e32 v0, 12, v0
	v_lshl_add_u64 v[34:35], v[50:51], 0, v[0:1]
	v_cvt_pk_bf16_f32 v30, v39, v37
	v_cvt_pk_bf16_f32 v31, v41, v43
	v_cvt_pk_bf16_f32 v32, v45, v47
	v_cvt_pk_bf16_f32 v33, v49, v53
	ds_read2_b32 v[36:37], v22 offset0:32 offset1:40
	ds_read2_b32 v[38:39], v22 offset0:97 offset1:105
	ds_read2_b32 v[40:41], v22 offset0:162 offset1:170
	ds_read2_b32 v[42:43], v22 offset0:227 offset1:235
	ds_read2_b32 v[44:45], v54 offset0:36 offset1:44
	ds_read2_b32 v[46:47], v54 offset0:101 offset1:109
	ds_read2_b32 v[48:49], v54 offset0:166 offset1:174
	ds_read2_b32 v[52:53], v54 offset0:231 offset1:239
	v_or_b32_e32 v0, s0, v26
	v_lshlrev_b32_e32 v0, 12, v0
	global_store_dwordx4 v[34:35], v[30:33], off
	v_lshl_add_u64 v[34:35], v[50:51], 0, v[0:1]
	v_or_b32_e32 v0, s0, v27
	s_waitcnt lgkmcnt(6)
	v_cvt_pk_bf16_f32 v30, v36, v38
	s_waitcnt lgkmcnt(4)
	v_cvt_pk_bf16_f32 v31, v40, v42
	s_waitcnt lgkmcnt(2)
	v_cvt_pk_bf16_f32 v32, v44, v46
	s_waitcnt lgkmcnt(0)
	v_cvt_pk_bf16_f32 v33, v48, v52
	global_store_dwordx4 v[34:35], v[30:33], off
	v_lshlrev_b32_e32 v0, 12, v0
	v_lshl_add_u64 v[34:35], v[50:51], 0, v[0:1]
	v_cvt_pk_bf16_f32 v30, v37, v39
	v_cvt_pk_bf16_f32 v31, v41, v43
	v_cvt_pk_bf16_f32 v32, v45, v47
	v_cvt_pk_bf16_f32 v33, v49, v53
	ds_read2_b32 v[36:37], v22 offset0:48 offset1:56
	ds_read2_b32 v[38:39], v22 offset0:113 offset1:121
	ds_read2_b32 v[40:41], v22 offset0:178 offset1:186
	ds_read2_b32 v[42:43], v22 offset0:243 offset1:251
	ds_read2_b32 v[44:45], v54 offset0:52 offset1:60
	ds_read2_b32 v[46:47], v54 offset0:117 offset1:125
	ds_read2_b32 v[48:49], v54 offset0:182 offset1:190
	ds_read2_b32 v[52:53], v54 offset0:247 offset1:255
	v_or_b32_e32 v0, s0, v28
	v_lshlrev_b32_e32 v0, 12, v0
	global_store_dwordx4 v[34:35], v[30:33], off
	v_lshl_add_u64 v[34:35], v[50:51], 0, v[0:1]
	v_or_b32_e32 v0, s0, v29
	s_waitcnt lgkmcnt(6)
	v_cvt_pk_bf16_f32 v30, v36, v38
	s_waitcnt lgkmcnt(4)
	v_cvt_pk_bf16_f32 v31, v40, v42
	s_waitcnt lgkmcnt(2)
	v_cvt_pk_bf16_f32 v32, v44, v46
	s_waitcnt lgkmcnt(0)
	v_cvt_pk_bf16_f32 v33, v48, v52
	v_lshlrev_b32_e32 v0, 12, v0
	global_store_dwordx4 v[34:35], v[30:33], off
	v_lshl_add_u64 v[34:35], v[50:51], 0, v[0:1]
	s_nop 0
	v_cvt_pk_bf16_f32 v30, v37, v39
	v_cvt_pk_bf16_f32 v31, v41, v43
	v_cvt_pk_bf16_f32 v32, v45, v47
	v_cvt_pk_bf16_f32 v33, v49, v53
	global_store_dwordx4 v[34:35], v[30:33], off
	s_waitcnt lgkmcnt(0)

.LBB0_568:
	s_andn2_b64 vcc, exec, s[0:1]
	s_cbranch_vccnz .LBB0_570
	s_add_i32 s0, s3, 0xec00
	s_and_b32 s1, s0, 0xffff
	s_mul_i32 s1, s1, 0xaaab
	s_lshr_b32 s4, s1, 16
	s_lshr_b32 s1, s1, 22
	s_mulk_i32 s1, 0x60
	s_sub_i32 s0, s0, s1
	s_and_b32 s1, s4, 0xffc0
	s_lshl_b32 s0, s0, 6
	v_or_b32_e32 v0, s1, v3
	v_readlane_b32 s68, v246, 43
	s_and_b32 s0, s0, 0xffc0
	v_mul_u32_u24_e32 v0, 0x6000, v0
	v_readlane_b32 s76, v246, 51
	v_readlane_b32 s77, v246, 52
	s_lshl_b32 s88, s0, 2
	s_mov_b32 s4, 0x18000
	v_lshl_add_u64 v[30:31], s[76:77], 0, v[0:1]
	v_lshl_add_u64 v[30:31], v[30:31], 0, s[88:89]
	v_lshlrev_b32_e32 v0, 2, v2
	v_lshl_add_u64 v[90:91], v[30:31], 0, v[0:1]
	v_add_co_u32_e32 v34, vcc, s4, v90
	s_mov_b32 s4, 0x30000
	s_nop 0
	v_addc_co_u32_e32 v35, vcc, 0, v91, vcc
	v_add_co_u32_e32 v38, vcc, s4, v90
	global_load_dwordx4 v[30:33], v[90:91], off nt
	s_nop 0
	global_load_dwordx4 v[34:37], v[34:35], off nt
	v_addc_co_u32_e32 v39, vcc, 0, v91, vcc
	s_mov_b32 s4, 0x48000
	v_add_co_u32_e32 v42, vcc, s4, v90
	s_mov_b32 s4, 0x78000
	s_nop 0
	v_addc_co_u32_e32 v43, vcc, 0, v91, vcc
	global_load_dwordx4 v[38:41], v[38:39], off nt
	s_nop 0
	global_load_dwordx4 v[42:45], v[42:43], off nt
	v_add_co_u32_e32 v46, vcc, s23, v90
	v_add_u32_e32 v0, 0x410, v20
	s_nop 0
	v_addc_co_u32_e32 v47, vcc, 0, v91, vcc
	v_add_co_u32_e32 v50, vcc, s4, v90
	s_mov_b32 s4, 0x90000
	s_nop 0
	v_addc_co_u32_e32 v51, vcc, 0, v91, vcc
	global_load_dwordx4 v[46:49], v[46:47], off nt
	s_nop 0
	global_load_dwordx4 v[50:53], v[50:51], off nt
	v_add_co_u32_e32 v54, vcc, s4, v90
	s_mov_b32 s4, 0xa8000
	s_nop 0
	v_addc_co_u32_e32 v55, vcc, 0, v91, vcc
	v_add_co_u32_e32 v58, vcc, s4, v90
	s_mov_b32 s4, 0xd8000
	s_nop 0
	v_addc_co_u32_e32 v59, vcc, 0, v91, vcc
	global_load_dwordx4 v[54:57], v[54:55], off nt
	s_nop 0
	global_load_dwordx4 v[58:61], v[58:59], off nt
	v_add_co_u32_e32 v62, vcc, s84, v90
	s_lshl_b32 s88, s1, 1
	s_nop 0
	v_addc_co_u32_e32 v63, vcc, 0, v91, vcc
	v_add_co_u32_e32 v66, vcc, s4, v90
	s_mov_b32 s4, 0xf0000
	s_nop 0
	v_addc_co_u32_e32 v67, vcc, 0, v91, vcc
	global_load_dwordx4 v[62:65], v[62:63], off nt
	s_nop 0
	global_load_dwordx4 v[66:69], v[66:67], off nt
	v_add_co_u32_e32 v70, vcc, s4, v90
	s_mov_b32 s4, 0x108000
	s_nop 0
	v_addc_co_u32_e32 v71, vcc, 0, v91, vcc
	v_add_co_u32_e32 v74, vcc, s4, v90
	s_mov_b32 s4, 0x138000
	s_nop 0
	v_addc_co_u32_e32 v75, vcc, 0, v91, vcc
	global_load_dwordx4 v[70:73], v[70:71], off nt
	s_nop 0
	global_load_dwordx4 v[74:77], v[74:75], off nt
	v_add_co_u32_e32 v78, vcc, s27, v90
	v_readlane_b32 s74, v246, 49
	s_nop 0
	v_addc_co_u32_e32 v79, vcc, 0, v91, vcc
	global_load_dwordx4 v[78:81], v[78:79], off nt
	v_add_co_u32_e32 v82, vcc, s4, v90
	s_mov_b32 s4, 0x150000
	s_nop 0
	v_addc_co_u32_e32 v83, vcc, 0, v91, vcc
	global_load_dwordx4 v[82:85], v[82:83], off nt
	v_add_co_u32_e32 v86, vcc, s4, v90
	s_mov_b32 s4, 0x168000
	s_nop 0
	v_addc_co_u32_e32 v87, vcc, 0, v91, vcc
	global_load_dwordx4 v[86:89], v[86:87], off nt
	v_add_co_u32_e32 v90, vcc, s4, v90
	v_readlane_b32 s75, v246, 50
	s_nop 0
	v_addc_co_u32_e32 v91, vcc, 0, v91, vcc
	global_load_dwordx4 v[90:93], v[90:91], off nt
	s_waitcnt vmcnt(0)
	ds_write2_b32 v20, v30, v31 offset1:1
	ds_write2_b32 v20, v32, v33 offset0:2 offset1:3
	ds_write2_b32 v0, v34, v35 offset1:1
	v_add_u32_e32 v0, 0x418, v20
	ds_write2_b32 v0, v36, v37 offset1:1
	v_add_u32_e32 v0, 0x820, v20
	v_readlane_b32 s72, v246, 47
	v_readlane_b32 s74, v245, 58
	s_mov_b64 s[90:91], s[12:13]
	v_readlane_b32 s75, v245, 59
	ds_write2_b32 v0, v38, v39 offset1:1
	v_add_u32_e32 v0, 0x828, v20
	ds_write2_b32 v0, v40, v41 offset1:1
	v_add_u32_e32 v0, 0xc30, v20
	ds_write2_b32 v0, v42, v43 offset1:1
	v_add_u32_e32 v0, 0xc38, v20
	ds_write2_b32 v0, v44, v45 offset1:1
	v_add_u32_e32 v0, 0x1040, v20
	v_readlane_b32 s72, v245, 15
	v_readlane_b32 s69, v246, 44
	v_readlane_b32 s70, v246, 45
	ds_write2_b32 v0, v46, v47 offset1:1
	v_add_u32_e32 v0, 0x1048, v20
	ds_write2_b32 v0, v48, v49 offset1:1
	v_add_u32_e32 v0, 0x1450, v20
	ds_write2_b32 v0, v50, v51 offset1:1
	v_add_u32_e32 v0, 0x1458, v20
	ds_write2_b32 v0, v52, v53 offset1:1
	v_add_u32_e32 v0, 0x1860, v20
	v_lshl_add_u64 v[50:51], v[14:15], 0, s[88:89]
	v_readlane_b32 s71, v246, 46
	v_readlane_b32 s73, v246, 48
	ds_write2_b32 v0, v54, v55 offset1:1
	v_add_u32_e32 v0, 0x1868, v20
	ds_write2_b32 v0, v56, v57 offset1:1
	v_add_u32_e32 v0, 0x1c70, v20
	ds_write2_b32 v0, v58, v59 offset1:1
	v_add_u32_e32 v0, 0x1c78, v20
	ds_write2_b32 v0, v60, v61 offset1:1
	v_add_u32_e32 v0, 0x2080, v20
	v_add_u32_e32 v54, 0x400, v22
	v_readlane_b32 s78, v246, 53
	v_readlane_b32 s79, v246, 54
	ds_write2_b32 v0, v62, v63 offset1:1
	v_add_u32_e32 v0, 0x2088, v20
	ds_write2_b32 v0, v64, v65 offset1:1
	v_add_u32_e32 v0, 0x2490, v20
	ds_write2_b32 v0, v66, v67 offset1:1
	v_add_u32_e32 v0, 0x2498, v20
	ds_write2_b32 v0, v68, v69 offset1:1
	v_add_u32_e32 v0, 0x28a0, v20
	v_readlane_b32 s80, v246, 55
	v_readlane_b32 s81, v246, 56
	v_readlane_b32 s82, v246, 57
	ds_write2_b32 v0, v70, v71 offset1:1
	v_add_u32_e32 v0, 0x28a8, v20
	ds_write2_b32 v0, v72, v73 offset1:1
	v_add_u32_e32 v0, 0x2cb0, v20
	ds_write2_b32 v0, v74, v75 offset1:1
	v_add_u32_e32 v0, 0x2cb8, v20
	ds_write2_b32 v0, v76, v77 offset1:1
	v_add_u32_e32 v0, 0x30c0, v20
	ds_write2_b32 v0, v78, v79 offset1:1
	v_add_u32_e32 v0, 0x30c8, v20
	ds_write2_b32 v0, v80, v81 offset1:1
	v_add_u32_e32 v0, 0x34d0, v20
	v_readlane_b32 s83, v246, 58
	ds_write2_b32 v0, v82, v83 offset1:1
	v_add_u32_e32 v0, 0x34d8, v20
	ds_write2_b32 v0, v84, v85 offset1:1
	v_add_u32_e32 v0, 0x38e0, v20
	ds_write2_b32 v0, v86, v87 offset1:1
	v_add_u32_e32 v0, 0x38e8, v20
	ds_write2_b32 v0, v88, v89 offset1:1
	v_add_u32_e32 v0, 0x3cf0, v20
	ds_write2_b32 v0, v90, v91 offset1:1
	v_add_u32_e32 v0, 0x3cf8, v20
	ds_write2_b32 v0, v92, v93 offset1:1
	s_waitcnt lgkmcnt(0)
	ds_read2_b32 v[34:35], v22 offset0:65 offset1:73
	ds_read2_b32 v[36:37], v22 offset1:8
	ds_read2_b32 v[38:39], v22 offset0:130 offset1:138
	ds_read2_b32 v[40:41], v22 offset0:195 offset1:203
	ds_read2_b32 v[42:43], v54 offset0:4 offset1:12
	ds_read2_b32 v[44:45], v54 offset0:69 offset1:77
	ds_read2_b32 v[46:47], v54 offset0:134 offset1:142
	ds_read2_b32 v[48:49], v54 offset0:199 offset1:207
	v_or_b32_e32 v0, s0, v21
	v_lshlrev_b32_e32 v0, 12, v0
	s_waitcnt lgkmcnt(6)
	v_cvt_pk_bf16_f32 v30, v36, v34
	s_waitcnt lgkmcnt(4)
	v_cvt_pk_bf16_f32 v31, v38, v40
	s_waitcnt lgkmcnt(2)
	v_cvt_pk_bf16_f32 v32, v42, v44
	s_waitcnt lgkmcnt(0)
	v_cvt_pk_bf16_f32 v33, v46, v48
	v_lshl_add_u64 v[52:53], v[50:51], 0, v[0:1]
	global_store_dwordx4 v[52:53], v[30:33], off
	v_or_b32_e32 v0, s0, v23
	v_lshlrev_b32_e32 v0, 12, v0
	v_cvt_pk_bf16_f32 v30, v37, v35
	v_cvt_pk_bf16_f32 v31, v39, v41
	v_cvt_pk_bf16_f32 v32, v43, v45
	v_cvt_pk_bf16_f32 v33, v47, v49
	ds_read2_b32 v[36:37], v22 offset0:81 offset1:89
	ds_read2_b32 v[38:39], v22 offset0:16 offset1:24
	ds_read2_b32 v[40:41], v22 offset0:146 offset1:154
	ds_read2_b32 v[42:43], v22 offset0:211 offset1:219
	ds_read2_b32 v[44:45], v54 offset0:20 offset1:28
	ds_read2_b32 v[46:47], v54 offset0:85 offset1:93
	ds_read2_b32 v[48:49], v54 offset0:150 offset1:158
	ds_read2_b32 v[52:53], v54 offset0:215 offset1:223
	v_lshl_add_u64 v[34:35], v[50:51], 0, v[0:1]
	v_or_b32_e32 v0, s0, v24
	v_lshlrev_b32_e32 v0, 12, v0
	global_store_dwordx4 v[34:35], v[30:33], off
	v_lshl_add_u64 v[34:35], v[50:51], 0, v[0:1]
	v_or_b32_e32 v0, s0, v25
	s_waitcnt lgkmcnt(6)
	v_cvt_pk_bf16_f32 v30, v38, v36
	s_waitcnt lgkmcnt(4)
	v_cvt_pk_bf16_f32 v31, v40, v42
	s_waitcnt lgkmcnt(2)
	v_cvt_pk_bf16_f32 v32, v44, v46
	s_waitcnt lgkmcnt(0)
	v_cvt_pk_bf16_f32 v33, v48, v52
	global_store_dwordx4 v[34:35], v[30:33], off
	v_lshlrev_b32_e32 v0, 12, v0
	v_lshl_add_u64 v[34:35], v[50:51], 0, v[0:1]
	v_cvt_pk_bf16_f32 v30, v39, v37
	v_cvt_pk_bf16_f32 v31, v41, v43
	v_cvt_pk_bf16_f32 v32, v45, v47
	v_cvt_pk_bf16_f32 v33, v49, v53
	ds_read2_b32 v[36:37], v22 offset0:32 offset1:40
	ds_read2_b32 v[38:39], v22 offset0:97 offset1:105
	ds_read2_b32 v[40:41], v22 offset0:162 offset1:170
	ds_read2_b32 v[42:43], v22 offset0:227 offset1:235
	ds_read2_b32 v[44:45], v54 offset0:36 offset1:44
	ds_read2_b32 v[46:47], v54 offset0:101 offset1:109
	ds_read2_b32 v[48:49], v54 offset0:166 offset1:174
	ds_read2_b32 v[52:53], v54 offset0:231 offset1:239
	v_or_b32_e32 v0, s0, v26
	v_lshlrev_b32_e32 v0, 12, v0
	global_store_dwordx4 v[34:35], v[30:33], off
	v_lshl_add_u64 v[34:35], v[50:51], 0, v[0:1]
	v_or_b32_e32 v0, s0, v27
	s_waitcnt lgkmcnt(6)
	v_cvt_pk_bf16_f32 v30, v36, v38
	s_waitcnt lgkmcnt(4)
	v_cvt_pk_bf16_f32 v31, v40, v42
	s_waitcnt lgkmcnt(2)
	v_cvt_pk_bf16_f32 v32, v44, v46
	s_waitcnt lgkmcnt(0)
	v_cvt_pk_bf16_f32 v33, v48, v52
	global_store_dwordx4 v[34:35], v[30:33], off
	v_lshlrev_b32_e32 v0, 12, v0
	v_lshl_add_u64 v[34:35], v[50:51], 0, v[0:1]
	v_cvt_pk_bf16_f32 v30, v37, v39
	v_cvt_pk_bf16_f32 v31, v41, v43
	v_cvt_pk_bf16_f32 v32, v45, v47
	v_cvt_pk_bf16_f32 v33, v49, v53
	ds_read2_b32 v[36:37], v22 offset0:48 offset1:56
	ds_read2_b32 v[38:39], v22 offset0:113 offset1:121
	ds_read2_b32 v[40:41], v22 offset0:178 offset1:186
	ds_read2_b32 v[42:43], v22 offset0:243 offset1:251
	ds_read2_b32 v[44:45], v54 offset0:52 offset1:60
	ds_read2_b32 v[46:47], v54 offset0:117 offset1:125
	ds_read2_b32 v[48:49], v54 offset0:182 offset1:190
	ds_read2_b32 v[52:53], v54 offset0:247 offset1:255
	v_or_b32_e32 v0, s0, v28
	v_lshlrev_b32_e32 v0, 12, v0
	global_store_dwordx4 v[34:35], v[30:33], off
	v_lshl_add_u64 v[34:35], v[50:51], 0, v[0:1]
	v_or_b32_e32 v0, s0, v29
	s_waitcnt lgkmcnt(6)
	v_cvt_pk_bf16_f32 v30, v36, v38
	s_waitcnt lgkmcnt(4)
	v_cvt_pk_bf16_f32 v31, v40, v42
	s_waitcnt lgkmcnt(2)
	v_cvt_pk_bf16_f32 v32, v44, v46
	s_waitcnt lgkmcnt(0)
	v_cvt_pk_bf16_f32 v33, v48, v52
	v_lshlrev_b32_e32 v0, 12, v0
	global_store_dwordx4 v[34:35], v[30:33], off
	v_lshl_add_u64 v[34:35], v[50:51], 0, v[0:1]
	s_nop 0
	v_cvt_pk_bf16_f32 v30, v37, v39
	v_cvt_pk_bf16_f32 v31, v41, v43
	v_cvt_pk_bf16_f32 v32, v45, v47
	v_cvt_pk_bf16_f32 v33, v49, v53
	global_store_dwordx4 v[34:35], v[30:33], off
	s_waitcnt lgkmcnt(0)

.LBB0_571:
	s_andn2_b64 vcc, exec, s[0:1]
	s_cbranch_vccnz .LBB0_573
	s_add_i32 s0, s9, 0x1e000
	s_and_b32 s1, s0, 0x1ffc0
	v_or_b32_e32 v0, s1, v3
	v_readlane_b32 s68, v246, 43
	s_and_b32 s0, s7, 0x7c0
	v_lshlrev_b32_e32 v0, 13, v0
	v_readlane_b32 s74, v246, 49
	v_readlane_b32 s75, v246, 50
	s_lshl_b32 s88, s0, 2
	s_mov_b32 s4, 0x18000
	v_lshl_add_u64 v[30:31], s[74:75], 0, v[0:1]
	v_lshl_add_u64 v[30:31], v[30:31], 0, s[88:89]
	v_lshlrev_b32_e32 v0, 2, v2
	v_lshl_add_u64 v[90:91], v[30:31], 0, v[0:1]
	v_add_co_u32_e32 v34, vcc, 0x8000, v90
	v_add_u32_e32 v0, 0x410, v20
	s_nop 0
	v_addc_co_u32_e32 v35, vcc, 0, v91, vcc
	v_add_co_u32_e32 v38, vcc, s56, v90
	global_load_dwordx4 v[30:33], v[90:91], off nt
	s_nop 0
	global_load_dwordx4 v[34:37], v[34:35], off nt
	v_addc_co_u32_e32 v39, vcc, 0, v91, vcc
	v_add_co_u32_e32 v42, vcc, s4, v90
	s_mov_b32 s4, 0x28000
	s_nop 0
	v_addc_co_u32_e32 v43, vcc, 0, v91, vcc
	global_load_dwordx4 v[38:41], v[38:39], off nt
	s_nop 0
	global_load_dwordx4 v[42:45], v[42:43], off nt
	v_add_co_u32_e32 v46, vcc, s65, v90
	s_lshl_b32 s88, s1, 1
	s_nop 0
	v_addc_co_u32_e32 v47, vcc, 0, v91, vcc
	v_add_co_u32_e32 v50, vcc, s4, v90
	s_mov_b32 s4, 0x30000
	s_nop 0
	v_addc_co_u32_e32 v51, vcc, 0, v91, vcc
	global_load_dwordx4 v[46:49], v[46:47], off nt
	s_nop 0
	global_load_dwordx4 v[50:53], v[50:51], off nt
	v_add_co_u32_e32 v54, vcc, s4, v90
	s_mov_b32 s4, 0x38000
	s_nop 0
	v_addc_co_u32_e32 v55, vcc, 0, v91, vcc
	v_add_co_u32_e32 v58, vcc, s4, v90
	s_mov_b32 s4, 0x48000
	s_nop 0
	v_addc_co_u32_e32 v59, vcc, 0, v91, vcc
	global_load_dwordx4 v[54:57], v[54:55], off nt
	s_nop 0
	global_load_dwordx4 v[58:61], v[58:59], off nt
	v_add_co_u32_e32 v62, vcc, s57, v90
	v_readlane_b32 s72, v246, 47
	s_nop 0
	v_addc_co_u32_e32 v63, vcc, 0, v91, vcc
	v_add_co_u32_e32 v66, vcc, s4, v90
	s_mov_b32 s4, 0x58000
	s_nop 0
	v_addc_co_u32_e32 v67, vcc, 0, v91, vcc
	global_load_dwordx4 v[62:65], v[62:63], off nt
	s_nop 0
	global_load_dwordx4 v[66:69], v[66:67], off nt
	v_add_co_u32_e32 v70, vcc, s63, v90
	v_readlane_b32 s74, v245, 58
	s_nop 0
	v_addc_co_u32_e32 v71, vcc, 0, v91, vcc
	v_add_co_u32_e32 v74, vcc, s4, v90
	s_mov_b32 s4, 0x68000
	s_nop 0
	v_addc_co_u32_e32 v75, vcc, 0, v91, vcc
	global_load_dwordx4 v[70:73], v[70:71], off nt
	s_nop 0
	global_load_dwordx4 v[74:77], v[74:75], off nt
	v_add_co_u32_e32 v78, vcc, s23, v90
	s_mov_b64 s[90:91], s[12:13]
	s_nop 0
	v_addc_co_u32_e32 v79, vcc, 0, v91, vcc
	v_add_co_u32_e32 v82, vcc, s4, v90
	s_mov_b32 s4, 0x78000
	s_nop 0
	v_addc_co_u32_e32 v83, vcc, 0, v91, vcc
	global_load_dwordx4 v[78:81], v[78:79], off nt
	s_nop 0
	global_load_dwordx4 v[82:85], v[82:83], off nt
	v_add_co_u32_e32 v86, vcc, s44, v90
	v_readlane_b32 s72, v245, 15
	s_nop 0
	v_addc_co_u32_e32 v87, vcc, 0, v91, vcc
	global_load_dwordx4 v[86:89], v[86:87], off nt
	v_add_co_u32_e32 v90, vcc, s4, v90
	v_readlane_b32 s75, v245, 59
	s_nop 0
	v_addc_co_u32_e32 v91, vcc, 0, v91, vcc
	global_load_dwordx4 v[90:93], v[90:91], off nt
	s_waitcnt vmcnt(0)
	ds_write2_b32 v20, v30, v31 offset1:1
	ds_write2_b32 v20, v32, v33 offset0:2 offset1:3
	ds_write2_b32 v0, v34, v35 offset1:1
	v_add_u32_e32 v0, 0x418, v20
	ds_write2_b32 v0, v36, v37 offset1:1
	v_add_u32_e32 v0, 0x820, v20
	v_readlane_b32 s69, v246, 44
	v_readlane_b32 s70, v246, 45
	v_readlane_b32 s71, v246, 46
	ds_write2_b32 v0, v38, v39 offset1:1
	v_add_u32_e32 v0, 0x828, v20
	ds_write2_b32 v0, v40, v41 offset1:1
	v_add_u32_e32 v0, 0xc30, v20
	ds_write2_b32 v0, v42, v43 offset1:1
	v_add_u32_e32 v0, 0xc38, v20
	ds_write2_b32 v0, v44, v45 offset1:1
	v_add_u32_e32 v0, 0x1040, v20
	v_readlane_b32 s73, v246, 48
	v_readlane_b32 s76, v246, 51
	v_readlane_b32 s77, v246, 52
	ds_write2_b32 v0, v46, v47 offset1:1
	v_add_u32_e32 v0, 0x1048, v20
	ds_write2_b32 v0, v48, v49 offset1:1
	v_add_u32_e32 v0, 0x1450, v20
	ds_write2_b32 v0, v50, v51 offset1:1
	v_add_u32_e32 v0, 0x1458, v20
	ds_write2_b32 v0, v52, v53 offset1:1
	v_add_u32_e32 v0, 0x1860, v20
	v_lshl_add_u64 v[50:51], v[16:17], 0, s[88:89]
	v_readlane_b32 s78, v246, 53
	v_readlane_b32 s79, v246, 54
	ds_write2_b32 v0, v54, v55 offset1:1
	v_add_u32_e32 v0, 0x1868, v20
	ds_write2_b32 v0, v56, v57 offset1:1
	v_add_u32_e32 v0, 0x1c70, v20
	ds_write2_b32 v0, v58, v59 offset1:1
	v_add_u32_e32 v0, 0x1c78, v20
	ds_write2_b32 v0, v60, v61 offset1:1
	v_add_u32_e32 v0, 0x2080, v20
	v_add_u32_e32 v54, 0x400, v22
	v_readlane_b32 s80, v246, 55
	v_readlane_b32 s81, v246, 56
	ds_write2_b32 v0, v62, v63 offset1:1
	v_add_u32_e32 v0, 0x2088, v20
	ds_write2_b32 v0, v64, v65 offset1:1
	v_add_u32_e32 v0, 0x2490, v20
	ds_write2_b32 v0, v66, v67 offset1:1
	v_add_u32_e32 v0, 0x2498, v20
	ds_write2_b32 v0, v68, v69 offset1:1
	v_add_u32_e32 v0, 0x28a0, v20
	v_readlane_b32 s82, v246, 57
	v_readlane_b32 s83, v246, 58
	ds_write2_b32 v0, v70, v71 offset1:1
	v_add_u32_e32 v0, 0x28a8, v20
	ds_write2_b32 v0, v72, v73 offset1:1
	v_add_u32_e32 v0, 0x2cb0, v20
	ds_write2_b32 v0, v74, v75 offset1:1
	v_add_u32_e32 v0, 0x2cb8, v20
	ds_write2_b32 v0, v76, v77 offset1:1
	v_add_u32_e32 v0, 0x30c0, v20
	ds_write2_b32 v0, v78, v79 offset1:1
	v_add_u32_e32 v0, 0x30c8, v20
	ds_write2_b32 v0, v80, v81 offset1:1
	v_add_u32_e32 v0, 0x34d0, v20
	ds_write2_b32 v0, v82, v83 offset1:1
	v_add_u32_e32 v0, 0x34d8, v20
	ds_write2_b32 v0, v84, v85 offset1:1
	v_add_u32_e32 v0, 0x38e0, v20
	ds_write2_b32 v0, v86, v87 offset1:1
	v_add_u32_e32 v0, 0x38e8, v20
	ds_write2_b32 v0, v88, v89 offset1:1
	v_add_u32_e32 v0, 0x3cf0, v20
	ds_write2_b32 v0, v90, v91 offset1:1
	v_add_u32_e32 v0, 0x3cf8, v20
	ds_write2_b32 v0, v92, v93 offset1:1
	s_waitcnt lgkmcnt(0)
	ds_read2_b32 v[34:35], v22 offset0:65 offset1:73
	ds_read2_b32 v[36:37], v22 offset1:8
	ds_read2_b32 v[38:39], v22 offset0:130 offset1:138
	ds_read2_b32 v[40:41], v22 offset0:195 offset1:203
	ds_read2_b32 v[42:43], v54 offset0:4 offset1:12
	ds_read2_b32 v[44:45], v54 offset0:69 offset1:77
	ds_read2_b32 v[46:47], v54 offset0:134 offset1:142
	ds_read2_b32 v[48:49], v54 offset0:199 offset1:207
	v_or_b32_e32 v0, s0, v21
	v_lshlrev_b32_e32 v0, 12, v0
	s_waitcnt lgkmcnt(6)
	v_cvt_pk_bf16_f32 v30, v36, v34
	s_waitcnt lgkmcnt(4)
	v_cvt_pk_bf16_f32 v31, v38, v40
	s_waitcnt lgkmcnt(2)
	v_cvt_pk_bf16_f32 v32, v42, v44
	s_waitcnt lgkmcnt(0)
	v_cvt_pk_bf16_f32 v33, v46, v48
	v_lshl_add_u64 v[52:53], v[50:51], 0, v[0:1]
	global_store_dwordx4 v[52:53], v[30:33], off
	v_or_b32_e32 v0, s0, v23
	v_lshlrev_b32_e32 v0, 12, v0
	v_cvt_pk_bf16_f32 v30, v37, v35
	v_cvt_pk_bf16_f32 v31, v39, v41
	v_cvt_pk_bf16_f32 v32, v43, v45
	v_cvt_pk_bf16_f32 v33, v47, v49
	ds_read2_b32 v[36:37], v22 offset0:81 offset1:89
	ds_read2_b32 v[38:39], v22 offset0:16 offset1:24
	ds_read2_b32 v[40:41], v22 offset0:146 offset1:154
	ds_read2_b32 v[42:43], v22 offset0:211 offset1:219
	ds_read2_b32 v[44:45], v54 offset0:20 offset1:28
	ds_read2_b32 v[46:47], v54 offset0:85 offset1:93
	ds_read2_b32 v[48:49], v54 offset0:150 offset1:158
	ds_read2_b32 v[52:53], v54 offset0:215 offset1:223
	v_lshl_add_u64 v[34:35], v[50:51], 0, v[0:1]
	v_or_b32_e32 v0, s0, v24
	v_lshlrev_b32_e32 v0, 12, v0
	global_store_dwordx4 v[34:35], v[30:33], off
	v_lshl_add_u64 v[34:35], v[50:51], 0, v[0:1]
	v_or_b32_e32 v0, s0, v25
	s_waitcnt lgkmcnt(6)
	v_cvt_pk_bf16_f32 v30, v38, v36
	s_waitcnt lgkmcnt(4)
	v_cvt_pk_bf16_f32 v31, v40, v42
	s_waitcnt lgkmcnt(2)
	v_cvt_pk_bf16_f32 v32, v44, v46
	s_waitcnt lgkmcnt(0)
	v_cvt_pk_bf16_f32 v33, v48, v52
	global_store_dwordx4 v[34:35], v[30:33], off
	v_lshlrev_b32_e32 v0, 12, v0
	v_lshl_add_u64 v[34:35], v[50:51], 0, v[0:1]
	v_cvt_pk_bf16_f32 v30, v39, v37
	v_cvt_pk_bf16_f32 v31, v41, v43
	v_cvt_pk_bf16_f32 v32, v45, v47
	v_cvt_pk_bf16_f32 v33, v49, v53
	ds_read2_b32 v[36:37], v22 offset0:32 offset1:40
	ds_read2_b32 v[38:39], v22 offset0:97 offset1:105
	ds_read2_b32 v[40:41], v22 offset0:162 offset1:170
	ds_read2_b32 v[42:43], v22 offset0:227 offset1:235
	ds_read2_b32 v[44:45], v54 offset0:36 offset1:44
	ds_read2_b32 v[46:47], v54 offset0:101 offset1:109
	ds_read2_b32 v[48:49], v54 offset0:166 offset1:174
	ds_read2_b32 v[52:53], v54 offset0:231 offset1:239
	v_or_b32_e32 v0, s0, v26
	v_lshlrev_b32_e32 v0, 12, v0
	global_store_dwordx4 v[34:35], v[30:33], off
	v_lshl_add_u64 v[34:35], v[50:51], 0, v[0:1]
	v_or_b32_e32 v0, s0, v27
	s_waitcnt lgkmcnt(6)
	v_cvt_pk_bf16_f32 v30, v36, v38
	s_waitcnt lgkmcnt(4)
	v_cvt_pk_bf16_f32 v31, v40, v42
	s_waitcnt lgkmcnt(2)
	v_cvt_pk_bf16_f32 v32, v44, v46
	s_waitcnt lgkmcnt(0)
	v_cvt_pk_bf16_f32 v33, v48, v52
	global_store_dwordx4 v[34:35], v[30:33], off
	v_lshlrev_b32_e32 v0, 12, v0
	v_lshl_add_u64 v[34:35], v[50:51], 0, v[0:1]
	v_cvt_pk_bf16_f32 v30, v37, v39
	v_cvt_pk_bf16_f32 v31, v41, v43
	v_cvt_pk_bf16_f32 v32, v45, v47
	v_cvt_pk_bf16_f32 v33, v49, v53
	ds_read2_b32 v[36:37], v22 offset0:48 offset1:56
	ds_read2_b32 v[38:39], v22 offset0:113 offset1:121
	ds_read2_b32 v[40:41], v22 offset0:178 offset1:186
	ds_read2_b32 v[42:43], v22 offset0:243 offset1:251
	ds_read2_b32 v[44:45], v54 offset0:52 offset1:60
	ds_read2_b32 v[46:47], v54 offset0:117 offset1:125
	ds_read2_b32 v[48:49], v54 offset0:182 offset1:190
	ds_read2_b32 v[52:53], v54 offset0:247 offset1:255
	v_or_b32_e32 v0, s0, v28
	v_lshlrev_b32_e32 v0, 12, v0
	global_store_dwordx4 v[34:35], v[30:33], off
	v_lshl_add_u64 v[34:35], v[50:51], 0, v[0:1]
	v_or_b32_e32 v0, s0, v29
	s_waitcnt lgkmcnt(6)
	v_cvt_pk_bf16_f32 v30, v36, v38
	s_waitcnt lgkmcnt(4)
	v_cvt_pk_bf16_f32 v31, v40, v42
	s_waitcnt lgkmcnt(2)
	v_cvt_pk_bf16_f32 v32, v44, v46
	s_waitcnt lgkmcnt(0)
	v_cvt_pk_bf16_f32 v33, v48, v52
	v_lshlrev_b32_e32 v0, 12, v0
	global_store_dwordx4 v[34:35], v[30:33], off
	v_lshl_add_u64 v[34:35], v[50:51], 0, v[0:1]
	s_nop 0
	v_cvt_pk_bf16_f32 v30, v37, v39
	v_cvt_pk_bf16_f32 v31, v41, v43
	v_cvt_pk_bf16_f32 v32, v45, v47
	v_cvt_pk_bf16_f32 v33, v49, v53
	global_store_dwordx4 v[34:35], v[30:33], off
	s_waitcnt lgkmcnt(0)

.LBB0_574:
	s_andn2_b64 vcc, exec, s[0:1]
	s_cbranch_vccnz .LBB0_547
	s_ashr_i32 s0, s3, 31
	s_lshr_b32 s0, s0, 25
	s_add_i32 s0, s3, s0
	s_ashr_i32 s0, s0, 7
	s_lshl_b32 s4, s0, 6
	v_or_b32_e32 v30, s4, v3
	s_lshl_b32 s0, s0, 13
	v_ashrrev_i32_e32 v31, 31, v30
	v_readlane_b32 s68, v246, 43
	s_sub_i32 s0, s7, s0
	v_lshlrev_b64 v[30:31], 15, v[30:31]
	v_readlane_b32 s69, v246, 44
	s_ashr_i32 s1, s0, 31
	v_lshlrev_b32_e32 v0, 2, v2
	v_lshl_add_u64 v[30:31], s[68:69], 0, v[30:31]
	v_lshl_add_u64 v[30:31], s[0:1], 2, v[30:31]
	v_lshl_add_u64 v[90:91], v[30:31], 0, v[0:1]
	v_add_co_u32_e32 v34, vcc, s65, v90
	s_mov_b32 s1, 0xa0000
	s_nop 0
	v_addc_co_u32_e32 v35, vcc, 0, v91, vcc
	v_add_co_u32_e32 v38, vcc, s57, v90
	global_load_dwordx4 v[30:33], v[90:91], off nt
	s_nop 0
	global_load_dwordx4 v[34:37], v[34:35], off nt
	v_addc_co_u32_e32 v39, vcc, 0, v91, vcc
	v_add_co_u32_e32 v42, vcc, s23, v90
	v_add_u32_e32 v0, 0x410, v20
	s_nop 0
	v_addc_co_u32_e32 v43, vcc, 0, v91, vcc
	global_load_dwordx4 v[38:41], v[38:39], off nt
	s_nop 0
	global_load_dwordx4 v[42:45], v[42:43], off nt
	v_add_co_u32_e32 v46, vcc, s22, v90
	s_ashr_i32 s5, s4, 31
	s_nop 0
	v_addc_co_u32_e32 v47, vcc, 0, v91, vcc
	v_add_co_u32_e32 v50, vcc, s1, v90
	s_mov_b32 s1, 0xe0000
	s_nop 0
	v_addc_co_u32_e32 v51, vcc, 0, v91, vcc
	global_load_dwordx4 v[46:49], v[46:47], off nt
	s_nop 0
	global_load_dwordx4 v[50:53], v[50:51], off nt
	v_add_co_u32_e32 v54, vcc, s84, v90
	v_readlane_b32 s74, v246, 49
	s_nop 0
	v_addc_co_u32_e32 v55, vcc, 0, v91, vcc
	v_add_co_u32_e32 v58, vcc, s1, v90
	s_mov_b32 s1, 0x100000
	s_nop 0
	v_addc_co_u32_e32 v59, vcc, 0, v91, vcc
	global_load_dwordx4 v[54:57], v[54:55], off nt
	s_nop 0
	global_load_dwordx4 v[58:61], v[58:59], off nt
	v_add_co_u32_e32 v62, vcc, s1, v90
	s_mov_b32 s1, 0x140000
	s_nop 0
	v_addc_co_u32_e32 v63, vcc, 0, v91, vcc
	v_add_co_u32_e32 v66, vcc, s27, v90
	v_readlane_b32 s75, v246, 50
	s_nop 0
	v_addc_co_u32_e32 v67, vcc, 0, v91, vcc
	global_load_dwordx4 v[62:65], v[62:63], off nt
	s_nop 0
	global_load_dwordx4 v[66:69], v[66:67], off nt
	v_add_co_u32_e32 v70, vcc, s1, v90
	s_mov_b32 s1, 0x180000
	s_nop 0
	v_addc_co_u32_e32 v71, vcc, 0, v91, vcc
	v_add_co_u32_e32 v74, vcc, s30, v90
	v_readlane_b32 s72, v246, 47
	s_nop 0
	v_addc_co_u32_e32 v75, vcc, 0, v91, vcc
	global_load_dwordx4 v[70:73], v[70:71], off nt
	s_nop 0
	global_load_dwordx4 v[74:77], v[74:75], off nt
	v_add_co_u32_e32 v78, vcc, s1, v90
	v_readlane_b32 s74, v245, 58
	s_nop 0
	v_addc_co_u32_e32 v79, vcc, 0, v91, vcc
	global_load_dwordx4 v[78:81], v[78:79], off nt
	v_add_co_u32_e32 v82, vcc, s31, v90
	s_mov_b64 s[90:91], s[12:13]
	s_nop 0
	v_addc_co_u32_e32 v83, vcc, 0, v91, vcc
	global_load_dwordx4 v[82:85], v[82:83], off nt
	v_add_co_u32_e32 v86, vcc, s35, v90
	v_readlane_b32 s75, v245, 59
	s_nop 0
	v_addc_co_u32_e32 v87, vcc, 0, v91, vcc
	global_load_dwordx4 v[86:89], v[86:87], off nt
	v_add_co_u32_e32 v90, vcc, s93, v90
	v_readlane_b32 s72, v245, 15
	s_nop 0
	v_addc_co_u32_e32 v91, vcc, 0, v91, vcc
	global_load_dwordx4 v[90:93], v[90:91], off nt
	s_waitcnt vmcnt(0)
	ds_write2_b32 v20, v30, v31 offset1:1
	ds_write2_b32 v20, v32, v33 offset0:2 offset1:3
	ds_write2_b32 v0, v34, v35 offset1:1
	v_add_u32_e32 v0, 0x418, v20
	ds_write2_b32 v0, v36, v37 offset1:1
	v_add_u32_e32 v0, 0x820, v20
	v_readlane_b32 s70, v246, 45
	v_readlane_b32 s71, v246, 46
	v_readlane_b32 s73, v246, 48
	ds_write2_b32 v0, v38, v39 offset1:1
	v_add_u32_e32 v0, 0x828, v20
	ds_write2_b32 v0, v40, v41 offset1:1
	v_add_u32_e32 v0, 0xc30, v20
	ds_write2_b32 v0, v42, v43 offset1:1
	v_add_u32_e32 v0, 0xc38, v20
	ds_write2_b32 v0, v44, v45 offset1:1
	v_add_u32_e32 v0, 0x1040, v20
	v_readlane_b32 s76, v246, 51
	v_readlane_b32 s77, v246, 52
	v_readlane_b32 s78, v246, 53
	ds_write2_b32 v0, v46, v47 offset1:1
	v_add_u32_e32 v0, 0x1048, v20
	ds_write2_b32 v0, v48, v49 offset1:1
	v_add_u32_e32 v0, 0x1450, v20
	ds_write2_b32 v0, v50, v51 offset1:1
	v_add_u32_e32 v0, 0x1458, v20
	ds_write2_b32 v0, v52, v53 offset1:1
	v_add_u32_e32 v0, 0x1860, v20
	v_add_u32_e32 v52, s0, v21
	v_ashrrev_i32_e32 v53, 31, v52
	v_lshl_add_u64 v[50:51], s[4:5], 1, v[18:19]
	ds_write2_b32 v0, v54, v55 offset1:1
	v_add_u32_e32 v0, 0x1868, v20
	ds_write2_b32 v0, v56, v57 offset1:1
	v_add_u32_e32 v0, 0x1c70, v20
	ds_write2_b32 v0, v58, v59 offset1:1
	v_add_u32_e32 v0, 0x1c78, v20
	ds_write2_b32 v0, v60, v61 offset1:1
	v_add_u32_e32 v0, 0x2080, v20
	v_lshlrev_b64 v[54:55], 12, v[52:53]
	v_lshl_add_u64 v[54:55], v[50:51], 0, v[54:55]
	v_readlane_b32 s79, v246, 54
	ds_write2_b32 v0, v62, v63 offset1:1
	v_add_u32_e32 v0, 0x2088, v20
	ds_write2_b32 v0, v64, v65 offset1:1
	v_add_u32_e32 v0, 0x2490, v20
	ds_write2_b32 v0, v66, v67 offset1:1
	v_add_u32_e32 v0, 0x2498, v20
	ds_write2_b32 v0, v68, v69 offset1:1
	v_add_u32_e32 v0, 0x28a0, v20
	v_readlane_b32 s80, v246, 55
	v_readlane_b32 s81, v246, 56
	v_readlane_b32 s82, v246, 57
	ds_write2_b32 v0, v70, v71 offset1:1
	v_add_u32_e32 v0, 0x28a8, v20
	ds_write2_b32 v0, v72, v73 offset1:1
	v_add_u32_e32 v0, 0x2cb0, v20
	ds_write2_b32 v0, v74, v75 offset1:1
	v_add_u32_e32 v0, 0x2cb8, v20
	ds_write2_b32 v0, v76, v77 offset1:1
	v_add_u32_e32 v0, 0x30c0, v20
	ds_write2_b32 v0, v78, v79 offset1:1
	v_add_u32_e32 v0, 0x30c8, v20
	ds_write2_b32 v0, v80, v81 offset1:1
	v_add_u32_e32 v0, 0x34d0, v20
	v_readlane_b32 s83, v246, 58
	ds_write2_b32 v0, v82, v83 offset1:1
	v_add_u32_e32 v0, 0x34d8, v20
	ds_write2_b32 v0, v84, v85 offset1:1
	v_add_u32_e32 v0, 0x38e0, v20
	ds_write2_b32 v0, v86, v87 offset1:1
	v_add_u32_e32 v0, 0x38e8, v20
	ds_write2_b32 v0, v88, v89 offset1:1
	v_add_u32_e32 v0, 0x3cf0, v20
	ds_write2_b32 v0, v90, v91 offset1:1
	v_add_u32_e32 v0, 0x3cf8, v20
	ds_write2_b32 v0, v92, v93 offset1:1
	s_waitcnt lgkmcnt(0)
	v_add_u32_e32 v0, 0x400, v22
	ds_read2_b32 v[34:35], v22 offset0:65 offset1:73
	ds_read2_b32 v[36:37], v22 offset1:8
	ds_read2_b32 v[38:39], v22 offset0:130 offset1:138
	ds_read2_b32 v[40:41], v22 offset0:195 offset1:203
	ds_read2_b32 v[42:43], v0 offset0:4 offset1:12
	ds_read2_b32 v[44:45], v0 offset0:69 offset1:77
	ds_read2_b32 v[46:47], v0 offset0:134 offset1:142
	ds_read2_b32 v[48:49], v0 offset0:199 offset1:207
	s_waitcnt lgkmcnt(6)
	v_cvt_pk_bf16_f32 v30, v36, v34
	s_waitcnt lgkmcnt(2)
	v_cvt_pk_bf16_f32 v32, v42, v44
	v_cvt_pk_bf16_f32 v31, v38, v40
	s_waitcnt lgkmcnt(0)
	v_cvt_pk_bf16_f32 v33, v46, v48
	v_add_u32_e32 v34, 8, v52
	global_store_dwordx4 v[54:55], v[30:33], off
	s_nop 1
	v_cvt_pk_bf16_f32 v30, v37, v35
	v_ashrrev_i32_e32 v35, 31, v34
	v_cvt_pk_bf16_f32 v31, v39, v41
	v_cvt_pk_bf16_f32 v32, v43, v45
	v_cvt_pk_bf16_f32 v33, v47, v49
	v_lshlrev_b64 v[34:35], 12, v[34:35]
	ds_read2_b32 v[36:37], v22 offset0:81 offset1:89
	ds_read2_b32 v[38:39], v22 offset0:16 offset1:24
	ds_read2_b32 v[40:41], v22 offset0:146 offset1:154
	ds_read2_b32 v[42:43], v22 offset0:211 offset1:219
	ds_read2_b32 v[44:45], v0 offset0:20 offset1:28
	ds_read2_b32 v[46:47], v0 offset0:85 offset1:93
	ds_read2_b32 v[48:49], v0 offset0:150 offset1:158
	ds_read2_b32 v[54:55], v0 offset0:215 offset1:223
	v_lshl_add_u64 v[34:35], v[50:51], 0, v[34:35]
	global_store_dwordx4 v[34:35], v[30:33], off
	v_add_u32_e32 v34, 16, v52
	v_ashrrev_i32_e32 v35, 31, v34
	v_lshlrev_b64 v[34:35], 12, v[34:35]
	s_waitcnt lgkmcnt(6)
	v_cvt_pk_bf16_f32 v30, v38, v36
	s_waitcnt lgkmcnt(4)
	v_cvt_pk_bf16_f32 v31, v40, v42
	s_waitcnt lgkmcnt(2)
	v_cvt_pk_bf16_f32 v32, v44, v46
	s_waitcnt lgkmcnt(0)
	v_cvt_pk_bf16_f32 v33, v48, v54
	v_lshl_add_u64 v[34:35], v[50:51], 0, v[34:35]
	global_store_dwordx4 v[34:35], v[30:33], off
	v_add_u32_e32 v34, 24, v52
	v_ashrrev_i32_e32 v35, 31, v34
	v_cvt_pk_bf16_f32 v30, v39, v37
	v_cvt_pk_bf16_f32 v31, v41, v43
	v_cvt_pk_bf16_f32 v32, v45, v47
	v_cvt_pk_bf16_f32 v33, v49, v55
	v_lshlrev_b64 v[34:35], 12, v[34:35]
	ds_read2_b32 v[36:37], v22 offset0:32 offset1:40
	ds_read2_b32 v[38:39], v22 offset0:97 offset1:105
	ds_read2_b32 v[40:41], v22 offset0:162 offset1:170
	ds_read2_b32 v[42:43], v22 offset0:227 offset1:235
	ds_read2_b32 v[44:45], v0 offset0:36 offset1:44
	ds_read2_b32 v[46:47], v0 offset0:101 offset1:109
	ds_read2_b32 v[48:49], v0 offset0:166 offset1:174
	ds_read2_b32 v[54:55], v0 offset0:231 offset1:239
	v_lshl_add_u64 v[34:35], v[50:51], 0, v[34:35]
	global_store_dwordx4 v[34:35], v[30:33], off
	v_add_u32_e32 v34, 32, v52
	v_ashrrev_i32_e32 v35, 31, v34
	v_lshlrev_b64 v[34:35], 12, v[34:35]
	s_waitcnt lgkmcnt(6)
	v_cvt_pk_bf16_f32 v30, v36, v38
	s_waitcnt lgkmcnt(4)
	v_cvt_pk_bf16_f32 v31, v40, v42
	s_waitcnt lgkmcnt(2)
	v_cvt_pk_bf16_f32 v32, v44, v46
	s_waitcnt lgkmcnt(0)
	v_cvt_pk_bf16_f32 v33, v48, v54
	v_lshl_add_u64 v[34:35], v[50:51], 0, v[34:35]
	global_store_dwordx4 v[34:35], v[30:33], off
	v_add_u32_e32 v34, 40, v52
	v_ashrrev_i32_e32 v35, 31, v34
	v_cvt_pk_bf16_f32 v30, v37, v39
	v_cvt_pk_bf16_f32 v31, v41, v43
	v_cvt_pk_bf16_f32 v32, v45, v47
	v_cvt_pk_bf16_f32 v33, v49, v55
	v_lshlrev_b64 v[34:35], 12, v[34:35]
	ds_read2_b32 v[36:37], v22 offset0:48 offset1:56
	ds_read2_b32 v[38:39], v22 offset0:113 offset1:121
	ds_read2_b32 v[40:41], v22 offset0:178 offset1:186
	ds_read2_b32 v[42:43], v22 offset0:243 offset1:251
	ds_read2_b32 v[44:45], v0 offset0:52 offset1:60
	ds_read2_b32 v[46:47], v0 offset0:117 offset1:125
	ds_read2_b32 v[48:49], v0 offset0:182 offset1:190
	ds_read2_b32 v[54:55], v0 offset0:247 offset1:255
	v_lshl_add_u64 v[34:35], v[50:51], 0, v[34:35]
	global_store_dwordx4 v[34:35], v[30:33], off
	v_add_u32_e32 v34, 48, v52
	v_ashrrev_i32_e32 v35, 31, v34
	v_lshlrev_b64 v[34:35], 12, v[34:35]
	s_waitcnt lgkmcnt(6)
	v_cvt_pk_bf16_f32 v30, v36, v38
	s_waitcnt lgkmcnt(4)
	v_cvt_pk_bf16_f32 v31, v40, v42
	s_waitcnt lgkmcnt(2)
	v_cvt_pk_bf16_f32 v32, v44, v46
	s_waitcnt lgkmcnt(0)
	v_cvt_pk_bf16_f32 v33, v48, v54
	v_lshl_add_u64 v[34:35], v[50:51], 0, v[34:35]
	global_store_dwordx4 v[34:35], v[30:33], off
	v_add_u32_e32 v34, 56, v52
	v_ashrrev_i32_e32 v35, 31, v34
	v_lshlrev_b64 v[34:35], 12, v[34:35]
	v_cvt_pk_bf16_f32 v30, v37, v39
	v_cvt_pk_bf16_f32 v31, v41, v43
	v_cvt_pk_bf16_f32 v32, v45, v47
	v_cvt_pk_bf16_f32 v33, v49, v55
	v_lshl_add_u64 v[34:35], v[50:51], 0, v[34:35]
	global_store_dwordx4 v[34:35], v[30:33], off
	s_waitcnt lgkmcnt(0)
	s_branch .LBB0_547

.LBB0_581:
	s_cmpk_gt_i32 s9, 0xfff
	s_mov_b64 s[0:1], -1
	s_cbranch_scc0 .LBB0_599
	s_cmpk_gt_u32 s9, 0x13ff
	s_cbranch_scc0 .LBB0_596
	s_cmpk_gt_u32 s9, 0x1fff
	s_cbranch_scc0 .LBB0_593
	s_cmpk_gt_u32 s9, 0x23ff
	s_cbranch_scc0 .LBB0_590
	s_cmpk_gt_u32 s9, 0x39ff
	s_cbranch_scc0 .LBB0_587
	s_and_b32 s1, s5, 0x1ffc0
	v_or_b32_e32 v0, s1, v3
	v_readlane_b32 s12, v247, 59
	s_and_b32 s0, s2, 0x7c0
	v_lshlrev_b32_e32 v0, 13, v0
	v_readlane_b32 s13, v247, 60
	s_lshl_b32 s88, s0, 2
	s_mov_b32 s6, 0x18000
	v_lshl_add_u64 v[26:27], s[12:13], 0, v[0:1]
	v_lshl_add_u64 v[26:27], v[26:27], 0, s[88:89]
	v_lshlrev_b32_e32 v0, 2, v2
	v_lshl_add_u64 v[88:89], v[26:27], 0, v[0:1]
	v_add_co_u32_e32 v30, vcc, 0x8000, v88
	v_add_u32_e32 v0, 0x410, v16
	s_nop 0
	v_addc_co_u32_e32 v31, vcc, 0, v89, vcc
	v_add_co_u32_e32 v34, vcc, s67, v88
	global_load_dwordx4 v[26:29], v[88:89], off nt
	s_nop 0
	global_load_dwordx4 v[30:33], v[30:31], off nt
	v_addc_co_u32_e32 v35, vcc, 0, v89, vcc
	v_add_co_u32_e32 v38, vcc, s6, v88
	s_mov_b32 s6, 0x28000
	s_nop 0
	v_addc_co_u32_e32 v39, vcc, 0, v89, vcc
	global_load_dwordx4 v[34:37], v[34:35], off nt
	s_nop 0
	global_load_dwordx4 v[38:41], v[38:39], off nt
	v_add_co_u32_e32 v42, vcc, s50, v88
	s_lshl_b32 s88, s1, 1
	s_nop 0
	v_addc_co_u32_e32 v43, vcc, 0, v89, vcc
	v_add_co_u32_e32 v46, vcc, s6, v88
	s_mov_b32 s6, 0x30000
	s_nop 0
	v_addc_co_u32_e32 v47, vcc, 0, v89, vcc
	global_load_dwordx4 v[42:45], v[42:43], off nt
	s_nop 0
	global_load_dwordx4 v[46:49], v[46:47], off nt
	v_add_co_u32_e32 v50, vcc, s6, v88
	s_mov_b32 s6, 0x38000
	s_nop 0
	v_addc_co_u32_e32 v51, vcc, 0, v89, vcc
	v_add_co_u32_e32 v54, vcc, s6, v88
	s_mov_b32 s6, 0x48000
	s_nop 0
	v_addc_co_u32_e32 v55, vcc, 0, v89, vcc
	global_load_dwordx4 v[50:53], v[50:51], off nt
	s_nop 0
	global_load_dwordx4 v[54:57], v[54:55], off nt
	v_add_co_u32_e32 v58, vcc, s93, v88
	v_readlane_b32 s14, v247, 61
	s_nop 0
	v_addc_co_u32_e32 v59, vcc, 0, v89, vcc
	v_add_co_u32_e32 v62, vcc, s6, v88
	s_mov_b32 s6, 0x50000
	s_nop 0
	v_addc_co_u32_e32 v63, vcc, 0, v89, vcc
	global_load_dwordx4 v[58:61], v[58:59], off nt
	s_nop 0
	global_load_dwordx4 v[62:65], v[62:63], off nt
	v_add_co_u32_e32 v68, vcc, s6, v88
	s_mov_b32 s6, 0x58000
	s_nop 0
	v_addc_co_u32_e32 v69, vcc, 0, v89, vcc
	v_add_co_u32_e32 v72, vcc, s6, v88
	s_mov_b32 s6, 0x68000
	s_nop 0
	v_addc_co_u32_e32 v73, vcc, 0, v89, vcc
	global_load_dwordx4 v[68:71], v[68:69], off nt
	s_nop 0
	global_load_dwordx4 v[72:75], v[72:73], off nt
	v_add_co_u32_e32 v76, vcc, s44, v88
	v_readlane_b32 s15, v247, 62
	s_nop 0
	v_addc_co_u32_e32 v77, vcc, 0, v89, vcc
	v_add_co_u32_e32 v80, vcc, s6, v88
	s_mov_b32 s6, 0x70000
	s_nop 0
	v_addc_co_u32_e32 v81, vcc, 0, v89, vcc
	global_load_dwordx4 v[76:79], v[76:77], off nt
	s_nop 0
	global_load_dwordx4 v[80:83], v[80:81], off nt
	v_add_co_u32_e32 v84, vcc, s6, v88
	s_mov_b32 s6, 0x78000
	s_nop 0
	v_addc_co_u32_e32 v85, vcc, 0, v89, vcc
	global_load_dwordx4 v[84:87], v[84:85], off nt
	v_add_co_u32_e32 v88, vcc, s6, v88
	v_readlane_b32 s16, v247, 63
	s_nop 0
	v_addc_co_u32_e32 v89, vcc, 0, v89, vcc
	global_load_dwordx4 v[88:91], v[88:89], off nt
	s_waitcnt vmcnt(15)
	ds_write2_b32 v16, v26, v27 offset1:1
	ds_write2_b32 v16, v28, v29 offset0:2 offset1:3
	s_waitcnt vmcnt(14)
	ds_write2_b32 v0, v30, v31 offset1:1
	v_add_u32_e32 v0, 0x418, v16
	ds_write2_b32 v0, v32, v33 offset1:1
	v_add_u32_e32 v0, 0x820, v16
	v_readlane_b32 s17, v246, 0
	v_readlane_b32 s18, v246, 1
	v_readlane_b32 s19, v246, 2
	s_waitcnt vmcnt(13)
	ds_write2_b32 v0, v34, v35 offset1:1
	v_add_u32_e32 v0, 0x828, v16
	ds_write2_b32 v0, v36, v37 offset1:1
	v_add_u32_e32 v0, 0xc30, v16
	s_waitcnt vmcnt(12)
	ds_write2_b32 v0, v38, v39 offset1:1
	v_add_u32_e32 v0, 0xc38, v16
	ds_write2_b32 v0, v40, v41 offset1:1
	v_add_u32_e32 v0, 0x1040, v16
	s_waitcnt vmcnt(11)
	ds_write2_b32 v0, v42, v43 offset1:1
	v_add_u32_e32 v0, 0x1048, v16
	ds_write2_b32 v0, v44, v45 offset1:1
	v_add_u32_e32 v0, 0x1450, v16
	s_waitcnt vmcnt(10)
	ds_write2_b32 v0, v46, v47 offset1:1
	v_add_u32_e32 v0, 0x1458, v16
	ds_write2_b32 v0, v48, v49 offset1:1
	v_add_u32_e32 v0, 0x1860, v16
	v_lshl_add_u64 v[46:47], v[4:5], 0, s[88:89]
	s_waitcnt vmcnt(9)
	ds_write2_b32 v0, v50, v51 offset1:1
	v_add_u32_e32 v0, 0x1868, v16
	ds_write2_b32 v0, v52, v53 offset1:1
	v_add_u32_e32 v0, 0x1c70, v16
	s_waitcnt vmcnt(8)
	ds_write2_b32 v0, v54, v55 offset1:1
	v_add_u32_e32 v0, 0x1c78, v16
	ds_write2_b32 v0, v56, v57 offset1:1
	v_add_u32_e32 v0, 0x2080, v16
	v_add_u32_e32 v50, 0x400, v18
	s_waitcnt vmcnt(7)
	ds_write2_b32 v0, v58, v59 offset1:1
	v_add_u32_e32 v0, 0x2088, v16
	ds_write2_b32 v0, v60, v61 offset1:1
	v_add_u32_e32 v0, 0x2490, v16
	s_waitcnt vmcnt(6)
	ds_write2_b32 v0, v62, v63 offset1:1
	v_add_u32_e32 v0, 0x2498, v16
	ds_write2_b32 v0, v64, v65 offset1:1
	v_add_u32_e32 v0, 0x28a0, v16
	s_waitcnt vmcnt(5)
	ds_write2_b32 v0, v68, v69 offset1:1
	v_add_u32_e32 v0, 0x28a8, v16
	ds_write2_b32 v0, v70, v71 offset1:1
	v_add_u32_e32 v0, 0x2cb0, v16
	s_waitcnt vmcnt(4)
	ds_write2_b32 v0, v72, v73 offset1:1
	v_add_u32_e32 v0, 0x2cb8, v16
	ds_write2_b32 v0, v74, v75 offset1:1
	v_add_u32_e32 v0, 0x30c0, v16
	s_waitcnt vmcnt(3)
	ds_write2_b32 v0, v76, v77 offset1:1
	v_add_u32_e32 v0, 0x30c8, v16
	ds_write2_b32 v0, v78, v79 offset1:1
	v_add_u32_e32 v0, 0x34d0, v16
	s_waitcnt vmcnt(2)
	ds_write2_b32 v0, v80, v81 offset1:1
	v_add_u32_e32 v0, 0x34d8, v16
	ds_write2_b32 v0, v82, v83 offset1:1
	v_add_u32_e32 v0, 0x38e0, v16
	s_waitcnt vmcnt(1)
	ds_write2_b32 v0, v84, v85 offset1:1
	v_add_u32_e32 v0, 0x38e8, v16
	ds_write2_b32 v0, v86, v87 offset1:1
	v_add_u32_e32 v0, 0x3cf0, v16
	s_waitcnt vmcnt(0)
	ds_write2_b32 v0, v88, v89 offset1:1
	v_add_u32_e32 v0, 0x3cf8, v16
	ds_write2_b32 v0, v90, v91 offset1:1
	s_waitcnt lgkmcnt(0)
	ds_read2_b32 v[30:31], v18 offset0:65 offset1:73
	ds_read2_b32 v[32:33], v18 offset1:8
	ds_read2_b32 v[34:35], v18 offset0:130 offset1:138
	ds_read2_b32 v[36:37], v18 offset0:195 offset1:203
	ds_read2_b32 v[38:39], v50 offset0:4 offset1:12
	ds_read2_b32 v[40:41], v50 offset0:69 offset1:77
	ds_read2_b32 v[42:43], v50 offset0:134 offset1:142
	ds_read2_b32 v[44:45], v50 offset0:199 offset1:207
	v_or_b32_e32 v0, s0, v17
	v_mul_u32_u24_e32 v0, 0x2c00, v0
	s_waitcnt lgkmcnt(6)
	v_cvt_pk_bf16_f32 v26, v32, v30
	s_waitcnt lgkmcnt(4)
	v_cvt_pk_bf16_f32 v27, v34, v36
	s_waitcnt lgkmcnt(2)
	v_cvt_pk_bf16_f32 v28, v38, v40
	s_waitcnt lgkmcnt(0)
	v_cvt_pk_bf16_f32 v29, v42, v44
	v_lshl_add_u64 v[48:49], v[46:47], 0, v[0:1]
	global_store_dwordx4 v[48:49], v[26:29], off
	v_or_b32_e32 v0, s0, v19
	v_mul_u32_u24_e32 v0, 0x2c00, v0
	v_cvt_pk_bf16_f32 v26, v33, v31
	v_cvt_pk_bf16_f32 v27, v35, v37
	v_cvt_pk_bf16_f32 v28, v39, v41
	v_cvt_pk_bf16_f32 v29, v43, v45
	ds_read2_b32 v[32:33], v18 offset0:16 offset1:24
	ds_read2_b32 v[34:35], v18 offset0:81 offset1:89
	ds_read2_b32 v[36:37], v18 offset0:146 offset1:154
	ds_read2_b32 v[38:39], v18 offset0:211 offset1:219
	ds_read2_b32 v[40:41], v50 offset0:20 offset1:28
	ds_read2_b32 v[42:43], v50 offset0:85 offset1:93
	ds_read2_b32 v[44:45], v50 offset0:150 offset1:158
	ds_read2_b32 v[48:49], v50 offset0:215 offset1:223
	v_lshl_add_u64 v[30:31], v[46:47], 0, v[0:1]
	v_or_b32_e32 v0, s0, v20
	v_mul_u32_u24_e32 v0, 0x2c00, v0
	global_store_dwordx4 v[30:31], v[26:29], off
	v_lshl_add_u64 v[30:31], v[46:47], 0, v[0:1]
	v_or_b32_e32 v0, s0, v21
	s_waitcnt lgkmcnt(6)
	v_cvt_pk_bf16_f32 v26, v32, v34
	s_waitcnt lgkmcnt(4)
	v_cvt_pk_bf16_f32 v27, v36, v38
	s_waitcnt lgkmcnt(2)
	v_cvt_pk_bf16_f32 v28, v40, v42
	s_waitcnt lgkmcnt(0)
	v_cvt_pk_bf16_f32 v29, v44, v48
	global_store_dwordx4 v[30:31], v[26:29], off
	v_mul_u32_u24_e32 v0, 0x2c00, v0
	v_lshl_add_u64 v[30:31], v[46:47], 0, v[0:1]
	v_cvt_pk_bf16_f32 v26, v33, v35
	v_cvt_pk_bf16_f32 v27, v37, v39
	v_cvt_pk_bf16_f32 v28, v41, v43
	v_cvt_pk_bf16_f32 v29, v45, v49
	ds_read2_b32 v[32:33], v18 offset0:32 offset1:40
	ds_read2_b32 v[34:35], v18 offset0:97 offset1:105
	ds_read2_b32 v[36:37], v18 offset0:162 offset1:170
	ds_read2_b32 v[38:39], v18 offset0:227 offset1:235
	ds_read2_b32 v[40:41], v50 offset0:36 offset1:44
	ds_read2_b32 v[42:43], v50 offset0:101 offset1:109
	ds_read2_b32 v[44:45], v50 offset0:166 offset1:174
	ds_read2_b32 v[48:49], v50 offset0:231 offset1:239
	v_or_b32_e32 v0, s0, v22
	v_mul_u32_u24_e32 v0, 0x2c00, v0
	global_store_dwordx4 v[30:31], v[26:29], off
	v_lshl_add_u64 v[30:31], v[46:47], 0, v[0:1]
	v_or_b32_e32 v0, s0, v23
	s_waitcnt lgkmcnt(6)
	v_cvt_pk_bf16_f32 v26, v32, v34
	s_waitcnt lgkmcnt(4)
	v_cvt_pk_bf16_f32 v27, v36, v38
	s_waitcnt lgkmcnt(2)
	v_cvt_pk_bf16_f32 v28, v40, v42
	s_waitcnt lgkmcnt(0)
	v_cvt_pk_bf16_f32 v29, v44, v48
	global_store_dwordx4 v[30:31], v[26:29], off
	v_mul_u32_u24_e32 v0, 0x2c00, v0
	v_lshl_add_u64 v[30:31], v[46:47], 0, v[0:1]
	v_cvt_pk_bf16_f32 v26, v33, v35
	v_cvt_pk_bf16_f32 v27, v37, v39
	v_cvt_pk_bf16_f32 v28, v41, v43
	v_cvt_pk_bf16_f32 v29, v45, v49
	ds_read2_b32 v[32:33], v18 offset0:48 offset1:56
	ds_read2_b32 v[34:35], v18 offset0:113 offset1:121
	ds_read2_b32 v[36:37], v18 offset0:178 offset1:186
	ds_read2_b32 v[38:39], v18 offset0:243 offset1:251
	ds_read2_b32 v[40:41], v50 offset0:52 offset1:60
	ds_read2_b32 v[42:43], v50 offset0:117 offset1:125
	ds_read2_b32 v[44:45], v50 offset0:182 offset1:190
	ds_read2_b32 v[48:49], v50 offset0:247 offset1:255
	v_or_b32_e32 v0, s0, v24
	v_mul_u32_u24_e32 v0, 0x2c00, v0
	global_store_dwordx4 v[30:31], v[26:29], off
	v_lshl_add_u64 v[30:31], v[46:47], 0, v[0:1]
	v_or_b32_e32 v0, s0, v25
	s_waitcnt lgkmcnt(6)
	v_cvt_pk_bf16_f32 v26, v32, v34
	s_waitcnt lgkmcnt(4)
	v_cvt_pk_bf16_f32 v27, v36, v38
	s_waitcnt lgkmcnt(2)
	v_cvt_pk_bf16_f32 v28, v40, v42
	s_waitcnt lgkmcnt(0)
	v_cvt_pk_bf16_f32 v29, v44, v48
	v_mul_u32_u24_e32 v0, 0x2c00, v0
	global_store_dwordx4 v[30:31], v[26:29], off
	v_lshl_add_u64 v[30:31], v[46:47], 0, v[0:1]
	s_mov_b64 s[0:1], 0
	v_cvt_pk_bf16_f32 v26, v33, v35
	v_cvt_pk_bf16_f32 v27, v37, v39
	v_cvt_pk_bf16_f32 v28, v41, v43
	v_cvt_pk_bf16_f32 v29, v45, v49
	global_store_dwordx4 v[30:31], v[26:29], off
	s_waitcnt lgkmcnt(0)
.LBB0_587:
	s_andn2_b64 vcc, exec, s[0:1]
	s_cbranch_vccnz .LBB0_589
	s_add_i32 s0, s9, 0xdc00
	s_and_b32 s1, s0, 0xffff
	s_mul_i32 s1, s1, 0xba2f
	s_lshr_b32 s1, s1, 23
	s_mul_i32 s6, s1, 0xb0
	s_sub_i32 s0, s0, s6
	s_lshl_b32 s6, s0, 6
	v_lshl_or_b32 v0, s1, 6, v3
	v_readlane_b32 s12, v248, 0
	s_and_b32 s7, s6, 0xffc0
	v_mul_u32_u24_e32 v0, 0xb000, v0
	v_readlane_b32 s14, v248, 2
	v_readlane_b32 s15, v248, 3
	s_lshl_b32 s88, s7, 2
	s_mov_b32 s7, 0x2c000
	v_lshl_add_u64 v[26:27], s[14:15], 0, v[0:1]
	v_lshl_add_u64 v[26:27], v[26:27], 0, s[88:89]
	v_lshlrev_b32_e32 v0, 2, v2
	v_lshl_add_u64 v[88:89], v[26:27], 0, v[0:1]
	v_add_co_u32_e32 v30, vcc, s7, v88
	s_mov_b32 s7, 0x58000
	s_nop 0
	v_addc_co_u32_e32 v31, vcc, 0, v89, vcc
	v_add_co_u32_e32 v34, vcc, s7, v88
	global_load_dwordx4 v[26:29], v[88:89], off nt
	s_nop 0
	global_load_dwordx4 v[30:33], v[30:31], off nt
	v_addc_co_u32_e32 v35, vcc, 0, v89, vcc
	s_mov_b32 s7, 0x84000
	v_add_co_u32_e32 v38, vcc, s7, v88
	s_mov_b32 s7, 0xb0000
	s_nop 0
	v_addc_co_u32_e32 v39, vcc, 0, v89, vcc
	global_load_dwordx4 v[34:37], v[34:35], off nt
	s_nop 0
	global_load_dwordx4 v[38:41], v[38:39], off nt
	v_add_co_u32_e32 v42, vcc, s7, v88
	s_mov_b32 s7, 0xdc000
	s_nop 0
	v_addc_co_u32_e32 v43, vcc, 0, v89, vcc
	v_add_co_u32_e32 v46, vcc, s7, v88
	s_mov_b32 s7, 0x108000
	s_nop 0
	v_addc_co_u32_e32 v47, vcc, 0, v89, vcc
	global_load_dwordx4 v[42:45], v[42:43], off nt
	s_nop 0
	global_load_dwordx4 v[46:49], v[46:47], off nt
	v_add_co_u32_e32 v50, vcc, s7, v88
	s_mov_b32 s7, 0x134000
	s_nop 0
	v_addc_co_u32_e32 v51, vcc, 0, v89, vcc
	v_add_co_u32_e32 v54, vcc, s7, v88
	s_mov_b32 s7, 0x18c000
	s_nop 0
	v_addc_co_u32_e32 v55, vcc, 0, v89, vcc
	global_load_dwordx4 v[50:53], v[50:51], off nt
	s_nop 0
	global_load_dwordx4 v[54:57], v[54:55], off nt
	v_add_co_u32_e32 v58, vcc, s51, v88
	v_add_u32_e32 v0, 0x410, v16
	s_nop 0
	v_addc_co_u32_e32 v59, vcc, 0, v89, vcc
	v_add_co_u32_e32 v62, vcc, s7, v88
	s_mov_b32 s7, 0x1b8000
	s_nop 0
	v_addc_co_u32_e32 v63, vcc, 0, v89, vcc
	global_load_dwordx4 v[58:61], v[58:59], off nt
	s_nop 0
	global_load_dwordx4 v[62:65], v[62:63], off nt
	v_add_co_u32_e32 v68, vcc, s7, v88
	s_mov_b32 s7, 0x1e4000
	s_nop 0
	v_addc_co_u32_e32 v69, vcc, 0, v89, vcc
	v_add_co_u32_e32 v72, vcc, s7, v88
	s_mov_b32 s7, 0x210000
	s_nop 0
	v_addc_co_u32_e32 v73, vcc, 0, v89, vcc
	global_load_dwordx4 v[68:71], v[68:69], off nt
	s_nop 0
	global_load_dwordx4 v[72:75], v[72:73], off nt
	v_add_co_u32_e32 v76, vcc, s7, v88
	s_mov_b32 s7, 0x23c000
	s_nop 0
	v_addc_co_u32_e32 v77, vcc, 0, v89, vcc
	global_load_dwordx4 v[76:79], v[76:77], off nt
	v_add_co_u32_e32 v80, vcc, s7, v88
	s_mov_b32 s7, 0x268000
	s_nop 0
	v_addc_co_u32_e32 v81, vcc, 0, v89, vcc
	global_load_dwordx4 v[80:83], v[80:81], off nt
	v_add_co_u32_e32 v84, vcc, s7, v88
	s_mov_b32 s7, 0x294000
	s_nop 0
	v_addc_co_u32_e32 v85, vcc, 0, v89, vcc
	global_load_dwordx4 v[84:87], v[84:85], off nt
	v_add_co_u32_e32 v88, vcc, s7, v88
	s_lshl_b32 s88, s1, 7
	s_nop 0
	v_addc_co_u32_e32 v89, vcc, 0, v89, vcc
	global_load_dwordx4 v[88:91], v[88:89], off nt
	s_waitcnt vmcnt(15)
	ds_write2_b32 v16, v26, v27 offset1:1
	ds_write2_b32 v16, v28, v29 offset0:2 offset1:3
	s_waitcnt vmcnt(14)
	ds_write2_b32 v0, v30, v31 offset1:1
	v_add_u32_e32 v0, 0x418, v16
	ds_write2_b32 v0, v32, v33 offset1:1
	v_add_u32_e32 v0, 0x820, v16
	s_and_b32 s1, s0, 0xffff
	s_lshl_b32 s0, s0, 7
	s_and_b32 s0, s0, 0x7f00
	s_add_i32 s7, s0, 0xffffd480
	s_waitcnt vmcnt(13)
	ds_write2_b32 v0, v34, v35 offset1:1
	v_add_u32_e32 v0, 0x828, v16
	ds_write2_b32 v0, v36, v37 offset1:1
	v_add_u32_e32 v0, 0xc30, v16
	s_waitcnt vmcnt(12)
	ds_write2_b32 v0, v38, v39 offset1:1
	v_add_u32_e32 v0, 0xc38, v16
	ds_write2_b32 v0, v40, v41 offset1:1
	v_add_u32_e32 v0, 0x1040, v16
	s_cmpk_lt_u32 s1, 0x58
	s_cselect_b32 s0, s0, s7
	s_and_b32 s1, s6, 64
	s_waitcnt vmcnt(11)
	ds_write2_b32 v0, v42, v43 offset1:1
	v_add_u32_e32 v0, 0x1048, v16
	ds_write2_b32 v0, v44, v45 offset1:1
	v_add_u32_e32 v0, 0x1450, v16
	s_waitcnt vmcnt(10)
	ds_write2_b32 v0, v46, v47 offset1:1
	v_add_u32_e32 v0, 0x1458, v16
	ds_write2_b32 v0, v48, v49 offset1:1
	v_add_u32_e32 v0, 0x1860, v16
	s_or_b32 s0, s1, s0
	v_or_b32_e32 v48, s0, v17
	v_ashrrev_i32_e32 v49, 31, v48
	s_waitcnt vmcnt(9)
	ds_write2_b32 v0, v50, v51 offset1:1
	v_add_u32_e32 v0, 0x1868, v16
	ds_write2_b32 v0, v52, v53 offset1:1
	v_add_u32_e32 v0, 0x1c70, v16
	s_waitcnt vmcnt(8)
	ds_write2_b32 v0, v54, v55 offset1:1
	v_add_u32_e32 v0, 0x1c78, v16
	ds_write2_b32 v0, v56, v57 offset1:1
	v_add_u32_e32 v0, 0x2080, v16
	v_lshl_add_u64 v[46:47], v[6:7], 0, s[88:89]
	v_lshlrev_b64 v[48:49], 12, v[48:49]
	v_lshl_add_u64 v[48:49], v[46:47], 0, v[48:49]
	s_waitcnt vmcnt(7)
	ds_write2_b32 v0, v58, v59 offset1:1
	v_add_u32_e32 v0, 0x2088, v16
	ds_write2_b32 v0, v60, v61 offset1:1
	v_add_u32_e32 v0, 0x2490, v16
	s_waitcnt vmcnt(6)
	ds_write2_b32 v0, v62, v63 offset1:1
	v_add_u32_e32 v0, 0x2498, v16
	ds_write2_b32 v0, v64, v65 offset1:1
	v_add_u32_e32 v0, 0x28a0, v16
	v_readlane_b32 s13, v248, 1
	v_readlane_b32 s16, v248, 4
	v_readlane_b32 s17, v248, 5
	s_waitcnt vmcnt(5)
	ds_write2_b32 v0, v68, v69 offset1:1
	v_add_u32_e32 v0, 0x28a8, v16
	ds_write2_b32 v0, v70, v71 offset1:1
	v_add_u32_e32 v0, 0x2cb0, v16
	s_waitcnt vmcnt(4)
	ds_write2_b32 v0, v72, v73 offset1:1
	v_add_u32_e32 v0, 0x2cb8, v16
	ds_write2_b32 v0, v74, v75 offset1:1
	v_add_u32_e32 v0, 0x30c0, v16
	s_waitcnt vmcnt(3)
	ds_write2_b32 v0, v76, v77 offset1:1
	v_add_u32_e32 v0, 0x30c8, v16
	ds_write2_b32 v0, v78, v79 offset1:1
	v_add_u32_e32 v0, 0x34d0, v16
	v_readlane_b32 s18, v248, 6
	s_waitcnt vmcnt(2)
	ds_write2_b32 v0, v80, v81 offset1:1
	v_add_u32_e32 v0, 0x34d8, v16
	ds_write2_b32 v0, v82, v83 offset1:1
	v_add_u32_e32 v0, 0x38e0, v16
	v_readlane_b32 s19, v248, 7
	s_waitcnt vmcnt(1)
	ds_write2_b32 v0, v84, v85 offset1:1
	v_add_u32_e32 v0, 0x38e8, v16
	ds_write2_b32 v0, v86, v87 offset1:1
	v_add_u32_e32 v0, 0x3cf0, v16
	s_waitcnt vmcnt(0)
	ds_write2_b32 v0, v88, v89 offset1:1
	v_add_u32_e32 v0, 0x3cf8, v16
	ds_write2_b32 v0, v90, v91 offset1:1
	s_waitcnt lgkmcnt(0)
	v_add_u32_e32 v0, 0x400, v18
	ds_read2_b32 v[30:31], v18 offset0:65 offset1:73
	ds_read2_b32 v[32:33], v18 offset1:8
	ds_read2_b32 v[34:35], v18 offset0:130 offset1:138
	ds_read2_b32 v[36:37], v18 offset0:195 offset1:203
	ds_read2_b32 v[38:39], v0 offset0:4 offset1:12
	ds_read2_b32 v[40:41], v0 offset0:69 offset1:77
	ds_read2_b32 v[42:43], v0 offset0:134 offset1:142
	ds_read2_b32 v[44:45], v0 offset0:199 offset1:207
	s_waitcnt lgkmcnt(6)
	v_cvt_pk_bf16_f32 v26, v32, v30
	s_waitcnt lgkmcnt(2)
	v_cvt_pk_bf16_f32 v28, v38, v40
	v_cvt_pk_bf16_f32 v27, v34, v36
	s_waitcnt lgkmcnt(0)
	v_cvt_pk_bf16_f32 v29, v42, v44
	v_or_b32_e32 v30, s0, v19
	global_store_dwordx4 v[48:49], v[26:29], off
	s_nop 1
	v_cvt_pk_bf16_f32 v26, v33, v31
	v_ashrrev_i32_e32 v31, 31, v30
	v_cvt_pk_bf16_f32 v27, v35, v37
	v_cvt_pk_bf16_f32 v28, v39, v41
	v_cvt_pk_bf16_f32 v29, v43, v45
	v_lshlrev_b64 v[30:31], 12, v[30:31]
	ds_read2_b32 v[32:33], v18 offset0:81 offset1:89
	ds_read2_b32 v[34:35], v18 offset0:16 offset1:24
	ds_read2_b32 v[36:37], v18 offset0:146 offset1:154
	ds_read2_b32 v[38:39], v18 offset0:211 offset1:219
	ds_read2_b32 v[40:41], v0 offset0:20 offset1:28
	ds_read2_b32 v[42:43], v0 offset0:85 offset1:93
	ds_read2_b32 v[44:45], v0 offset0:150 offset1:158
	ds_read2_b32 v[48:49], v0 offset0:215 offset1:223
	v_lshl_add_u64 v[30:31], v[46:47], 0, v[30:31]
	global_store_dwordx4 v[30:31], v[26:29], off
	v_or_b32_e32 v30, s0, v20
	v_ashrrev_i32_e32 v31, 31, v30
	v_lshlrev_b64 v[30:31], 12, v[30:31]
	s_waitcnt lgkmcnt(6)
	v_cvt_pk_bf16_f32 v26, v34, v32
	s_waitcnt lgkmcnt(4)
	v_cvt_pk_bf16_f32 v27, v36, v38
	s_waitcnt lgkmcnt(2)
	v_cvt_pk_bf16_f32 v28, v40, v42
	s_waitcnt lgkmcnt(0)
	v_cvt_pk_bf16_f32 v29, v44, v48
	v_lshl_add_u64 v[30:31], v[46:47], 0, v[30:31]
	global_store_dwordx4 v[30:31], v[26:29], off
	v_or_b32_e32 v30, s0, v21
	v_ashrrev_i32_e32 v31, 31, v30
	v_cvt_pk_bf16_f32 v26, v35, v33
	v_cvt_pk_bf16_f32 v27, v37, v39
	v_cvt_pk_bf16_f32 v28, v41, v43
	v_cvt_pk_bf16_f32 v29, v45, v49
	v_lshlrev_b64 v[30:31], 12, v[30:31]
	ds_read2_b32 v[32:33], v18 offset0:32 offset1:40
	ds_read2_b32 v[34:35], v18 offset0:97 offset1:105
	ds_read2_b32 v[36:37], v18 offset0:162 offset1:170
	ds_read2_b32 v[38:39], v18 offset0:227 offset1:235
	ds_read2_b32 v[40:41], v0 offset0:36 offset1:44
	ds_read2_b32 v[42:43], v0 offset0:101 offset1:109
	ds_read2_b32 v[44:45], v0 offset0:166 offset1:174
	ds_read2_b32 v[48:49], v0 offset0:231 offset1:239
	v_lshl_add_u64 v[30:31], v[46:47], 0, v[30:31]
	global_store_dwordx4 v[30:31], v[26:29], off
	v_or_b32_e32 v30, s0, v22
	v_ashrrev_i32_e32 v31, 31, v30
	v_lshlrev_b64 v[30:31], 12, v[30:31]
	s_waitcnt lgkmcnt(6)
	v_cvt_pk_bf16_f32 v26, v32, v34
	s_waitcnt lgkmcnt(4)
	v_cvt_pk_bf16_f32 v27, v36, v38
	s_waitcnt lgkmcnt(2)
	v_cvt_pk_bf16_f32 v28, v40, v42
	s_waitcnt lgkmcnt(0)
	v_cvt_pk_bf16_f32 v29, v44, v48
	v_lshl_add_u64 v[30:31], v[46:47], 0, v[30:31]
	global_store_dwordx4 v[30:31], v[26:29], off
	v_or_b32_e32 v30, s0, v23
	v_ashrrev_i32_e32 v31, 31, v30
	v_cvt_pk_bf16_f32 v26, v33, v35
	v_cvt_pk_bf16_f32 v27, v37, v39
	v_cvt_pk_bf16_f32 v28, v41, v43
	v_cvt_pk_bf16_f32 v29, v45, v49
	v_lshlrev_b64 v[30:31], 12, v[30:31]
	ds_read2_b32 v[32:33], v18 offset0:48 offset1:56
	ds_read2_b32 v[34:35], v18 offset0:113 offset1:121
	ds_read2_b32 v[36:37], v18 offset0:178 offset1:186
	ds_read2_b32 v[38:39], v18 offset0:243 offset1:251
	ds_read2_b32 v[40:41], v0 offset0:52 offset1:60
	ds_read2_b32 v[42:43], v0 offset0:117 offset1:125
	ds_read2_b32 v[44:45], v0 offset0:182 offset1:190
	ds_read2_b32 v[48:49], v0 offset0:247 offset1:255
	v_lshl_add_u64 v[30:31], v[46:47], 0, v[30:31]
	global_store_dwordx4 v[30:31], v[26:29], off
	v_or_b32_e32 v30, s0, v24
	v_ashrrev_i32_e32 v31, 31, v30
	v_lshlrev_b64 v[30:31], 12, v[30:31]
	s_waitcnt lgkmcnt(6)
	v_cvt_pk_bf16_f32 v26, v32, v34
	s_waitcnt lgkmcnt(4)
	v_cvt_pk_bf16_f32 v27, v36, v38
	s_waitcnt lgkmcnt(2)
	v_cvt_pk_bf16_f32 v28, v40, v42
	s_waitcnt lgkmcnt(0)
	v_cvt_pk_bf16_f32 v29, v44, v48
	v_lshl_add_u64 v[30:31], v[46:47], 0, v[30:31]
	global_store_dwordx4 v[30:31], v[26:29], off
	v_or_b32_e32 v30, s0, v25
	v_ashrrev_i32_e32 v31, 31, v30
	v_lshlrev_b64 v[30:31], 12, v[30:31]
	v_cvt_pk_bf16_f32 v26, v33, v35
	v_cvt_pk_bf16_f32 v27, v37, v39
	v_cvt_pk_bf16_f32 v28, v41, v43
	v_cvt_pk_bf16_f32 v29, v45, v49
	v_lshl_add_u64 v[30:31], v[46:47], 0, v[30:31]
	global_store_dwordx4 v[30:31], v[26:29], off
	s_waitcnt lgkmcnt(0)

.LBB0_590:
	s_andn2_b64 vcc, exec, s[0:1]
	s_cbranch_vccnz .LBB0_592
	s_add_i32 s0, s5, 0x3400
	s_and_b32 s1, s0, 0x1ffc0
	v_or_b32_e32 v0, s1, v3
	v_readlane_b32 s12, v248, 0
	s_and_b32 s0, s2, 0x7c0
	v_lshlrev_b32_e32 v0, 13, v0
	v_readlane_b32 s13, v248, 1
	s_lshl_b32 s88, s0, 2
	s_mov_b32 s6, 0x18000
	v_lshl_add_u64 v[26:27], s[12:13], 0, v[0:1]
	v_lshl_add_u64 v[26:27], v[26:27], 0, s[88:89]
	v_lshlrev_b32_e32 v0, 2, v2
	v_lshl_add_u64 v[88:89], v[26:27], 0, v[0:1]
	v_add_co_u32_e32 v30, vcc, 0x8000, v88
	v_add_u32_e32 v0, 0x410, v16
	s_nop 0
	v_addc_co_u32_e32 v31, vcc, 0, v89, vcc
	v_add_co_u32_e32 v34, vcc, s67, v88
	global_load_dwordx4 v[26:29], v[88:89], off nt
	s_nop 0
	global_load_dwordx4 v[30:33], v[30:31], off nt
	v_addc_co_u32_e32 v35, vcc, 0, v89, vcc
	v_add_co_u32_e32 v38, vcc, s6, v88
	s_mov_b32 s6, 0x28000
	s_nop 0
	v_addc_co_u32_e32 v39, vcc, 0, v89, vcc
	global_load_dwordx4 v[34:37], v[34:35], off nt
	s_nop 0
	global_load_dwordx4 v[38:41], v[38:39], off nt
	v_add_co_u32_e32 v42, vcc, s50, v88
	s_lshl_b32 s88, s1, 1
	s_nop 0
	v_addc_co_u32_e32 v43, vcc, 0, v89, vcc
	v_add_co_u32_e32 v46, vcc, s6, v88
	s_mov_b32 s6, 0x30000
	s_nop 0
	v_addc_co_u32_e32 v47, vcc, 0, v89, vcc
	global_load_dwordx4 v[42:45], v[42:43], off nt
	s_nop 0
	global_load_dwordx4 v[46:49], v[46:47], off nt
	v_add_co_u32_e32 v50, vcc, s6, v88
	s_mov_b32 s6, 0x38000
	s_nop 0
	v_addc_co_u32_e32 v51, vcc, 0, v89, vcc
	v_add_co_u32_e32 v54, vcc, s6, v88
	s_mov_b32 s6, 0x48000
	s_nop 0
	v_addc_co_u32_e32 v55, vcc, 0, v89, vcc
	global_load_dwordx4 v[50:53], v[50:51], off nt
	s_nop 0
	global_load_dwordx4 v[54:57], v[54:55], off nt
	v_add_co_u32_e32 v58, vcc, s93, v88
	v_readlane_b32 s14, v248, 2
	s_nop 0
	v_addc_co_u32_e32 v59, vcc, 0, v89, vcc
	v_add_co_u32_e32 v62, vcc, s6, v88
	s_mov_b32 s6, 0x50000
	s_nop 0
	v_addc_co_u32_e32 v63, vcc, 0, v89, vcc
	global_load_dwordx4 v[58:61], v[58:59], off nt
	s_nop 0
	global_load_dwordx4 v[62:65], v[62:63], off nt
	v_add_co_u32_e32 v68, vcc, s6, v88
	s_mov_b32 s6, 0x58000
	s_nop 0
	v_addc_co_u32_e32 v69, vcc, 0, v89, vcc
	v_add_co_u32_e32 v72, vcc, s6, v88
	s_mov_b32 s6, 0x68000
	s_nop 0
	v_addc_co_u32_e32 v73, vcc, 0, v89, vcc
	global_load_dwordx4 v[68:71], v[68:69], off nt
	s_nop 0
	global_load_dwordx4 v[72:75], v[72:73], off nt
	v_add_co_u32_e32 v76, vcc, s44, v88
	v_readlane_b32 s15, v248, 3
	s_nop 0
	v_addc_co_u32_e32 v77, vcc, 0, v89, vcc
	v_add_co_u32_e32 v80, vcc, s6, v88
	s_mov_b32 s6, 0x70000
	s_nop 0
	v_addc_co_u32_e32 v81, vcc, 0, v89, vcc
	global_load_dwordx4 v[76:79], v[76:77], off nt
	s_nop 0
	global_load_dwordx4 v[80:83], v[80:81], off nt
	v_add_co_u32_e32 v84, vcc, s6, v88
	s_mov_b32 s6, 0x78000
	s_nop 0
	v_addc_co_u32_e32 v85, vcc, 0, v89, vcc
	global_load_dwordx4 v[84:87], v[84:85], off nt
	v_add_co_u32_e32 v88, vcc, s6, v88
	v_readlane_b32 s16, v248, 4
	s_nop 0
	v_addc_co_u32_e32 v89, vcc, 0, v89, vcc
	global_load_dwordx4 v[88:91], v[88:89], off nt
	s_waitcnt vmcnt(15)
	ds_write2_b32 v16, v26, v27 offset1:1
	ds_write2_b32 v16, v28, v29 offset0:2 offset1:3
	s_waitcnt vmcnt(14)
	ds_write2_b32 v0, v30, v31 offset1:1
	v_add_u32_e32 v0, 0x418, v16
	ds_write2_b32 v0, v32, v33 offset1:1
	v_add_u32_e32 v0, 0x820, v16
	v_readlane_b32 s17, v248, 5
	v_readlane_b32 s18, v248, 6
	v_readlane_b32 s19, v248, 7
	s_waitcnt vmcnt(13)
	ds_write2_b32 v0, v34, v35 offset1:1
	v_add_u32_e32 v0, 0x828, v16
	ds_write2_b32 v0, v36, v37 offset1:1
	v_add_u32_e32 v0, 0xc30, v16
	s_waitcnt vmcnt(12)
	ds_write2_b32 v0, v38, v39 offset1:1
	v_add_u32_e32 v0, 0xc38, v16
	ds_write2_b32 v0, v40, v41 offset1:1
	v_add_u32_e32 v0, 0x1040, v16
	s_waitcnt vmcnt(11)
	ds_write2_b32 v0, v42, v43 offset1:1
	v_add_u32_e32 v0, 0x1048, v16
	ds_write2_b32 v0, v44, v45 offset1:1
	v_add_u32_e32 v0, 0x1450, v16
	s_waitcnt vmcnt(10)
	ds_write2_b32 v0, v46, v47 offset1:1
	v_add_u32_e32 v0, 0x1458, v16
	ds_write2_b32 v0, v48, v49 offset1:1
	v_add_u32_e32 v0, 0x1860, v16
	v_lshl_add_u64 v[46:47], v[8:9], 0, s[88:89]
	s_waitcnt vmcnt(9)
	ds_write2_b32 v0, v50, v51 offset1:1
	v_add_u32_e32 v0, 0x1868, v16
	ds_write2_b32 v0, v52, v53 offset1:1
	v_add_u32_e32 v0, 0x1c70, v16
	s_waitcnt vmcnt(8)
	ds_write2_b32 v0, v54, v55 offset1:1
	v_add_u32_e32 v0, 0x1c78, v16
	ds_write2_b32 v0, v56, v57 offset1:1
	v_add_u32_e32 v0, 0x2080, v16
	v_add_u32_e32 v50, 0x400, v18
	s_waitcnt vmcnt(7)
	ds_write2_b32 v0, v58, v59 offset1:1
	v_add_u32_e32 v0, 0x2088, v16
	ds_write2_b32 v0, v60, v61 offset1:1
	v_add_u32_e32 v0, 0x2490, v16
	s_waitcnt vmcnt(6)
	ds_write2_b32 v0, v62, v63 offset1:1
	v_add_u32_e32 v0, 0x2498, v16
	ds_write2_b32 v0, v64, v65 offset1:1
	v_add_u32_e32 v0, 0x28a0, v16
	s_waitcnt vmcnt(5)
	ds_write2_b32 v0, v68, v69 offset1:1
	v_add_u32_e32 v0, 0x28a8, v16
	ds_write2_b32 v0, v70, v71 offset1:1
	v_add_u32_e32 v0, 0x2cb0, v16
	s_waitcnt vmcnt(4)
	ds_write2_b32 v0, v72, v73 offset1:1
	v_add_u32_e32 v0, 0x2cb8, v16
	ds_write2_b32 v0, v74, v75 offset1:1
	v_add_u32_e32 v0, 0x30c0, v16
	s_waitcnt vmcnt(3)
	ds_write2_b32 v0, v76, v77 offset1:1
	v_add_u32_e32 v0, 0x30c8, v16
	ds_write2_b32 v0, v78, v79 offset1:1
	v_add_u32_e32 v0, 0x34d0, v16
	s_waitcnt vmcnt(2)
	ds_write2_b32 v0, v80, v81 offset1:1
	v_add_u32_e32 v0, 0x34d8, v16
	ds_write2_b32 v0, v82, v83 offset1:1
	v_add_u32_e32 v0, 0x38e0, v16
	s_waitcnt vmcnt(1)
	ds_write2_b32 v0, v84, v85 offset1:1
	v_add_u32_e32 v0, 0x38e8, v16
	ds_write2_b32 v0, v86, v87 offset1:1
	v_add_u32_e32 v0, 0x3cf0, v16
	s_waitcnt vmcnt(0)
	ds_write2_b32 v0, v88, v89 offset1:1
	v_add_u32_e32 v0, 0x3cf8, v16
	ds_write2_b32 v0, v90, v91 offset1:1
	s_waitcnt lgkmcnt(0)
	ds_read2_b32 v[30:31], v18 offset0:65 offset1:73
	ds_read2_b32 v[32:33], v18 offset1:8
	ds_read2_b32 v[34:35], v18 offset0:130 offset1:138
	ds_read2_b32 v[36:37], v18 offset0:195 offset1:203
	ds_read2_b32 v[38:39], v50 offset0:4 offset1:12
	ds_read2_b32 v[40:41], v50 offset0:69 offset1:77
	ds_read2_b32 v[42:43], v50 offset0:134 offset1:142
	ds_read2_b32 v[44:45], v50 offset0:199 offset1:207
	v_or_b32_e32 v0, s0, v17
	v_lshlrev_b32_e32 v0, 12, v0
	s_waitcnt lgkmcnt(6)
	v_cvt_pk_bf16_f32 v26, v32, v30
	s_waitcnt lgkmcnt(4)
	v_cvt_pk_bf16_f32 v27, v34, v36
	s_waitcnt lgkmcnt(2)
	v_cvt_pk_bf16_f32 v28, v38, v40
	s_waitcnt lgkmcnt(0)
	v_cvt_pk_bf16_f32 v29, v42, v44
	v_lshl_add_u64 v[48:49], v[46:47], 0, v[0:1]
	global_store_dwordx4 v[48:49], v[26:29], off
	v_or_b32_e32 v0, s0, v19
	v_lshlrev_b32_e32 v0, 12, v0
	v_cvt_pk_bf16_f32 v26, v33, v31
	v_cvt_pk_bf16_f32 v27, v35, v37
	v_cvt_pk_bf16_f32 v28, v39, v41
	v_cvt_pk_bf16_f32 v29, v43, v45
	ds_read2_b32 v[32:33], v18 offset0:81 offset1:89
	ds_read2_b32 v[34:35], v18 offset0:16 offset1:24
	ds_read2_b32 v[36:37], v18 offset0:146 offset1:154
	ds_read2_b32 v[38:39], v18 offset0:211 offset1:219
	ds_read2_b32 v[40:41], v50 offset0:20 offset1:28
	ds_read2_b32 v[42:43], v50 offset0:85 offset1:93
	ds_read2_b32 v[44:45], v50 offset0:150 offset1:158
	ds_read2_b32 v[48:49], v50 offset0:215 offset1:223
	v_lshl_add_u64 v[30:31], v[46:47], 0, v[0:1]
	v_or_b32_e32 v0, s0, v20
	v_lshlrev_b32_e32 v0, 12, v0
	global_store_dwordx4 v[30:31], v[26:29], off
	v_lshl_add_u64 v[30:31], v[46:47], 0, v[0:1]
	v_or_b32_e32 v0, s0, v21
	s_waitcnt lgkmcnt(6)
	v_cvt_pk_bf16_f32 v26, v34, v32
	s_waitcnt lgkmcnt(4)
	v_cvt_pk_bf16_f32 v27, v36, v38
	s_waitcnt lgkmcnt(2)
	v_cvt_pk_bf16_f32 v28, v40, v42
	s_waitcnt lgkmcnt(0)
	v_cvt_pk_bf16_f32 v29, v44, v48
	global_store_dwordx4 v[30:31], v[26:29], off
	v_lshlrev_b32_e32 v0, 12, v0
	v_lshl_add_u64 v[30:31], v[46:47], 0, v[0:1]
	v_cvt_pk_bf16_f32 v26, v35, v33
	v_cvt_pk_bf16_f32 v27, v37, v39
	v_cvt_pk_bf16_f32 v28, v41, v43
	v_cvt_pk_bf16_f32 v29, v45, v49
	ds_read2_b32 v[32:33], v18 offset0:32 offset1:40
	ds_read2_b32 v[34:35], v18 offset0:97 offset1:105
	ds_read2_b32 v[36:37], v18 offset0:162 offset1:170
	ds_read2_b32 v[38:39], v18 offset0:227 offset1:235
	ds_read2_b32 v[40:41], v50 offset0:36 offset1:44
	ds_read2_b32 v[42:43], v50 offset0:101 offset1:109
	ds_read2_b32 v[44:45], v50 offset0:166 offset1:174
	ds_read2_b32 v[48:49], v50 offset0:231 offset1:239
	v_or_b32_e32 v0, s0, v22
	v_lshlrev_b32_e32 v0, 12, v0
	global_store_dwordx4 v[30:31], v[26:29], off
	v_lshl_add_u64 v[30:31], v[46:47], 0, v[0:1]
	v_or_b32_e32 v0, s0, v23
	s_waitcnt lgkmcnt(6)
	v_cvt_pk_bf16_f32 v26, v32, v34
	s_waitcnt lgkmcnt(4)
	v_cvt_pk_bf16_f32 v27, v36, v38
	s_waitcnt lgkmcnt(2)
	v_cvt_pk_bf16_f32 v28, v40, v42
	s_waitcnt lgkmcnt(0)
	v_cvt_pk_bf16_f32 v29, v44, v48
	global_store_dwordx4 v[30:31], v[26:29], off
	v_lshlrev_b32_e32 v0, 12, v0
	v_lshl_add_u64 v[30:31], v[46:47], 0, v[0:1]
	v_cvt_pk_bf16_f32 v26, v33, v35
	v_cvt_pk_bf16_f32 v27, v37, v39
	v_cvt_pk_bf16_f32 v28, v41, v43
	v_cvt_pk_bf16_f32 v29, v45, v49
	ds_read2_b32 v[32:33], v18 offset0:48 offset1:56
	ds_read2_b32 v[34:35], v18 offset0:113 offset1:121
	ds_read2_b32 v[36:37], v18 offset0:178 offset1:186
	ds_read2_b32 v[38:39], v18 offset0:243 offset1:251
	ds_read2_b32 v[40:41], v50 offset0:52 offset1:60
	ds_read2_b32 v[42:43], v50 offset0:117 offset1:125
	ds_read2_b32 v[44:45], v50 offset0:182 offset1:190
	ds_read2_b32 v[48:49], v50 offset0:247 offset1:255
	v_or_b32_e32 v0, s0, v24
	v_lshlrev_b32_e32 v0, 12, v0
	global_store_dwordx4 v[30:31], v[26:29], off
	v_lshl_add_u64 v[30:31], v[46:47], 0, v[0:1]
	v_or_b32_e32 v0, s0, v25
	s_waitcnt lgkmcnt(6)
	v_cvt_pk_bf16_f32 v26, v32, v34
	s_waitcnt lgkmcnt(4)
	v_cvt_pk_bf16_f32 v27, v36, v38
	s_waitcnt lgkmcnt(2)
	v_cvt_pk_bf16_f32 v28, v40, v42
	s_waitcnt lgkmcnt(0)
	v_cvt_pk_bf16_f32 v29, v44, v48
	v_lshlrev_b32_e32 v0, 12, v0
	global_store_dwordx4 v[30:31], v[26:29], off
	v_lshl_add_u64 v[30:31], v[46:47], 0, v[0:1]
	s_nop 0
	v_cvt_pk_bf16_f32 v26, v33, v35
	v_cvt_pk_bf16_f32 v27, v37, v39
	v_cvt_pk_bf16_f32 v28, v41, v43
	v_cvt_pk_bf16_f32 v29, v45, v49
	global_store_dwordx4 v[30:31], v[26:29], off
	s_waitcnt lgkmcnt(0)

.LBB0_593:
	s_andn2_b64 vcc, exec, s[0:1]
	s_cbranch_vccnz .LBB0_595
	s_add_i32 s0, s9, 0xec00
	s_and_b32 s1, s0, 0xffff
	s_mul_i32 s1, s1, 0xaaab
	s_lshr_b32 s6, s1, 16
	s_lshr_b32 s1, s1, 22
	s_mulk_i32 s1, 0x60
	s_sub_i32 s0, s0, s1
	s_and_b32 s1, s6, 0xffc0
	s_lshl_b32 s0, s0, 6
	v_or_b32_e32 v0, s1, v3
	v_readlane_b32 s68, v246, 43
	s_and_b32 s0, s0, 0xffc0
	v_mul_u32_u24_e32 v0, 0x6000, v0
	v_readlane_b32 s76, v246, 51
	v_readlane_b32 s77, v246, 52
	s_lshl_b32 s88, s0, 2
	s_mov_b32 s6, 0x18000
	v_lshl_add_u64 v[26:27], s[76:77], 0, v[0:1]
	v_lshl_add_u64 v[26:27], v[26:27], 0, s[88:89]
	v_lshlrev_b32_e32 v0, 2, v2
	v_lshl_add_u64 v[88:89], v[26:27], 0, v[0:1]
	v_add_co_u32_e32 v30, vcc, s6, v88
	s_mov_b32 s6, 0x30000
	s_nop 0
	v_addc_co_u32_e32 v31, vcc, 0, v89, vcc
	v_add_co_u32_e32 v34, vcc, s6, v88
	global_load_dwordx4 v[26:29], v[88:89], off nt
	s_nop 0
	global_load_dwordx4 v[30:33], v[30:31], off nt
	v_addc_co_u32_e32 v35, vcc, 0, v89, vcc
	s_mov_b32 s6, 0x48000
	v_add_co_u32_e32 v38, vcc, s6, v88
	s_mov_b32 s6, 0x78000
	s_nop 0
	v_addc_co_u32_e32 v39, vcc, 0, v89, vcc
	global_load_dwordx4 v[34:37], v[34:35], off nt
	s_nop 0
	global_load_dwordx4 v[38:41], v[38:39], off nt
	v_add_co_u32_e32 v42, vcc, s44, v88
	v_add_u32_e32 v0, 0x410, v16
	s_nop 0
	v_addc_co_u32_e32 v43, vcc, 0, v89, vcc
	v_add_co_u32_e32 v46, vcc, s6, v88
	s_mov_b32 s6, 0x90000
	s_nop 0
	v_addc_co_u32_e32 v47, vcc, 0, v89, vcc
	global_load_dwordx4 v[42:45], v[42:43], off nt
	s_nop 0
	global_load_dwordx4 v[46:49], v[46:47], off nt
	v_add_co_u32_e32 v50, vcc, s6, v88
	s_mov_b32 s6, 0xa8000
	s_nop 0
	v_addc_co_u32_e32 v51, vcc, 0, v89, vcc
	v_add_co_u32_e32 v54, vcc, s6, v88
	s_mov_b32 s6, 0xc0000
	s_nop 0
	v_addc_co_u32_e32 v55, vcc, 0, v89, vcc
	global_load_dwordx4 v[50:53], v[50:51], off nt
	s_nop 0
	global_load_dwordx4 v[54:57], v[54:55], off nt
	v_add_co_u32_e32 v58, vcc, s6, v88
	s_mov_b32 s6, 0xd8000
	s_nop 0
	v_addc_co_u32_e32 v59, vcc, 0, v89, vcc
	v_add_co_u32_e32 v62, vcc, s6, v88
	s_mov_b32 s6, 0xf0000
	s_nop 0
	v_addc_co_u32_e32 v63, vcc, 0, v89, vcc
	global_load_dwordx4 v[58:61], v[58:59], off nt
	s_nop 0
	global_load_dwordx4 v[62:65], v[62:63], off nt
	v_add_co_u32_e32 v68, vcc, s6, v88
	s_mov_b32 s6, 0x108000
	s_nop 0
	v_addc_co_u32_e32 v69, vcc, 0, v89, vcc
	v_add_co_u32_e32 v72, vcc, s6, v88
	s_mov_b32 s6, 0x120000
	s_nop 0
	v_addc_co_u32_e32 v73, vcc, 0, v89, vcc
	global_load_dwordx4 v[68:71], v[68:69], off nt
	s_nop 0
	global_load_dwordx4 v[72:75], v[72:73], off nt
	v_add_co_u32_e32 v76, vcc, s6, v88
	s_mov_b32 s6, 0x138000
	s_nop 0
	v_addc_co_u32_e32 v77, vcc, 0, v89, vcc
	global_load_dwordx4 v[76:79], v[76:77], off nt
	v_add_co_u32_e32 v80, vcc, s6, v88
	s_mov_b32 s6, 0x150000
	s_nop 0
	v_addc_co_u32_e32 v81, vcc, 0, v89, vcc
	global_load_dwordx4 v[80:83], v[80:81], off nt
	v_add_co_u32_e32 v84, vcc, s6, v88
	s_mov_b32 s6, 0x168000
	s_nop 0
	v_addc_co_u32_e32 v85, vcc, 0, v89, vcc
	global_load_dwordx4 v[84:87], v[84:85], off nt
	v_add_co_u32_e32 v88, vcc, s6, v88
	s_lshl_b32 s88, s1, 1
	s_nop 0
	v_addc_co_u32_e32 v89, vcc, 0, v89, vcc
	global_load_dwordx4 v[88:91], v[88:89], off nt
	s_waitcnt vmcnt(15)
	ds_write2_b32 v16, v26, v27 offset1:1
	ds_write2_b32 v16, v28, v29 offset0:2 offset1:3
	s_waitcnt vmcnt(14)
	ds_write2_b32 v0, v30, v31 offset1:1
	v_add_u32_e32 v0, 0x418, v16
	ds_write2_b32 v0, v32, v33 offset1:1
	v_add_u32_e32 v0, 0x820, v16
	v_readlane_b32 s74, v246, 49
	v_readlane_b32 s75, v246, 50
	v_readlane_b32 s72, v246, 47
	v_readlane_b32 s74, v245, 58
	s_waitcnt vmcnt(13)
	ds_write2_b32 v0, v34, v35 offset1:1
	v_add_u32_e32 v0, 0x828, v16
	ds_write2_b32 v0, v36, v37 offset1:1
	v_add_u32_e32 v0, 0xc30, v16
	s_waitcnt vmcnt(12)
	ds_write2_b32 v0, v38, v39 offset1:1
	v_add_u32_e32 v0, 0xc38, v16
	ds_write2_b32 v0, v40, v41 offset1:1
	v_add_u32_e32 v0, 0x1040, v16
	v_readlane_b32 s75, v245, 59
	v_readlane_b32 s72, v245, 15
	v_readlane_b32 s69, v246, 44
	s_waitcnt vmcnt(11)
	ds_write2_b32 v0, v42, v43 offset1:1
	v_add_u32_e32 v0, 0x1048, v16
	ds_write2_b32 v0, v44, v45 offset1:1
	v_add_u32_e32 v0, 0x1450, v16
	s_waitcnt vmcnt(10)
	ds_write2_b32 v0, v46, v47 offset1:1
	v_add_u32_e32 v0, 0x1458, v16
	ds_write2_b32 v0, v48, v49 offset1:1
	v_add_u32_e32 v0, 0x1860, v16
	v_lshl_add_u64 v[46:47], v[10:11], 0, s[88:89]
	v_readlane_b32 s70, v246, 45
	v_readlane_b32 s71, v246, 46
	s_waitcnt vmcnt(9)
	ds_write2_b32 v0, v50, v51 offset1:1
	v_add_u32_e32 v0, 0x1868, v16
	ds_write2_b32 v0, v52, v53 offset1:1
	v_add_u32_e32 v0, 0x1c70, v16
	s_waitcnt vmcnt(8)
	ds_write2_b32 v0, v54, v55 offset1:1
	v_add_u32_e32 v0, 0x1c78, v16
	ds_write2_b32 v0, v56, v57 offset1:1
	v_add_u32_e32 v0, 0x2080, v16
	v_add_u32_e32 v50, 0x400, v18
	v_readlane_b32 s73, v246, 48
	v_readlane_b32 s78, v246, 53
	s_waitcnt vmcnt(7)
	ds_write2_b32 v0, v58, v59 offset1:1
	v_add_u32_e32 v0, 0x2088, v16
	ds_write2_b32 v0, v60, v61 offset1:1
	v_add_u32_e32 v0, 0x2490, v16
	s_waitcnt vmcnt(6)
	ds_write2_b32 v0, v62, v63 offset1:1
	v_add_u32_e32 v0, 0x2498, v16
	ds_write2_b32 v0, v64, v65 offset1:1
	v_add_u32_e32 v0, 0x28a0, v16
	v_readlane_b32 s79, v246, 54
	v_readlane_b32 s80, v246, 55
	v_readlane_b32 s81, v246, 56
	s_waitcnt vmcnt(5)
	ds_write2_b32 v0, v68, v69 offset1:1
	v_add_u32_e32 v0, 0x28a8, v16
	ds_write2_b32 v0, v70, v71 offset1:1
	v_add_u32_e32 v0, 0x2cb0, v16
	s_waitcnt vmcnt(4)
	ds_write2_b32 v0, v72, v73 offset1:1
	v_add_u32_e32 v0, 0x2cb8, v16
	ds_write2_b32 v0, v74, v75 offset1:1
	v_add_u32_e32 v0, 0x30c0, v16
	s_waitcnt vmcnt(3)
	ds_write2_b32 v0, v76, v77 offset1:1
	v_add_u32_e32 v0, 0x30c8, v16
	ds_write2_b32 v0, v78, v79 offset1:1
	v_add_u32_e32 v0, 0x34d0, v16
	v_readlane_b32 s82, v246, 57
	s_waitcnt vmcnt(2)
	ds_write2_b32 v0, v80, v81 offset1:1
	v_add_u32_e32 v0, 0x34d8, v16
	ds_write2_b32 v0, v82, v83 offset1:1
	v_add_u32_e32 v0, 0x38e0, v16
	v_readlane_b32 s83, v246, 58
	s_waitcnt vmcnt(1)
	ds_write2_b32 v0, v84, v85 offset1:1
	v_add_u32_e32 v0, 0x38e8, v16
	ds_write2_b32 v0, v86, v87 offset1:1
	v_add_u32_e32 v0, 0x3cf0, v16
	s_waitcnt vmcnt(0)
	ds_write2_b32 v0, v88, v89 offset1:1
	v_add_u32_e32 v0, 0x3cf8, v16
	ds_write2_b32 v0, v90, v91 offset1:1
	s_waitcnt lgkmcnt(0)
	ds_read2_b32 v[30:31], v18 offset0:65 offset1:73
	ds_read2_b32 v[32:33], v18 offset1:8
	ds_read2_b32 v[34:35], v18 offset0:130 offset1:138
	ds_read2_b32 v[36:37], v18 offset0:195 offset1:203
	ds_read2_b32 v[38:39], v50 offset0:4 offset1:12
	ds_read2_b32 v[40:41], v50 offset0:69 offset1:77
	ds_read2_b32 v[42:43], v50 offset0:134 offset1:142
	ds_read2_b32 v[44:45], v50 offset0:199 offset1:207
	v_or_b32_e32 v0, s0, v17
	v_lshlrev_b32_e32 v0, 12, v0
	s_waitcnt lgkmcnt(6)
	v_cvt_pk_bf16_f32 v26, v32, v30
	s_waitcnt lgkmcnt(4)
	v_cvt_pk_bf16_f32 v27, v34, v36
	s_waitcnt lgkmcnt(2)
	v_cvt_pk_bf16_f32 v28, v38, v40
	s_waitcnt lgkmcnt(0)
	v_cvt_pk_bf16_f32 v29, v42, v44
	v_lshl_add_u64 v[48:49], v[46:47], 0, v[0:1]
	global_store_dwordx4 v[48:49], v[26:29], off
	v_or_b32_e32 v0, s0, v19
	v_lshlrev_b32_e32 v0, 12, v0
	v_cvt_pk_bf16_f32 v26, v33, v31
	v_cvt_pk_bf16_f32 v27, v35, v37
	v_cvt_pk_bf16_f32 v28, v39, v41
	v_cvt_pk_bf16_f32 v29, v43, v45
	ds_read2_b32 v[32:33], v18 offset0:81 offset1:89
	ds_read2_b32 v[34:35], v18 offset0:16 offset1:24
	ds_read2_b32 v[36:37], v18 offset0:146 offset1:154
	ds_read2_b32 v[38:39], v18 offset0:211 offset1:219
	ds_read2_b32 v[40:41], v50 offset0:20 offset1:28
	ds_read2_b32 v[42:43], v50 offset0:85 offset1:93
	ds_read2_b32 v[44:45], v50 offset0:150 offset1:158
	ds_read2_b32 v[48:49], v50 offset0:215 offset1:223
	v_lshl_add_u64 v[30:31], v[46:47], 0, v[0:1]
	v_or_b32_e32 v0, s0, v20
	v_lshlrev_b32_e32 v0, 12, v0
	global_store_dwordx4 v[30:31], v[26:29], off
	v_lshl_add_u64 v[30:31], v[46:47], 0, v[0:1]
	v_or_b32_e32 v0, s0, v21
	s_waitcnt lgkmcnt(6)
	v_cvt_pk_bf16_f32 v26, v34, v32
	s_waitcnt lgkmcnt(4)
	v_cvt_pk_bf16_f32 v27, v36, v38
	s_waitcnt lgkmcnt(2)
	v_cvt_pk_bf16_f32 v28, v40, v42
	s_waitcnt lgkmcnt(0)
	v_cvt_pk_bf16_f32 v29, v44, v48
	global_store_dwordx4 v[30:31], v[26:29], off
	v_lshlrev_b32_e32 v0, 12, v0
	v_lshl_add_u64 v[30:31], v[46:47], 0, v[0:1]
	v_cvt_pk_bf16_f32 v26, v35, v33
	v_cvt_pk_bf16_f32 v27, v37, v39
	v_cvt_pk_bf16_f32 v28, v41, v43
	v_cvt_pk_bf16_f32 v29, v45, v49
	ds_read2_b32 v[32:33], v18 offset0:32 offset1:40
	ds_read2_b32 v[34:35], v18 offset0:97 offset1:105
	ds_read2_b32 v[36:37], v18 offset0:162 offset1:170
	ds_read2_b32 v[38:39], v18 offset0:227 offset1:235
	ds_read2_b32 v[40:41], v50 offset0:36 offset1:44
	ds_read2_b32 v[42:43], v50 offset0:101 offset1:109
	ds_read2_b32 v[44:45], v50 offset0:166 offset1:174
	ds_read2_b32 v[48:49], v50 offset0:231 offset1:239
	v_or_b32_e32 v0, s0, v22
	v_lshlrev_b32_e32 v0, 12, v0
	global_store_dwordx4 v[30:31], v[26:29], off
	v_lshl_add_u64 v[30:31], v[46:47], 0, v[0:1]
	v_or_b32_e32 v0, s0, v23
	s_waitcnt lgkmcnt(6)
	v_cvt_pk_bf16_f32 v26, v32, v34
	s_waitcnt lgkmcnt(4)
	v_cvt_pk_bf16_f32 v27, v36, v38
	s_waitcnt lgkmcnt(2)
	v_cvt_pk_bf16_f32 v28, v40, v42
	s_waitcnt lgkmcnt(0)
	v_cvt_pk_bf16_f32 v29, v44, v48
	global_store_dwordx4 v[30:31], v[26:29], off
	v_lshlrev_b32_e32 v0, 12, v0
	v_lshl_add_u64 v[30:31], v[46:47], 0, v[0:1]
	v_cvt_pk_bf16_f32 v26, v33, v35
	v_cvt_pk_bf16_f32 v27, v37, v39
	v_cvt_pk_bf16_f32 v28, v41, v43
	v_cvt_pk_bf16_f32 v29, v45, v49
	ds_read2_b32 v[32:33], v18 offset0:48 offset1:56
	ds_read2_b32 v[34:35], v18 offset0:113 offset1:121
	ds_read2_b32 v[36:37], v18 offset0:178 offset1:186
	ds_read2_b32 v[38:39], v18 offset0:243 offset1:251
	ds_read2_b32 v[40:41], v50 offset0:52 offset1:60
	ds_read2_b32 v[42:43], v50 offset0:117 offset1:125
	ds_read2_b32 v[44:45], v50 offset0:182 offset1:190
	ds_read2_b32 v[48:49], v50 offset0:247 offset1:255
	v_or_b32_e32 v0, s0, v24
	v_lshlrev_b32_e32 v0, 12, v0
	global_store_dwordx4 v[30:31], v[26:29], off
	v_lshl_add_u64 v[30:31], v[46:47], 0, v[0:1]
	v_or_b32_e32 v0, s0, v25
	s_waitcnt lgkmcnt(6)
	v_cvt_pk_bf16_f32 v26, v32, v34
	s_waitcnt lgkmcnt(4)
	v_cvt_pk_bf16_f32 v27, v36, v38
	s_waitcnt lgkmcnt(2)
	v_cvt_pk_bf16_f32 v28, v40, v42
	s_waitcnt lgkmcnt(0)
	v_cvt_pk_bf16_f32 v29, v44, v48
	v_lshlrev_b32_e32 v0, 12, v0
	global_store_dwordx4 v[30:31], v[26:29], off
	v_lshl_add_u64 v[30:31], v[46:47], 0, v[0:1]
	s_nop 0
	v_cvt_pk_bf16_f32 v26, v33, v35
	v_cvt_pk_bf16_f32 v27, v37, v39
	v_cvt_pk_bf16_f32 v28, v41, v43
	v_cvt_pk_bf16_f32 v29, v45, v49
	global_store_dwordx4 v[30:31], v[26:29], off
	s_waitcnt lgkmcnt(0)

.LBB0_596:
	s_andn2_b64 vcc, exec, s[0:1]
	s_cbranch_vccnz .LBB0_598
	s_add_i32 s0, s5, 0x5400
	s_and_b32 s1, s0, 0x1ffc0
	v_or_b32_e32 v0, s1, v3
	v_readlane_b32 s68, v246, 43
	s_and_b32 s0, s2, 0x7c0
	v_lshlrev_b32_e32 v0, 13, v0
	v_readlane_b32 s74, v246, 49
	v_readlane_b32 s75, v246, 50
	s_lshl_b32 s88, s0, 2
	s_mov_b32 s6, 0x18000
	v_lshl_add_u64 v[26:27], s[74:75], 0, v[0:1]
	v_lshl_add_u64 v[26:27], v[26:27], 0, s[88:89]
	v_lshlrev_b32_e32 v0, 2, v2
	v_lshl_add_u64 v[88:89], v[26:27], 0, v[0:1]
	v_add_co_u32_e32 v30, vcc, 0x8000, v88
	v_add_u32_e32 v0, 0x410, v16
	s_nop 0
	v_addc_co_u32_e32 v31, vcc, 0, v89, vcc
	v_add_co_u32_e32 v34, vcc, s67, v88
	global_load_dwordx4 v[26:29], v[88:89], off nt
	s_nop 0
	global_load_dwordx4 v[30:33], v[30:31], off nt
	v_addc_co_u32_e32 v35, vcc, 0, v89, vcc
	v_add_co_u32_e32 v38, vcc, s6, v88
	s_mov_b32 s6, 0x28000
	s_nop 0
	v_addc_co_u32_e32 v39, vcc, 0, v89, vcc
	global_load_dwordx4 v[34:37], v[34:35], off nt
	s_nop 0
	global_load_dwordx4 v[38:41], v[38:39], off nt
	v_add_co_u32_e32 v42, vcc, s50, v88
	s_lshl_b32 s88, s1, 1
	s_nop 0
	v_addc_co_u32_e32 v43, vcc, 0, v89, vcc
	v_add_co_u32_e32 v46, vcc, s6, v88
	s_mov_b32 s6, 0x30000
	s_nop 0
	v_addc_co_u32_e32 v47, vcc, 0, v89, vcc
	global_load_dwordx4 v[42:45], v[42:43], off nt
	s_nop 0
	global_load_dwordx4 v[46:49], v[46:47], off nt
	v_add_co_u32_e32 v50, vcc, s6, v88
	s_mov_b32 s6, 0x38000
	s_nop 0
	v_addc_co_u32_e32 v51, vcc, 0, v89, vcc
	v_add_co_u32_e32 v54, vcc, s6, v88
	s_mov_b32 s6, 0x48000
	s_nop 0
	v_addc_co_u32_e32 v55, vcc, 0, v89, vcc
	global_load_dwordx4 v[50:53], v[50:51], off nt
	s_nop 0
	global_load_dwordx4 v[54:57], v[54:55], off nt
	v_add_co_u32_e32 v58, vcc, s93, v88
	v_readlane_b32 s72, v246, 47
	s_nop 0
	v_addc_co_u32_e32 v59, vcc, 0, v89, vcc
	v_add_co_u32_e32 v62, vcc, s6, v88
	s_mov_b32 s6, 0x50000
	s_nop 0
	v_addc_co_u32_e32 v63, vcc, 0, v89, vcc
	global_load_dwordx4 v[58:61], v[58:59], off nt
	s_nop 0
	global_load_dwordx4 v[62:65], v[62:63], off nt
	v_add_co_u32_e32 v68, vcc, s6, v88
	s_mov_b32 s6, 0x58000
	s_nop 0
	v_addc_co_u32_e32 v69, vcc, 0, v89, vcc
	v_add_co_u32_e32 v72, vcc, s6, v88
	s_mov_b32 s6, 0x68000
	s_nop 0
	v_addc_co_u32_e32 v73, vcc, 0, v89, vcc
	global_load_dwordx4 v[68:71], v[68:69], off nt
	s_nop 0
	global_load_dwordx4 v[72:75], v[72:73], off nt
	v_add_co_u32_e32 v76, vcc, s44, v88
	v_readlane_b32 s74, v245, 58
	s_nop 0
	v_addc_co_u32_e32 v77, vcc, 0, v89, vcc
	v_add_co_u32_e32 v80, vcc, s6, v88
	s_mov_b32 s6, 0x70000
	s_nop 0
	v_addc_co_u32_e32 v81, vcc, 0, v89, vcc
	global_load_dwordx4 v[76:79], v[76:77], off nt
	s_nop 0
	global_load_dwordx4 v[80:83], v[80:81], off nt
	v_add_co_u32_e32 v84, vcc, s6, v88
	s_mov_b32 s6, 0x78000
	s_nop 0
	v_addc_co_u32_e32 v85, vcc, 0, v89, vcc
	global_load_dwordx4 v[84:87], v[84:85], off nt
	v_add_co_u32_e32 v88, vcc, s6, v88
	v_readlane_b32 s72, v245, 15
	s_nop 0
	v_addc_co_u32_e32 v89, vcc, 0, v89, vcc
	global_load_dwordx4 v[88:91], v[88:89], off nt
	s_waitcnt vmcnt(15)
	ds_write2_b32 v16, v26, v27 offset1:1
	ds_write2_b32 v16, v28, v29 offset0:2 offset1:3
	s_waitcnt vmcnt(14)
	ds_write2_b32 v0, v30, v31 offset1:1
	v_add_u32_e32 v0, 0x418, v16
	ds_write2_b32 v0, v32, v33 offset1:1
	v_add_u32_e32 v0, 0x820, v16
	v_readlane_b32 s75, v245, 59
	v_readlane_b32 s69, v246, 44
	v_readlane_b32 s70, v246, 45
	s_waitcnt vmcnt(13)
	ds_write2_b32 v0, v34, v35 offset1:1
	v_add_u32_e32 v0, 0x828, v16
	ds_write2_b32 v0, v36, v37 offset1:1
	v_add_u32_e32 v0, 0xc30, v16
	s_waitcnt vmcnt(12)
	ds_write2_b32 v0, v38, v39 offset1:1
	v_add_u32_e32 v0, 0xc38, v16
	ds_write2_b32 v0, v40, v41 offset1:1
	v_add_u32_e32 v0, 0x1040, v16
	v_readlane_b32 s71, v246, 46
	v_readlane_b32 s73, v246, 48
	v_readlane_b32 s76, v246, 51
	s_waitcnt vmcnt(11)
	ds_write2_b32 v0, v42, v43 offset1:1
	v_add_u32_e32 v0, 0x1048, v16
	ds_write2_b32 v0, v44, v45 offset1:1
	v_add_u32_e32 v0, 0x1450, v16
	s_waitcnt vmcnt(10)
	ds_write2_b32 v0, v46, v47 offset1:1
	v_add_u32_e32 v0, 0x1458, v16
	ds_write2_b32 v0, v48, v49 offset1:1
	v_add_u32_e32 v0, 0x1860, v16
	v_lshl_add_u64 v[46:47], v[12:13], 0, s[88:89]
	v_readlane_b32 s77, v246, 52
	v_readlane_b32 s78, v246, 53
	s_waitcnt vmcnt(9)
	ds_write2_b32 v0, v50, v51 offset1:1
	v_add_u32_e32 v0, 0x1868, v16
	ds_write2_b32 v0, v52, v53 offset1:1
	v_add_u32_e32 v0, 0x1c70, v16
	s_waitcnt vmcnt(8)
	ds_write2_b32 v0, v54, v55 offset1:1
	v_add_u32_e32 v0, 0x1c78, v16
	ds_write2_b32 v0, v56, v57 offset1:1
	v_add_u32_e32 v0, 0x2080, v16
	v_add_u32_e32 v50, 0x400, v18
	v_readlane_b32 s79, v246, 54
	v_readlane_b32 s80, v246, 55
	s_waitcnt vmcnt(7)
	ds_write2_b32 v0, v58, v59 offset1:1
	v_add_u32_e32 v0, 0x2088, v16
	ds_write2_b32 v0, v60, v61 offset1:1
	v_add_u32_e32 v0, 0x2490, v16
	s_waitcnt vmcnt(6)
	ds_write2_b32 v0, v62, v63 offset1:1
	v_add_u32_e32 v0, 0x2498, v16
	ds_write2_b32 v0, v64, v65 offset1:1
	v_add_u32_e32 v0, 0x28a0, v16
	v_readlane_b32 s81, v246, 56
	v_readlane_b32 s82, v246, 57
	v_readlane_b32 s83, v246, 58
	s_waitcnt vmcnt(5)
	ds_write2_b32 v0, v68, v69 offset1:1
	v_add_u32_e32 v0, 0x28a8, v16
	ds_write2_b32 v0, v70, v71 offset1:1
	v_add_u32_e32 v0, 0x2cb0, v16
	s_waitcnt vmcnt(4)
	ds_write2_b32 v0, v72, v73 offset1:1
	v_add_u32_e32 v0, 0x2cb8, v16
	ds_write2_b32 v0, v74, v75 offset1:1
	v_add_u32_e32 v0, 0x30c0, v16
	s_waitcnt vmcnt(3)
	ds_write2_b32 v0, v76, v77 offset1:1
	v_add_u32_e32 v0, 0x30c8, v16
	ds_write2_b32 v0, v78, v79 offset1:1
	v_add_u32_e32 v0, 0x34d0, v16
	s_waitcnt vmcnt(2)
	ds_write2_b32 v0, v80, v81 offset1:1
	v_add_u32_e32 v0, 0x34d8, v16
	ds_write2_b32 v0, v82, v83 offset1:1
	v_add_u32_e32 v0, 0x38e0, v16
	s_waitcnt vmcnt(1)
	ds_write2_b32 v0, v84, v85 offset1:1
	v_add_u32_e32 v0, 0x38e8, v16
	ds_write2_b32 v0, v86, v87 offset1:1
	v_add_u32_e32 v0, 0x3cf0, v16
	s_waitcnt vmcnt(0)
	ds_write2_b32 v0, v88, v89 offset1:1
	v_add_u32_e32 v0, 0x3cf8, v16
	ds_write2_b32 v0, v90, v91 offset1:1
	s_waitcnt lgkmcnt(0)
	ds_read2_b32 v[30:31], v18 offset0:65 offset1:73
	ds_read2_b32 v[32:33], v18 offset1:8
	ds_read2_b32 v[34:35], v18 offset0:130 offset1:138
	ds_read2_b32 v[36:37], v18 offset0:195 offset1:203
	ds_read2_b32 v[38:39], v50 offset0:4 offset1:12
	ds_read2_b32 v[40:41], v50 offset0:69 offset1:77
	ds_read2_b32 v[42:43], v50 offset0:134 offset1:142
	ds_read2_b32 v[44:45], v50 offset0:199 offset1:207
	v_or_b32_e32 v0, s0, v17
	v_lshlrev_b32_e32 v0, 12, v0
	s_waitcnt lgkmcnt(6)
	v_cvt_pk_bf16_f32 v26, v32, v30
	s_waitcnt lgkmcnt(4)
	v_cvt_pk_bf16_f32 v27, v34, v36
	s_waitcnt lgkmcnt(2)
	v_cvt_pk_bf16_f32 v28, v38, v40
	s_waitcnt lgkmcnt(0)
	v_cvt_pk_bf16_f32 v29, v42, v44
	v_lshl_add_u64 v[48:49], v[46:47], 0, v[0:1]
	global_store_dwordx4 v[48:49], v[26:29], off
	v_or_b32_e32 v0, s0, v19
	v_lshlrev_b32_e32 v0, 12, v0
	v_cvt_pk_bf16_f32 v26, v33, v31
	v_cvt_pk_bf16_f32 v27, v35, v37
	v_cvt_pk_bf16_f32 v28, v39, v41
	v_cvt_pk_bf16_f32 v29, v43, v45
	ds_read2_b32 v[32:33], v18 offset0:81 offset1:89
	ds_read2_b32 v[34:35], v18 offset0:16 offset1:24
	ds_read2_b32 v[36:37], v18 offset0:146 offset1:154
	ds_read2_b32 v[38:39], v18 offset0:211 offset1:219
	ds_read2_b32 v[40:41], v50 offset0:20 offset1:28
	ds_read2_b32 v[42:43], v50 offset0:85 offset1:93
	ds_read2_b32 v[44:45], v50 offset0:150 offset1:158
	ds_read2_b32 v[48:49], v50 offset0:215 offset1:223
	v_lshl_add_u64 v[30:31], v[46:47], 0, v[0:1]
	v_or_b32_e32 v0, s0, v20
	v_lshlrev_b32_e32 v0, 12, v0
	global_store_dwordx4 v[30:31], v[26:29], off
	v_lshl_add_u64 v[30:31], v[46:47], 0, v[0:1]
	v_or_b32_e32 v0, s0, v21
	s_waitcnt lgkmcnt(6)
	v_cvt_pk_bf16_f32 v26, v34, v32
	s_waitcnt lgkmcnt(4)
	v_cvt_pk_bf16_f32 v27, v36, v38
	s_waitcnt lgkmcnt(2)
	v_cvt_pk_bf16_f32 v28, v40, v42
	s_waitcnt lgkmcnt(0)
	v_cvt_pk_bf16_f32 v29, v44, v48
	global_store_dwordx4 v[30:31], v[26:29], off
	v_lshlrev_b32_e32 v0, 12, v0
	v_lshl_add_u64 v[30:31], v[46:47], 0, v[0:1]
	v_cvt_pk_bf16_f32 v26, v35, v33
	v_cvt_pk_bf16_f32 v27, v37, v39
	v_cvt_pk_bf16_f32 v28, v41, v43
	v_cvt_pk_bf16_f32 v29, v45, v49
	ds_read2_b32 v[32:33], v18 offset0:32 offset1:40
	ds_read2_b32 v[34:35], v18 offset0:97 offset1:105
	ds_read2_b32 v[36:37], v18 offset0:162 offset1:170
	ds_read2_b32 v[38:39], v18 offset0:227 offset1:235
	ds_read2_b32 v[40:41], v50 offset0:36 offset1:44
	ds_read2_b32 v[42:43], v50 offset0:101 offset1:109
	ds_read2_b32 v[44:45], v50 offset0:166 offset1:174
	ds_read2_b32 v[48:49], v50 offset0:231 offset1:239
	v_or_b32_e32 v0, s0, v22
	v_lshlrev_b32_e32 v0, 12, v0
	global_store_dwordx4 v[30:31], v[26:29], off
	v_lshl_add_u64 v[30:31], v[46:47], 0, v[0:1]
	v_or_b32_e32 v0, s0, v23
	s_waitcnt lgkmcnt(6)
	v_cvt_pk_bf16_f32 v26, v32, v34
	s_waitcnt lgkmcnt(4)
	v_cvt_pk_bf16_f32 v27, v36, v38
	s_waitcnt lgkmcnt(2)
	v_cvt_pk_bf16_f32 v28, v40, v42
	s_waitcnt lgkmcnt(0)
	v_cvt_pk_bf16_f32 v29, v44, v48
	global_store_dwordx4 v[30:31], v[26:29], off
	v_lshlrev_b32_e32 v0, 12, v0
	v_lshl_add_u64 v[30:31], v[46:47], 0, v[0:1]
	v_cvt_pk_bf16_f32 v26, v33, v35
	v_cvt_pk_bf16_f32 v27, v37, v39
	v_cvt_pk_bf16_f32 v28, v41, v43
	v_cvt_pk_bf16_f32 v29, v45, v49
	ds_read2_b32 v[32:33], v18 offset0:48 offset1:56
	ds_read2_b32 v[34:35], v18 offset0:113 offset1:121
	ds_read2_b32 v[36:37], v18 offset0:178 offset1:186
	ds_read2_b32 v[38:39], v18 offset0:243 offset1:251
	ds_read2_b32 v[40:41], v50 offset0:52 offset1:60
	ds_read2_b32 v[42:43], v50 offset0:117 offset1:125
	ds_read2_b32 v[44:45], v50 offset0:182 offset1:190
	ds_read2_b32 v[48:49], v50 offset0:247 offset1:255
	v_or_b32_e32 v0, s0, v24
	v_lshlrev_b32_e32 v0, 12, v0
	global_store_dwordx4 v[30:31], v[26:29], off
	v_lshl_add_u64 v[30:31], v[46:47], 0, v[0:1]
	v_or_b32_e32 v0, s0, v25
	s_waitcnt lgkmcnt(6)
	v_cvt_pk_bf16_f32 v26, v32, v34
	s_waitcnt lgkmcnt(4)
	v_cvt_pk_bf16_f32 v27, v36, v38
	s_waitcnt lgkmcnt(2)
	v_cvt_pk_bf16_f32 v28, v40, v42
	s_waitcnt lgkmcnt(0)
	v_cvt_pk_bf16_f32 v29, v44, v48
	v_lshlrev_b32_e32 v0, 12, v0
	global_store_dwordx4 v[30:31], v[26:29], off
	v_lshl_add_u64 v[30:31], v[46:47], 0, v[0:1]
	s_nop 0
	v_cvt_pk_bf16_f32 v26, v33, v35
	v_cvt_pk_bf16_f32 v27, v37, v39
	v_cvt_pk_bf16_f32 v28, v41, v43
	v_cvt_pk_bf16_f32 v29, v45, v49
	global_store_dwordx4 v[30:31], v[26:29], off
	s_waitcnt lgkmcnt(0)

.LBB0_599:
	s_andn2_b64 vcc, exec, s[0:1]
	s_cbranch_vccnz .LBB0_580
	s_ashr_i32 s0, s9, 31
	s_lshr_b32 s0, s0, 25
	s_add_i32 s0, s9, s0
	s_ashr_i32 s0, s0, 7
	s_lshl_b32 s6, s0, 6
	v_or_b32_e32 v26, s6, v3
	s_lshl_b32 s0, s0, 13
	v_ashrrev_i32_e32 v27, 31, v26
	v_readlane_b32 s68, v246, 43
	s_sub_i32 s0, s2, s0
	v_lshlrev_b64 v[26:27], 15, v[26:27]
	v_readlane_b32 s69, v246, 44
	s_ashr_i32 s1, s0, 31
	v_lshlrev_b32_e32 v0, 2, v2
	v_lshl_add_u64 v[26:27], s[68:69], 0, v[26:27]
	v_lshl_add_u64 v[26:27], s[0:1], 2, v[26:27]
	v_lshl_add_u64 v[88:89], v[26:27], 0, v[0:1]
	v_add_co_u32_e32 v26, vcc, s50, v88
	s_mov_b32 s1, 0xa0000
	s_nop 0
	v_addc_co_u32_e32 v27, vcc, 0, v89, vcc
	v_add_co_u32_e32 v30, vcc, s93, v88
	global_load_dwordx4 v[26:29], v[26:27], off nt
	s_nop 0
	v_addc_co_u32_e32 v31, vcc, 0, v89, vcc
	v_add_co_u32_e32 v34, vcc, s44, v88
	v_add_u32_e32 v0, 0x410, v16
	s_nop 0
	v_addc_co_u32_e32 v35, vcc, 0, v89, vcc
	v_add_co_u32_e32 v38, vcc, s45, v88
	global_load_dwordx4 v[30:33], v[30:31], off nt
	s_nop 0
	global_load_dwordx4 v[34:37], v[34:35], off nt
	v_addc_co_u32_e32 v39, vcc, 0, v89, vcc
	v_add_co_u32_e32 v42, vcc, s1, v88
	s_mov_b32 s1, 0xc0000
	s_nop 0
	v_addc_co_u32_e32 v43, vcc, 0, v89, vcc
	v_add_co_u32_e32 v50, vcc, s1, v88
	global_load_dwordx4 v[38:41], v[38:39], off nt
	s_nop 0
	global_load_dwordx4 v[42:45], v[42:43], off nt
	s_nop 0
	global_load_dwordx4 v[46:49], v[88:89], off nt
	v_addc_co_u32_e32 v51, vcc, 0, v89, vcc
	s_mov_b32 s1, 0xe0000
	v_add_co_u32_e32 v54, vcc, s1, v88
	s_mov_b32 s1, 0x100000
	s_nop 0
	v_addc_co_u32_e32 v55, vcc, 0, v89, vcc
	global_load_dwordx4 v[50:53], v[50:51], off nt
	v_add_co_u32_e32 v58, vcc, s1, v88
	s_mov_b32 s1, 0x120000
	s_nop 0
	v_addc_co_u32_e32 v59, vcc, 0, v89, vcc
	v_add_co_u32_e32 v62, vcc, s1, v88
	global_load_dwordx4 v[54:57], v[54:55], off nt
	s_nop 0
	global_load_dwordx4 v[58:61], v[58:59], off nt
	v_addc_co_u32_e32 v63, vcc, 0, v89, vcc
	s_mov_b32 s1, 0x140000
	v_add_co_u32_e32 v68, vcc, s1, v88
	global_load_dwordx4 v[62:65], v[62:63], off nt
	s_nop 0
	v_addc_co_u32_e32 v69, vcc, 0, v89, vcc
	v_add_co_u32_e32 v72, vcc, s51, v88
	global_load_dwordx4 v[68:71], v[68:69], off nt
	s_nop 0
	v_addc_co_u32_e32 v73, vcc, 0, v89, vcc
	s_mov_b32 s1, 0x180000
	v_add_co_u32_e32 v76, vcc, s1, v88
	s_mov_b32 s1, 0x1a0000
	s_nop 0
	v_addc_co_u32_e32 v77, vcc, 0, v89, vcc
	global_load_dwordx4 v[72:75], v[72:73], off nt
	s_nop 0
	global_load_dwordx4 v[76:79], v[76:77], off nt
	v_add_co_u32_e32 v80, vcc, s1, v88
	s_mov_b32 s1, 0x1c0000
	s_nop 0
	v_addc_co_u32_e32 v81, vcc, 0, v89, vcc
	global_load_dwordx4 v[80:83], v[80:81], off nt
	v_add_co_u32_e32 v84, vcc, s1, v88
	v_add_u32_e32 v67, 0x418, v16
	s_nop 0
	v_addc_co_u32_e32 v85, vcc, 0, v89, vcc
	global_load_dwordx4 v[84:87], v[84:85], off nt
	v_add_co_u32_e32 v88, vcc, s65, v88
	v_add_u32_e32 v92, 0x820, v16
	s_nop 0
	v_addc_co_u32_e32 v89, vcc, 0, v89, vcc
	global_load_dwordx4 v[88:91], v[88:89], off nt
	v_add_u32_e32 v93, 0x828, v16
	v_add_u32_e32 v94, 0xc30, v16
	v_add_u32_e32 v95, 0xc38, v16
	v_add_u32_e32 v96, 0x1040, v16
	s_waitcnt vmcnt(15)
	ds_write2_b32 v0, v26, v27 offset1:1
	ds_write2_b32 v67, v28, v29 offset1:1
	s_waitcnt vmcnt(14)
	ds_write2_b32 v92, v30, v31 offset1:1
	ds_write2_b32 v93, v32, v33 offset1:1
	s_waitcnt vmcnt(13)
	ds_write2_b32 v94, v34, v35 offset1:1
	ds_write2_b32 v95, v36, v37 offset1:1
	s_waitcnt vmcnt(12)
	ds_write2_b32 v96, v38, v39 offset1:1
	v_add_u32_e32 v0, 0x1048, v16
	ds_write2_b32 v0, v40, v41 offset1:1
	v_add_u32_e32 v0, 0x1450, v16
	s_waitcnt vmcnt(11)
	ds_write2_b32 v0, v42, v43 offset1:1
	v_add_u32_e32 v0, 0x1458, v16
	ds_write2_b32 v0, v44, v45 offset1:1
	s_waitcnt vmcnt(10)
	ds_write2_b32 v16, v46, v47 offset1:1
	ds_write2_b32 v16, v48, v49 offset0:2 offset1:3
	v_add_u32_e32 v0, 0x1860, v16
	v_add_u32_e32 v48, s0, v17
	s_ashr_i32 s7, s6, 31
	v_ashrrev_i32_e32 v49, 31, v48
	s_waitcnt vmcnt(9)
	ds_write2_b32 v0, v50, v51 offset1:1
	v_add_u32_e32 v0, 0x1868, v16
	ds_write2_b32 v0, v52, v53 offset1:1
	v_add_u32_e32 v0, 0x1c70, v16
	v_lshl_add_u64 v[46:47], s[6:7], 1, v[14:15]
	v_lshlrev_b64 v[50:51], 12, v[48:49]
	v_lshl_add_u64 v[50:51], v[46:47], 0, v[50:51]
	s_waitcnt vmcnt(8)
	ds_write2_b32 v0, v54, v55 offset1:1
	v_add_u32_e32 v0, 0x1c78, v16
	ds_write2_b32 v0, v56, v57 offset1:1
	v_add_u32_e32 v0, 0x2080, v16
	s_waitcnt vmcnt(7)
	ds_write2_b32 v0, v58, v59 offset1:1
	v_add_u32_e32 v0, 0x2088, v16
	ds_write2_b32 v0, v60, v61 offset1:1
	v_add_u32_e32 v0, 0x2490, v16
	s_waitcnt vmcnt(6)
	ds_write2_b32 v0, v62, v63 offset1:1
	v_add_u32_e32 v0, 0x2498, v16
	ds_write2_b32 v0, v64, v65 offset1:1
	v_add_u32_e32 v0, 0x28a0, v16
	s_waitcnt vmcnt(5)
	ds_write2_b32 v0, v68, v69 offset1:1
	v_add_u32_e32 v0, 0x28a8, v16
	ds_write2_b32 v0, v70, v71 offset1:1
	v_add_u32_e32 v0, 0x2cb0, v16
	v_readlane_b32 s74, v246, 49
	v_readlane_b32 s75, v246, 50
	v_readlane_b32 s72, v246, 47
	v_readlane_b32 s74, v245, 58
	s_waitcnt vmcnt(4)
	ds_write2_b32 v0, v72, v73 offset1:1
	v_add_u32_e32 v0, 0x2cb8, v16
	ds_write2_b32 v0, v74, v75 offset1:1
	v_add_u32_e32 v0, 0x30c0, v16
	s_waitcnt vmcnt(3)
	ds_write2_b32 v0, v76, v77 offset1:1
	v_add_u32_e32 v0, 0x30c8, v16
	ds_write2_b32 v0, v78, v79 offset1:1
	v_add_u32_e32 v0, 0x34d0, v16
	s_waitcnt vmcnt(2)
	ds_write2_b32 v0, v80, v81 offset1:1
	v_add_u32_e32 v0, 0x34d8, v16
	ds_write2_b32 v0, v82, v83 offset1:1
	v_add_u32_e32 v0, 0x38e0, v16
	v_readlane_b32 s75, v245, 59
	s_waitcnt vmcnt(1)
	ds_write2_b32 v0, v84, v85 offset1:1
	v_add_u32_e32 v0, 0x38e8, v16
	ds_write2_b32 v0, v86, v87 offset1:1
	v_add_u32_e32 v0, 0x3cf0, v16
	v_readlane_b32 s72, v245, 15
	v_readlane_b32 s70, v246, 45
	s_waitcnt vmcnt(0)
	ds_write2_b32 v0, v88, v89 offset1:1
	v_add_u32_e32 v0, 0x3cf8, v16
	ds_write2_b32 v0, v90, v91 offset1:1
	s_waitcnt lgkmcnt(0)
	v_add_u32_e32 v0, 0x400, v18
	ds_read2_b32 v[30:31], v18 offset0:65 offset1:73
	ds_read2_b32 v[32:33], v18 offset1:8
	ds_read2_b32 v[34:35], v18 offset0:130 offset1:138
	ds_read2_b32 v[36:37], v18 offset0:195 offset1:203
	ds_read2_b32 v[38:39], v0 offset0:4 offset1:12
	ds_read2_b32 v[40:41], v0 offset0:69 offset1:77
	ds_read2_b32 v[42:43], v0 offset0:134 offset1:142
	ds_read2_b32 v[44:45], v0 offset0:199 offset1:207
	v_readlane_b32 s71, v246, 46
	s_waitcnt lgkmcnt(6)
	v_cvt_pk_bf16_f32 v26, v32, v30
	s_waitcnt lgkmcnt(2)
	v_cvt_pk_bf16_f32 v28, v38, v40
	v_cvt_pk_bf16_f32 v27, v34, v36
	s_waitcnt lgkmcnt(0)
	v_cvt_pk_bf16_f32 v29, v42, v44
	v_add_u32_e32 v30, 8, v48
	global_store_dwordx4 v[50:51], v[26:29], off
	v_readlane_b32 s73, v246, 48
	v_readlane_b32 s76, v246, 51
	v_cvt_pk_bf16_f32 v26, v33, v31
	v_ashrrev_i32_e32 v31, 31, v30
	v_cvt_pk_bf16_f32 v27, v35, v37
	v_cvt_pk_bf16_f32 v28, v39, v41
	v_cvt_pk_bf16_f32 v29, v43, v45
	v_lshlrev_b64 v[30:31], 12, v[30:31]
	ds_read2_b32 v[32:33], v18 offset0:81 offset1:89
	ds_read2_b32 v[34:35], v18 offset0:16 offset1:24
	ds_read2_b32 v[36:37], v18 offset0:146 offset1:154
	ds_read2_b32 v[38:39], v18 offset0:211 offset1:219
	ds_read2_b32 v[40:41], v0 offset0:20 offset1:28
	ds_read2_b32 v[42:43], v0 offset0:85 offset1:93
	ds_read2_b32 v[44:45], v0 offset0:150 offset1:158
	ds_read2_b32 v[50:51], v0 offset0:215 offset1:223
	v_lshl_add_u64 v[30:31], v[46:47], 0, v[30:31]
	global_store_dwordx4 v[30:31], v[26:29], off
	v_add_u32_e32 v30, 16, v48
	v_ashrrev_i32_e32 v31, 31, v30
	v_lshlrev_b64 v[30:31], 12, v[30:31]
	s_waitcnt lgkmcnt(6)
	v_cvt_pk_bf16_f32 v26, v34, v32
	s_waitcnt lgkmcnt(4)
	v_cvt_pk_bf16_f32 v27, v36, v38
	s_waitcnt lgkmcnt(2)
	v_cvt_pk_bf16_f32 v28, v40, v42
	s_waitcnt lgkmcnt(0)
	v_cvt_pk_bf16_f32 v29, v44, v50
	v_lshl_add_u64 v[30:31], v[46:47], 0, v[30:31]
	global_store_dwordx4 v[30:31], v[26:29], off
	v_add_u32_e32 v30, 24, v48
	v_ashrrev_i32_e32 v31, 31, v30
	v_cvt_pk_bf16_f32 v26, v35, v33
	v_cvt_pk_bf16_f32 v27, v37, v39
	v_cvt_pk_bf16_f32 v28, v41, v43
	v_cvt_pk_bf16_f32 v29, v45, v51
	v_lshlrev_b64 v[30:31], 12, v[30:31]
	ds_read2_b32 v[32:33], v18 offset0:32 offset1:40
	ds_read2_b32 v[34:35], v18 offset0:97 offset1:105
	ds_read2_b32 v[36:37], v18 offset0:162 offset1:170
	ds_read2_b32 v[38:39], v18 offset0:227 offset1:235
	ds_read2_b32 v[40:41], v0 offset0:36 offset1:44
	ds_read2_b32 v[42:43], v0 offset0:101 offset1:109
	ds_read2_b32 v[44:45], v0 offset0:166 offset1:174
	ds_read2_b32 v[50:51], v0 offset0:231 offset1:239
	v_lshl_add_u64 v[30:31], v[46:47], 0, v[30:31]
	global_store_dwordx4 v[30:31], v[26:29], off
	v_add_u32_e32 v30, 32, v48
	v_ashrrev_i32_e32 v31, 31, v30
	v_lshlrev_b64 v[30:31], 12, v[30:31]
	s_waitcnt lgkmcnt(6)
	v_cvt_pk_bf16_f32 v26, v32, v34
	s_waitcnt lgkmcnt(4)
	v_cvt_pk_bf16_f32 v27, v36, v38
	s_waitcnt lgkmcnt(2)
	v_cvt_pk_bf16_f32 v28, v40, v42
	s_waitcnt lgkmcnt(0)
	v_cvt_pk_bf16_f32 v29, v44, v50
	v_lshl_add_u64 v[30:31], v[46:47], 0, v[30:31]
	global_store_dwordx4 v[30:31], v[26:29], off
	v_add_u32_e32 v30, 40, v48
	v_ashrrev_i32_e32 v31, 31, v30
	v_cvt_pk_bf16_f32 v26, v33, v35
	v_cvt_pk_bf16_f32 v27, v37, v39
	v_cvt_pk_bf16_f32 v28, v41, v43
	v_cvt_pk_bf16_f32 v29, v45, v51
	v_lshlrev_b64 v[30:31], 12, v[30:31]
	ds_read2_b32 v[32:33], v18 offset0:48 offset1:56
	ds_read2_b32 v[34:35], v18 offset0:113 offset1:121
	ds_read2_b32 v[36:37], v18 offset0:178 offset1:186
	ds_read2_b32 v[38:39], v18 offset0:243 offset1:251
	ds_read2_b32 v[40:41], v0 offset0:52 offset1:60
	ds_read2_b32 v[42:43], v0 offset0:117 offset1:125
	ds_read2_b32 v[44:45], v0 offset0:182 offset1:190
	ds_read2_b32 v[50:51], v0 offset0:247 offset1:255
	v_lshl_add_u64 v[30:31], v[46:47], 0, v[30:31]
	global_store_dwordx4 v[30:31], v[26:29], off
	v_add_u32_e32 v30, 48, v48
	v_ashrrev_i32_e32 v31, 31, v30
	v_lshlrev_b64 v[30:31], 12, v[30:31]
	s_waitcnt lgkmcnt(6)
	v_cvt_pk_bf16_f32 v26, v32, v34
	s_waitcnt lgkmcnt(4)
	v_cvt_pk_bf16_f32 v27, v36, v38
	s_waitcnt lgkmcnt(2)
	v_cvt_pk_bf16_f32 v28, v40, v42
	s_waitcnt lgkmcnt(0)
	v_cvt_pk_bf16_f32 v29, v44, v50
	v_lshl_add_u64 v[30:31], v[46:47], 0, v[30:31]
	global_store_dwordx4 v[30:31], v[26:29], off
	v_add_u32_e32 v30, 56, v48
	v_ashrrev_i32_e32 v31, 31, v30
	v_lshlrev_b64 v[30:31], 12, v[30:31]
	v_cvt_pk_bf16_f32 v26, v33, v35
	v_cvt_pk_bf16_f32 v27, v37, v39
	v_cvt_pk_bf16_f32 v28, v41, v43
	v_cvt_pk_bf16_f32 v29, v45, v51
	v_lshl_add_u64 v[30:31], v[46:47], 0, v[30:31]
	global_store_dwordx4 v[30:31], v[26:29], off
	s_waitcnt lgkmcnt(0)
	v_readlane_b32 s77, v246, 52
	v_readlane_b32 s78, v246, 53
	v_readlane_b32 s79, v246, 54
	v_readlane_b32 s80, v246, 55
	v_readlane_b32 s81, v246, 56
	v_readlane_b32 s82, v246, 57
	v_readlane_b32 s83, v246, 58
	s_branch .LBB0_580
